# GEMM loops: accumulator K-halves back to back, m outer / n inner variant
# speedup vs baseline: 1.0243x; 1.0110x over previous
; #define PG8_STAGE(bufoff, gbase, voff) do { _Pragma("unroll") for (int _i = 0; _i < 2; ++_i) \
;         __builtin_amdgcn_global_load_lds((const unsigned*)((const char*)(gbase) + (voff)[_i]), (PG8_LAS unsigned*)(lds + (bufoff) + ldsw + _i * 8192), 16, 0, 0); } while (0)
; #define PG8_LDA(dst, b, h) do { _Pragma("unroll") for (int m = 0; m < 4; ++m) _Pragma("unroll") for (int k = 0; k < 2; ++k) dst[m][k] = *(const PG8_LAS bf16x8*)(lds + PG8_SA(b, h) + aoff + m * 2048 + k * 1024); } while (0)
; #define PG8_LDB(dst, b, h) do { _Pragma("unroll") for (int n = 0; n < 2; ++n) _Pragma("unroll") for (int k = 0; k < 2; ++k) dst[n][k] = *(const PG8_LAS bf16x8*)(lds + PG8_SB(b, h) + boff + n * 2048 + k * 1024); } while (0)
; #define PG8_MMA(ai, bj, At, Bt) do { __builtin_amdgcn_s_setprio(1); _Pragma("unroll") for (int m = 0; m < 4; ++m) _Pragma("unroll") for (int n = 0; n < 2; ++n) _Pragma("unroll") for (int k = 0; k < 2; ++k) \
;         acc[ai][bj][m][n] = __builtin_amdgcn_mfma_f32_16x16x32_bf16(Bt[n][k], At[m][k], acc[ai][bj][m][n], 0, 0, 0); __builtin_amdgcn_s_setprio(0); } while (0)
; #define PG8_WAIT_V(n) asm volatile("s_waitcnt vmcnt(" #n ")" ::: "memory")
; #define PG8_WAIT_L(n) asm volatile("s_waitcnt lgkmcnt(" #n ")" ::: "memory")
; #define PG8_BAR __builtin_amdgcn_s_barrier()
; #define PG8_SCHED __builtin_amdgcn_sched_barrier(0)
;     ...
;             const bool last = (t == nt - 2);
;             const char* a1 = PG8_KADV(cA, (size_t)(t + 1) * kstep);
;             const char* a2 = last ? nA : PG8_KADV(cA, (size_t)(t + 2) * kstep); const char* b2 = last ? nB : PG8_KADV(cB, (size_t)(t + 2) * kstep);
;             const char* a3 = PG8_KADV(a2, kstep); const char* b3 = PG8_KADV(b2, kstep);
;             if (last && has_next) S.a_ready(nxt);
;             if constexpr (SP2) {
;             PG8_LDB(B0, 0, 0); PG8_LDB(B1, 0, 1); PG8_SCHED; PG8_LDA(At, 0, 0); PG8_STAGE(PG8_SA(1, 1), a1 + hstep, voffA);
;             PG8_WAIT_V(8); PG8_WAIT_L(0); PG8_BAR; PG8_MMA(0, 0, At, B0); PG8_MMA(0, 1, At, B1); PG8_BAR; PG8_SCHED;
;             PG8_LDA(At, 0, 1); PG8_STAGE(PG8_SB(0, 0), b2, voffB); PG8_STAGE(PG8_SB(0, 1), b2 + hstep, voffB); PG8_STAGE(PG8_SA(0, 0), a2, voffA);
;             PG8_WAIT_V(8); PG8_WAIT_L(0); PG8_BAR; PG8_MMA(1, 0, At, B0); PG8_MMA(1, 1, At, B1); PG8_BAR; PG8_SCHED;
.LBB0_230:
	s_add_u32 s12, s80, 0xfff80080
	s_addc_u32 s13, s81, -1
	s_add_i32 s30, 0, 0x10000
	s_cmp_eq_u32 s28, 28
	s_cselect_b32 s85, s15, s13
	s_cselect_b32 s84, s20, s12
	s_cselect_b32 s83, s21, s25
	s_cselect_b32 s82, s22, s23
	s_add_i32 s12, 0, 0x14000
	v_add_u32_e32 v156, s30, v141
	v_add_u32_e32 v168, s12, v141
	ds_read_b128 v[144:147], v156
	ds_read_b128 v[148:151], v156 offset:1024
	ds_read_b128 v[152:155], v156 offset:2048
	ds_read_b128 v[156:159], v156 offset:3072
	ds_read_b128 v[160:163], v168
	ds_read_b128 v[164:167], v168 offset:1024
	ds_read_b128 v[182:185], v168 offset:2048
	ds_read_b128 v[186:189], v168 offset:3072
	s_add_i32 m0, s1, 0xc000
	ds_read_b128 v[190:193], v143
	ds_read_b128 v[194:197], v143 offset:1024
	ds_read_b128 v[198:201], v143 offset:2048
	ds_read_b128 v[202:205], v143 offset:3072
	ds_read_b128 v[206:209], v143 offset:4096
	ds_read_b128 v[210:213], v143 offset:5120
	ds_read_b128 v[214:217], v143 offset:6144
	ds_read_b128 v[218:221], v143 offset:7168
	global_load_lds_dwordx4 v136, s[80:81]
	s_add_i32 m0, s1, 0xe000
	s_nop 0
	global_load_lds_dwordx4 v138, s[80:81]
	s_waitcnt vmcnt(8)
	s_waitcnt lgkmcnt(0)
	s_barrier
	s_setprio 1
	s_waitcnt lgkmcnt(0)
	v_mfma_f32_16x16x32_bf16 v[124:127], v[144:147], v[190:193], v[124:127]
	v_mfma_f32_16x16x32_bf16 v[124:127], v[148:151], v[194:197], v[124:127]
	v_mfma_f32_16x16x32_bf16 v[120:123], v[152:155], v[190:193], v[120:123]
	v_mfma_f32_16x16x32_bf16 v[120:123], v[156:159], v[194:197], v[120:123]
	v_mfma_f32_16x16x32_bf16 v[116:119], v[160:163], v[190:193], v[116:119]
	v_mfma_f32_16x16x32_bf16 v[116:119], v[164:167], v[194:197], v[116:119]
	v_mfma_f32_16x16x32_bf16 v[112:115], v[182:185], v[190:193], v[112:115]
	v_mfma_f32_16x16x32_bf16 v[112:115], v[186:189], v[194:197], v[112:115]
	v_mfma_f32_16x16x32_bf16 v[108:111], v[144:147], v[198:201], v[108:111]
	v_mfma_f32_16x16x32_bf16 v[108:111], v[148:151], v[202:205], v[108:111]
	v_mfma_f32_16x16x32_bf16 v[104:107], v[152:155], v[198:201], v[104:107]
	v_mfma_f32_16x16x32_bf16 v[104:107], v[156:159], v[202:205], v[104:107]
	v_mfma_f32_16x16x32_bf16 v[100:103], v[160:163], v[198:201], v[100:103]
	v_mfma_f32_16x16x32_bf16 v[100:103], v[164:167], v[202:205], v[100:103]
	v_mfma_f32_16x16x32_bf16 v[96:99], v[182:185], v[198:201], v[96:99]
	v_mfma_f32_16x16x32_bf16 v[96:99], v[186:189], v[202:205], v[96:99]
	s_setprio 0
	s_setprio 1
	v_mfma_f32_16x16x32_bf16 v[92:95], v[144:147], v[206:209], v[92:95]
	v_mfma_f32_16x16x32_bf16 v[92:95], v[148:151], v[210:213], v[92:95]
	v_mfma_f32_16x16x32_bf16 v[88:91], v[152:155], v[206:209], v[88:91]
	v_mfma_f32_16x16x32_bf16 v[88:91], v[156:159], v[210:213], v[88:91]
	v_mfma_f32_16x16x32_bf16 v[84:87], v[160:163], v[206:209], v[84:87]
	v_mfma_f32_16x16x32_bf16 v[84:87], v[164:167], v[210:213], v[84:87]
	v_mfma_f32_16x16x32_bf16 v[80:83], v[182:185], v[206:209], v[80:83]
	v_mfma_f32_16x16x32_bf16 v[80:83], v[186:189], v[210:213], v[80:83]
	v_mfma_f32_16x16x32_bf16 v[76:79], v[144:147], v[214:217], v[76:79]
	v_mfma_f32_16x16x32_bf16 v[76:79], v[148:151], v[218:221], v[76:79]
	v_mfma_f32_16x16x32_bf16 v[72:75], v[152:155], v[214:217], v[72:75]
	v_mfma_f32_16x16x32_bf16 v[72:75], v[156:159], v[218:221], v[72:75]
	v_mfma_f32_16x16x32_bf16 v[68:71], v[160:163], v[214:217], v[68:71]
	v_mfma_f32_16x16x32_bf16 v[68:71], v[164:167], v[218:221], v[68:71]
	v_mfma_f32_16x16x32_bf16 v[64:67], v[182:185], v[214:217], v[64:67]
	v_mfma_f32_16x16x32_bf16 v[64:67], v[186:189], v[218:221], v[64:67]
	s_setprio 0
	s_barrier
	s_add_i32 s13, s30, s0
	s_mov_b32 m0, s13
	ds_read_b128 v[190:193], v143 offset:16384
	ds_read_b128 v[194:197], v143 offset:17408
	ds_read_b128 v[198:201], v143 offset:18432
	ds_read_b128 v[202:205], v143 offset:19456
	ds_read_b128 v[206:209], v143 offset:20480
	ds_read_b128 v[210:213], v143 offset:21504
	ds_read_b128 v[214:217], v143 offset:22528
	ds_read_b128 v[218:221], v143 offset:23552
	global_load_lds_dwordx4 v132, s[82:83]
	s_add_i32 m0, s13, 0x2000
	s_add_u32 s42, s82, 0x80000
	s_addc_u32 s43, s83, 0
	s_add_i32 s12, s12, s0
	global_load_lds_dwordx4 v128, s[82:83]
	s_mov_b32 m0, s12
	s_nop 0
	global_load_lds_dwordx4 v132, s[42:43]
	s_add_i32 m0, s12, 0x2000
	s_nop 0
	global_load_lds_dwordx4 v128, s[42:43]
	s_mov_b32 m0, s1
	s_nop 0
	global_load_lds_dwordx4 v134, s[84:85]
	s_mov_b32 m0, s2
	s_nop 0
	global_load_lds_dwordx4 v130, s[84:85]
	s_waitcnt vmcnt(8)
	s_waitcnt lgkmcnt(0)
	s_barrier
	s_setprio 1
	s_waitcnt lgkmcnt(0)
	v_mfma_f32_16x16x32_bf16 v[60:63], v[144:147], v[190:193], v[60:63]
	v_mfma_f32_16x16x32_bf16 v[60:63], v[148:151], v[194:197], v[60:63]
	v_mfma_f32_16x16x32_bf16 v[56:59], v[152:155], v[190:193], v[56:59]
	v_mfma_f32_16x16x32_bf16 v[56:59], v[156:159], v[194:197], v[56:59]
	v_mfma_f32_16x16x32_bf16 v[52:55], v[160:163], v[190:193], v[52:55]
	v_mfma_f32_16x16x32_bf16 v[52:55], v[164:167], v[194:197], v[52:55]
	v_mfma_f32_16x16x32_bf16 v[48:51], v[182:185], v[190:193], v[48:51]
	v_mfma_f32_16x16x32_bf16 v[48:51], v[186:189], v[194:197], v[48:51]
	v_mfma_f32_16x16x32_bf16 v[44:47], v[144:147], v[198:201], v[44:47]
	v_mfma_f32_16x16x32_bf16 v[44:47], v[148:151], v[202:205], v[44:47]
	v_mfma_f32_16x16x32_bf16 v[40:43], v[152:155], v[198:201], v[40:43]
	v_mfma_f32_16x16x32_bf16 v[40:43], v[156:159], v[202:205], v[40:43]
	v_mfma_f32_16x16x32_bf16 v[36:39], v[160:163], v[198:201], v[36:39]
	v_mfma_f32_16x16x32_bf16 v[36:39], v[164:167], v[202:205], v[36:39]
	v_mfma_f32_16x16x32_bf16 v[32:35], v[182:185], v[198:201], v[32:35]
	v_mfma_f32_16x16x32_bf16 v[32:35], v[186:189], v[202:205], v[32:35]
	s_setprio 0
	s_setprio 1
	v_mfma_f32_16x16x32_bf16 v[28:31], v[144:147], v[206:209], v[28:31]
	v_mfma_f32_16x16x32_bf16 v[28:31], v[148:151], v[210:213], v[28:31]
	v_mfma_f32_16x16x32_bf16 v[24:27], v[152:155], v[206:209], v[24:27]
	v_mfma_f32_16x16x32_bf16 v[24:27], v[156:159], v[210:213], v[24:27]
	v_mfma_f32_16x16x32_bf16 v[20:23], v[160:163], v[206:209], v[20:23]
	v_mfma_f32_16x16x32_bf16 v[20:23], v[164:167], v[210:213], v[20:23]
	v_mfma_f32_16x16x32_bf16 v[16:19], v[182:185], v[206:209], v[16:19]
	v_mfma_f32_16x16x32_bf16 v[16:19], v[186:189], v[210:213], v[16:19]
	v_mfma_f32_16x16x32_bf16 v[12:15], v[144:147], v[214:217], v[12:15]
	v_mfma_f32_16x16x32_bf16 v[12:15], v[148:151], v[218:221], v[12:15]
	v_mfma_f32_16x16x32_bf16 v[8:11], v[152:155], v[214:217], v[8:11]
	v_mfma_f32_16x16x32_bf16 v[8:11], v[156:159], v[218:221], v[8:11]
	v_mfma_f32_16x16x32_bf16 v[4:7], v[160:163], v[214:217], v[4:7]
	v_mfma_f32_16x16x32_bf16 v[4:7], v[164:167], v[218:221], v[4:7]
	v_mfma_f32_16x16x32_bf16 v[0:3], v[182:185], v[214:217], v[0:3]
	v_mfma_f32_16x16x32_bf16 v[0:3], v[186:189], v[218:221], v[0:3]
	s_setprio 0
	s_barrier
; #define PG8_STAGE(bufoff, gbase, voff) do { _Pragma("unroll") for (int _i = 0; _i < 2; ++_i) \
;         __builtin_amdgcn_global_load_lds((const unsigned*)((const char*)(gbase) + (voff)[_i]), (PG8_LAS unsigned*)(lds + (bufoff) + ldsw + _i * 8192), 16, 0, 0); } while (0)
; #define PG8_LDA(dst, b, h) do { _Pragma("unroll") for (int m = 0; m < 4; ++m) _Pragma("unroll") for (int k = 0; k < 2; ++k) dst[m][k] = *(const PG8_LAS bf16x8*)(lds + PG8_SA(b, h) + aoff + m * 2048 + k * 1024); } while (0)
; #define PG8_LDB(dst, b, h) do { _Pragma("unroll") for (int n = 0; n < 2; ++n) _Pragma("unroll") for (int k = 0; k < 2; ++k) dst[n][k] = *(const PG8_LAS bf16x8*)(lds + PG8_SB(b, h) + boff + n * 2048 + k * 1024); } while (0)
; #define PG8_MMA(ai, bj, At, Bt) do { __builtin_amdgcn_s_setprio(1); _Pragma("unroll") for (int m = 0; m < 4; ++m) _Pragma("unroll") for (int n = 0; n < 2; ++n) _Pragma("unroll") for (int k = 0; k < 2; ++k) \
;         acc[ai][bj][m][n] = __builtin_amdgcn_mfma_f32_16x16x32_bf16(Bt[n][k], At[m][k], acc[ai][bj][m][n], 0, 0, 0); __builtin_amdgcn_s_setprio(0); } while (0)
; #define PG8_WAIT_V(n) asm volatile("s_waitcnt vmcnt(" #n ")" ::: "memory")
; #define PG8_WAIT_L(n) asm volatile("s_waitcnt lgkmcnt(" #n ")" ::: "memory")
; #define PG8_BAR __builtin_amdgcn_s_barrier()
; #define PG8_SCHED __builtin_amdgcn_sched_barrier(0)
;     ...
;             PG8_LDB(B0, 1, 0); PG8_LDB(B1, 1, 1); PG8_SCHED; PG8_LDA(At, 1, 0); PG8_STAGE(PG8_SA(0, 1), a2 + hstep, voffA);
;             PG8_WAIT_V(8); PG8_WAIT_L(0); PG8_BAR; PG8_MMA(0, 0, At, B0); PG8_MMA(0, 1, At, B1); PG8_BAR; PG8_SCHED;
;             PG8_LDA(At, 1, 1); PG8_STAGE(PG8_SB(1, 0), b3, voffB); PG8_STAGE(PG8_SB(1, 1), b3 + hstep, voffB); PG8_STAGE(PG8_SA(1, 0), a3, voffA);
;             PG8_WAIT_V(8); PG8_WAIT_L(0); PG8_BAR; PG8_MMA(1, 0, At, B0); PG8_MMA(1, 1, At, B1); PG8_BAR; PG8_SCHED;
	s_add_i32 s12, 0, 0x18000
	s_add_i32 s13, 0, 0x1c000
	v_add_u32_e32 v156, s12, v141
	v_add_u32_e32 v168, s13, v141
	ds_read_b128 v[144:147], v156
	ds_read_b128 v[148:151], v156 offset:1024
	ds_read_b128 v[152:155], v156 offset:2048
	ds_read_b128 v[156:159], v156 offset:3072
	ds_read_b128 v[160:163], v168
	ds_read_b128 v[164:167], v168 offset:1024
	ds_read_b128 v[182:185], v168 offset:2048
	ds_read_b128 v[186:189], v168 offset:3072
	s_add_u32 s42, s84, 0x80000
	s_addc_u32 s43, s85, 0
	s_mov_b32 m0, s3
	ds_read_b128 v[190:193], v143 offset:32768
	ds_read_b128 v[194:197], v143 offset:33792
	ds_read_b128 v[198:201], v143 offset:34816
	ds_read_b128 v[202:205], v143 offset:35840
	ds_read_b128 v[206:209], v143 offset:36864
	ds_read_b128 v[210:213], v143 offset:37888
	ds_read_b128 v[214:217], v143 offset:38912
	ds_read_b128 v[218:221], v143 offset:39936
	global_load_lds_dwordx4 v134, s[42:43]
	s_mov_b32 m0, s8
	s_nop 0
	global_load_lds_dwordx4 v130, s[42:43]
	s_waitcnt vmcnt(8)
	s_waitcnt lgkmcnt(0)
	s_barrier
	s_setprio 1
	s_waitcnt lgkmcnt(0)
	v_mfma_f32_16x16x32_bf16 v[124:127], v[144:147], v[190:193], v[124:127]
	v_mfma_f32_16x16x32_bf16 v[124:127], v[148:151], v[194:197], v[124:127]
	v_mfma_f32_16x16x32_bf16 v[120:123], v[152:155], v[190:193], v[120:123]
	v_mfma_f32_16x16x32_bf16 v[120:123], v[156:159], v[194:197], v[120:123]
	v_mfma_f32_16x16x32_bf16 v[116:119], v[160:163], v[190:193], v[116:119]
	v_mfma_f32_16x16x32_bf16 v[116:119], v[164:167], v[194:197], v[116:119]
	v_mfma_f32_16x16x32_bf16 v[112:115], v[182:185], v[190:193], v[112:115]
	v_mfma_f32_16x16x32_bf16 v[112:115], v[186:189], v[194:197], v[112:115]
	v_mfma_f32_16x16x32_bf16 v[108:111], v[144:147], v[198:201], v[108:111]
	v_mfma_f32_16x16x32_bf16 v[108:111], v[148:151], v[202:205], v[108:111]
	v_mfma_f32_16x16x32_bf16 v[104:107], v[152:155], v[198:201], v[104:107]
	v_mfma_f32_16x16x32_bf16 v[104:107], v[156:159], v[202:205], v[104:107]
	v_mfma_f32_16x16x32_bf16 v[100:103], v[160:163], v[198:201], v[100:103]
	v_mfma_f32_16x16x32_bf16 v[100:103], v[164:167], v[202:205], v[100:103]
	v_mfma_f32_16x16x32_bf16 v[96:99], v[182:185], v[198:201], v[96:99]
	v_mfma_f32_16x16x32_bf16 v[96:99], v[186:189], v[202:205], v[96:99]
	s_setprio 0
	s_setprio 1
	v_mfma_f32_16x16x32_bf16 v[92:95], v[144:147], v[206:209], v[92:95]
	v_mfma_f32_16x16x32_bf16 v[92:95], v[148:151], v[210:213], v[92:95]
	v_mfma_f32_16x16x32_bf16 v[88:91], v[152:155], v[206:209], v[88:91]
	v_mfma_f32_16x16x32_bf16 v[88:91], v[156:159], v[210:213], v[88:91]
	v_mfma_f32_16x16x32_bf16 v[84:87], v[160:163], v[206:209], v[84:87]
	v_mfma_f32_16x16x32_bf16 v[84:87], v[164:167], v[210:213], v[84:87]
	v_mfma_f32_16x16x32_bf16 v[80:83], v[182:185], v[206:209], v[80:83]
	v_mfma_f32_16x16x32_bf16 v[80:83], v[186:189], v[210:213], v[80:83]
	v_mfma_f32_16x16x32_bf16 v[76:79], v[144:147], v[214:217], v[76:79]
	v_mfma_f32_16x16x32_bf16 v[76:79], v[148:151], v[218:221], v[76:79]
	v_mfma_f32_16x16x32_bf16 v[72:75], v[152:155], v[214:217], v[72:75]
	v_mfma_f32_16x16x32_bf16 v[72:75], v[156:159], v[218:221], v[72:75]
	v_mfma_f32_16x16x32_bf16 v[68:71], v[160:163], v[214:217], v[68:71]
	v_mfma_f32_16x16x32_bf16 v[68:71], v[164:167], v[218:221], v[68:71]
	v_mfma_f32_16x16x32_bf16 v[64:67], v[182:185], v[214:217], v[64:67]
	v_mfma_f32_16x16x32_bf16 v[64:67], v[186:189], v[218:221], v[64:67]
	s_setprio 0
	s_barrier
	s_add_i32 s12, s12, s0
	s_mov_b32 m0, s12
	ds_read_b128 v[190:193], v143 offset:49152
	ds_read_b128 v[194:197], v143 offset:50176
	ds_read_b128 v[198:201], v143 offset:51200
	ds_read_b128 v[202:205], v143 offset:52224
	ds_read_b128 v[206:209], v143 offset:53248
	ds_read_b128 v[210:213], v143 offset:54272
	ds_read_b128 v[214:217], v143 offset:55296
	ds_read_b128 v[218:221], v143 offset:56320
	s_add_u32 s100, s82, s16
	s_addc_u32 s101, s83, s17
	global_load_lds_dwordx4 v132, s[100:101]
	s_add_i32 m0, s12, 0x2000
	s_add_u32 s42, s82, 0x80080
	s_addc_u32 s43, s83, 0
	s_add_i32 s12, s13, s0
	global_load_lds_dwordx4 v128, s[100:101]
	s_mov_b32 m0, s12
	s_nop 0
	global_load_lds_dwordx4 v132, s[42:43]
	s_add_i32 m0, s12, 0x2000
	s_nop 0
	global_load_lds_dwordx4 v128, s[42:43]
	s_mov_b32 m0, s9
	s_nop 0
	s_add_u32 s100, s84, s16
	s_addc_u32 s101, s85, s17
	global_load_lds_dwordx4 v134, s[100:101]
	s_mov_b32 m0, s10
	s_nop 0
	global_load_lds_dwordx4 v130, s[100:101]
	s_waitcnt vmcnt(8)
	s_waitcnt lgkmcnt(0)
	s_barrier
	s_setprio 1
	s_waitcnt lgkmcnt(0)
	v_mfma_f32_16x16x32_bf16 v[60:63], v[144:147], v[190:193], v[60:63]
	v_mfma_f32_16x16x32_bf16 v[60:63], v[148:151], v[194:197], v[60:63]
	v_mfma_f32_16x16x32_bf16 v[56:59], v[152:155], v[190:193], v[56:59]
	v_mfma_f32_16x16x32_bf16 v[56:59], v[156:159], v[194:197], v[56:59]
	v_mfma_f32_16x16x32_bf16 v[52:55], v[160:163], v[190:193], v[52:55]
	v_mfma_f32_16x16x32_bf16 v[52:55], v[164:167], v[194:197], v[52:55]
	v_mfma_f32_16x16x32_bf16 v[48:51], v[182:185], v[190:193], v[48:51]
	v_mfma_f32_16x16x32_bf16 v[48:51], v[186:189], v[194:197], v[48:51]
	v_mfma_f32_16x16x32_bf16 v[44:47], v[144:147], v[198:201], v[44:47]
	v_mfma_f32_16x16x32_bf16 v[44:47], v[148:151], v[202:205], v[44:47]
	v_mfma_f32_16x16x32_bf16 v[40:43], v[152:155], v[198:201], v[40:43]
	v_mfma_f32_16x16x32_bf16 v[40:43], v[156:159], v[202:205], v[40:43]
	v_mfma_f32_16x16x32_bf16 v[36:39], v[160:163], v[198:201], v[36:39]
	v_mfma_f32_16x16x32_bf16 v[36:39], v[164:167], v[202:205], v[36:39]
	v_mfma_f32_16x16x32_bf16 v[32:35], v[182:185], v[198:201], v[32:35]
	v_mfma_f32_16x16x32_bf16 v[32:35], v[186:189], v[202:205], v[32:35]
	s_setprio 0
	s_setprio 1
	v_mfma_f32_16x16x32_bf16 v[28:31], v[144:147], v[206:209], v[28:31]
	v_mfma_f32_16x16x32_bf16 v[28:31], v[148:151], v[210:213], v[28:31]
	v_mfma_f32_16x16x32_bf16 v[24:27], v[152:155], v[206:209], v[24:27]
	v_mfma_f32_16x16x32_bf16 v[24:27], v[156:159], v[210:213], v[24:27]
	v_mfma_f32_16x16x32_bf16 v[20:23], v[160:163], v[206:209], v[20:23]
	v_mfma_f32_16x16x32_bf16 v[20:23], v[164:167], v[210:213], v[20:23]
	v_mfma_f32_16x16x32_bf16 v[16:19], v[182:185], v[206:209], v[16:19]
	v_mfma_f32_16x16x32_bf16 v[16:19], v[186:189], v[210:213], v[16:19]
	v_mfma_f32_16x16x32_bf16 v[12:15], v[144:147], v[214:217], v[12:15]
	v_mfma_f32_16x16x32_bf16 v[12:15], v[148:151], v[218:221], v[12:15]
	v_mfma_f32_16x16x32_bf16 v[8:11], v[152:155], v[214:217], v[8:11]
	v_mfma_f32_16x16x32_bf16 v[8:11], v[156:159], v[218:221], v[8:11]
	v_mfma_f32_16x16x32_bf16 v[4:7], v[160:163], v[214:217], v[4:7]
	v_mfma_f32_16x16x32_bf16 v[4:7], v[164:167], v[218:221], v[4:7]
	v_mfma_f32_16x16x32_bf16 v[0:3], v[182:185], v[214:217], v[0:3]
	v_mfma_f32_16x16x32_bf16 v[0:3], v[186:189], v[218:221], v[0:3]
	s_setprio 0
	s_barrier
	s_add_i32 s28, s28, 2
	s_add_u32 s80, s80, 0x100
	s_addc_u32 s81, s81, 0
	s_add_u32 s23, s23, 0x100
	s_addc_u32 s25, s25, 0
	s_cmp_gt_u32 s28, 29
	s_cbranch_scc0 .LBB0_230
	s_and_b64 vcc, exec, s[68:69]
	s_cbranch_vccz .LBB0_233
	s_barrier

; #define PG8_STAGE(bufoff, gbase, voff) do { _Pragma("unroll") for (int _i = 0; _i < 2; ++_i) \
;         __builtin_amdgcn_global_load_lds((const unsigned*)((const char*)(gbase) + (voff)[_i]), (PG8_LAS unsigned*)(lds + (bufoff) + ldsw + _i * 8192), 16, 0, 0); } while (0)
; #define PG8_LDA(dst, b, h) do { _Pragma("unroll") for (int m = 0; m < 4; ++m) _Pragma("unroll") for (int k = 0; k < 2; ++k) dst[m][k] = *(const PG8_LAS bf16x8*)(lds + PG8_SA(b, h) + aoff + m * 2048 + k * 1024); } while (0)
; #define PG8_LDB(dst, b, h) do { _Pragma("unroll") for (int n = 0; n < 2; ++n) _Pragma("unroll") for (int k = 0; k < 2; ++k) dst[n][k] = *(const PG8_LAS bf16x8*)(lds + PG8_SB(b, h) + boff + n * 2048 + k * 1024); } while (0)
; #define PG8_MMA(ai, bj, At, Bt) do { __builtin_amdgcn_s_setprio(1); _Pragma("unroll") for (int m = 0; m < 4; ++m) _Pragma("unroll") for (int n = 0; n < 2; ++n) _Pragma("unroll") for (int k = 0; k < 2; ++k) \
;         acc[ai][bj][m][n] = __builtin_amdgcn_mfma_f32_16x16x32_bf16(Bt[n][k], At[m][k], acc[ai][bj][m][n], 0, 0, 0); __builtin_amdgcn_s_setprio(0); } while (0)
; #define PG8_WAIT_V(n) asm volatile("s_waitcnt vmcnt(" #n ")" ::: "memory")
; #define PG8_WAIT_L(n) asm volatile("s_waitcnt lgkmcnt(" #n ")" ::: "memory")
; #define PG8_BAR __builtin_amdgcn_s_barrier()
; #define PG8_SCHED __builtin_amdgcn_sched_barrier(0)
;     ...
;             const bool last = (t == nt - 2);
;             const char* a1 = PG8_KADV(cA, (size_t)(t + 1) * kstep);
;             const char* a2 = last ? nA : PG8_KADV(cA, (size_t)(t + 2) * kstep); const char* b2 = last ? nB : PG8_KADV(cB, (size_t)(t + 2) * kstep);
;             const char* a3 = PG8_KADV(a2, kstep); const char* b3 = PG8_KADV(b2, kstep);
;             if (last && has_next) S.a_ready(nxt);
;             if constexpr (SP2) {
;             PG8_LDB(B0, 0, 0); PG8_LDB(B1, 0, 1); PG8_SCHED; PG8_LDA(At, 0, 0); PG8_STAGE(PG8_SA(1, 1), a1 + hstep, voffA);
;             PG8_WAIT_V(8); PG8_WAIT_L(0); PG8_BAR; PG8_MMA(0, 0, At, B0); PG8_MMA(0, 1, At, B1); PG8_BAR; PG8_SCHED;
;             PG8_LDA(At, 0, 1); PG8_STAGE(PG8_SB(0, 0), b2, voffB); PG8_STAGE(PG8_SB(0, 1), b2 + hstep, voffB); PG8_STAGE(PG8_SA(0, 0), a2, voffA);
;             PG8_WAIT_V(8); PG8_WAIT_L(0); PG8_BAR; PG8_MMA(1, 0, At, B0); PG8_MMA(1, 1, At, B1); PG8_BAR; PG8_SCHED;
.LBB0_313:
	s_add_u32 s78, s76, 0xffffff00
	s_addc_u32 s79, s77, -1
	s_add_i32 s12, 0, 0x10000
	s_cmpk_eq_i32 s3, 0x54
	s_cselect_b32 s83, s7, s79
	s_cselect_b32 s82, s6, s78
	s_cselect_b32 s81, s75, s30
	s_cselect_b32 s80, s74, s2
	s_add_i32 s13, 0, 0x14000
	v_add_u32_e32 v152, s12, v166
	v_add_u32_e32 v164, s13, v166
	ds_read_b128 v[128:131], v152
	ds_read_b128 v[132:135], v152 offset:1024
	ds_read_b128 v[148:151], v152 offset:2048
	ds_read_b128 v[152:155], v152 offset:3072
	ds_read_b128 v[156:159], v164
	ds_read_b128 v[160:163], v164 offset:1024
	ds_read_b128 v[170:173], v164 offset:2048
	ds_read_b128 v[178:181], v164 offset:3072
	s_add_i32 m0, s9, 0xc000
	ds_read_b128 v[184:187], v183
	ds_read_b128 v[188:191], v183 offset:1024
	ds_read_b128 v[192:195], v183 offset:2048
	ds_read_b128 v[196:199], v183 offset:3072
	ds_read_b128 v[200:203], v183 offset:4096
	ds_read_b128 v[204:207], v183 offset:5120
	ds_read_b128 v[208:211], v183 offset:6144
	ds_read_b128 v[212:215], v183 offset:7168
	global_load_lds_dwordx4 v144, s[76:77]
	s_add_i32 m0, s9, 0xe000
	s_nop 0
	global_load_lds_dwordx4 v146, s[76:77]
	s_waitcnt vmcnt(8)
	s_waitcnt lgkmcnt(0)
	s_barrier
	s_setprio 1
	s_waitcnt lgkmcnt(0)
	v_mfma_f32_16x16x32_bf16 v[124:127], v[128:131], v[184:187], v[124:127]
	v_mfma_f32_16x16x32_bf16 v[124:127], v[132:135], v[188:191], v[124:127]
	v_mfma_f32_16x16x32_bf16 v[120:123], v[148:151], v[184:187], v[120:123]
	v_mfma_f32_16x16x32_bf16 v[120:123], v[152:155], v[188:191], v[120:123]
	v_mfma_f32_16x16x32_bf16 v[116:119], v[156:159], v[184:187], v[116:119]
	v_mfma_f32_16x16x32_bf16 v[116:119], v[160:163], v[188:191], v[116:119]
	v_mfma_f32_16x16x32_bf16 v[108:111], v[170:173], v[184:187], v[108:111]
	v_mfma_f32_16x16x32_bf16 v[108:111], v[178:181], v[188:191], v[108:111]
	v_mfma_f32_16x16x32_bf16 v[112:115], v[128:131], v[192:195], v[112:115]
	v_mfma_f32_16x16x32_bf16 v[112:115], v[132:135], v[196:199], v[112:115]
	v_mfma_f32_16x16x32_bf16 v[104:107], v[148:151], v[192:195], v[104:107]
	v_mfma_f32_16x16x32_bf16 v[104:107], v[152:155], v[196:199], v[104:107]
	v_mfma_f32_16x16x32_bf16 v[100:103], v[156:159], v[192:195], v[100:103]
	v_mfma_f32_16x16x32_bf16 v[100:103], v[160:163], v[196:199], v[100:103]
	v_mfma_f32_16x16x32_bf16 v[96:99], v[170:173], v[192:195], v[96:99]
	v_mfma_f32_16x16x32_bf16 v[96:99], v[178:181], v[196:199], v[96:99]
	s_setprio 0
	s_setprio 1
	v_mfma_f32_16x16x32_bf16 v[92:95], v[128:131], v[200:203], v[92:95]
	v_mfma_f32_16x16x32_bf16 v[92:95], v[132:135], v[204:207], v[92:95]
	v_mfma_f32_16x16x32_bf16 v[88:91], v[148:151], v[200:203], v[88:91]
	v_mfma_f32_16x16x32_bf16 v[88:91], v[152:155], v[204:207], v[88:91]
	v_mfma_f32_16x16x32_bf16 v[84:87], v[156:159], v[200:203], v[84:87]
	v_mfma_f32_16x16x32_bf16 v[84:87], v[160:163], v[204:207], v[84:87]
	v_mfma_f32_16x16x32_bf16 v[76:79], v[170:173], v[200:203], v[76:79]
	v_mfma_f32_16x16x32_bf16 v[76:79], v[178:181], v[204:207], v[76:79]
	v_mfma_f32_16x16x32_bf16 v[80:83], v[128:131], v[208:211], v[80:83]
	v_mfma_f32_16x16x32_bf16 v[80:83], v[132:135], v[212:215], v[80:83]
	v_mfma_f32_16x16x32_bf16 v[72:75], v[148:151], v[208:211], v[72:75]
	v_mfma_f32_16x16x32_bf16 v[72:75], v[152:155], v[212:215], v[72:75]
	v_mfma_f32_16x16x32_bf16 v[68:71], v[156:159], v[208:211], v[68:71]
	v_mfma_f32_16x16x32_bf16 v[68:71], v[160:163], v[212:215], v[68:71]
	v_mfma_f32_16x16x32_bf16 v[64:67], v[170:173], v[208:211], v[64:67]
	v_mfma_f32_16x16x32_bf16 v[64:67], v[178:181], v[212:215], v[64:67]
	s_setprio 0
	s_barrier
	s_add_i32 s12, s12, s8
	s_mov_b32 m0, s12
	ds_read_b128 v[184:187], v183 offset:16384
	ds_read_b128 v[188:191], v183 offset:17408
	ds_read_b128 v[192:195], v183 offset:18432
	ds_read_b128 v[196:199], v183 offset:19456
	ds_read_b128 v[200:203], v183 offset:20480
	ds_read_b128 v[204:207], v183 offset:21504
	ds_read_b128 v[208:211], v183 offset:22528
	ds_read_b128 v[212:215], v183 offset:23552
	global_load_lds_dwordx4 v138, s[80:81]
	s_add_i32 m0, s12, 0x2000
	s_add_u32 s42, s80, 0x160000
	s_addc_u32 s43, s81, 0
	s_add_i32 s12, s13, s8
	global_load_lds_dwordx4 v142, s[80:81]
	s_mov_b32 m0, s12
	s_nop 0
	global_load_lds_dwordx4 v138, s[42:43]
	s_add_i32 m0, s12, 0x2000
	s_nop 0
	global_load_lds_dwordx4 v142, s[42:43]
	s_mov_b32 m0, s9
	s_nop 0
	global_load_lds_dwordx4 v136, s[82:83]
	s_mov_b32 m0, s10
	s_nop 0
	global_load_lds_dwordx4 v140, s[82:83]
	s_waitcnt vmcnt(8)
	s_waitcnt lgkmcnt(0)
	s_barrier
	s_setprio 1
	s_waitcnt lgkmcnt(0)
	v_mfma_f32_16x16x32_bf16 v[60:63], v[128:131], v[184:187], v[60:63]
	v_mfma_f32_16x16x32_bf16 v[60:63], v[132:135], v[188:191], v[60:63]
	v_mfma_f32_16x16x32_bf16 v[56:59], v[148:151], v[184:187], v[56:59]
	v_mfma_f32_16x16x32_bf16 v[56:59], v[152:155], v[188:191], v[56:59]
	v_mfma_f32_16x16x32_bf16 v[52:55], v[156:159], v[184:187], v[52:55]
	v_mfma_f32_16x16x32_bf16 v[52:55], v[160:163], v[188:191], v[52:55]
	v_mfma_f32_16x16x32_bf16 v[44:47], v[170:173], v[184:187], v[44:47]
	v_mfma_f32_16x16x32_bf16 v[44:47], v[178:181], v[188:191], v[44:47]
	v_mfma_f32_16x16x32_bf16 v[48:51], v[128:131], v[192:195], v[48:51]
	v_mfma_f32_16x16x32_bf16 v[48:51], v[132:135], v[196:199], v[48:51]
	v_mfma_f32_16x16x32_bf16 v[40:43], v[148:151], v[192:195], v[40:43]
	v_mfma_f32_16x16x32_bf16 v[40:43], v[152:155], v[196:199], v[40:43]
	v_mfma_f32_16x16x32_bf16 v[36:39], v[156:159], v[192:195], v[36:39]
	v_mfma_f32_16x16x32_bf16 v[36:39], v[160:163], v[196:199], v[36:39]
	v_mfma_f32_16x16x32_bf16 v[32:35], v[170:173], v[192:195], v[32:35]
	v_mfma_f32_16x16x32_bf16 v[32:35], v[178:181], v[196:199], v[32:35]
	s_setprio 0
	s_setprio 1
	v_mfma_f32_16x16x32_bf16 v[28:31], v[128:131], v[200:203], v[28:31]
	v_mfma_f32_16x16x32_bf16 v[28:31], v[132:135], v[204:207], v[28:31]
	v_mfma_f32_16x16x32_bf16 v[24:27], v[148:151], v[200:203], v[24:27]
	v_mfma_f32_16x16x32_bf16 v[24:27], v[152:155], v[204:207], v[24:27]
	v_mfma_f32_16x16x32_bf16 v[20:23], v[156:159], v[200:203], v[20:23]
	v_mfma_f32_16x16x32_bf16 v[20:23], v[160:163], v[204:207], v[20:23]
	v_mfma_f32_16x16x32_bf16 v[12:15], v[170:173], v[200:203], v[12:15]
	v_mfma_f32_16x16x32_bf16 v[12:15], v[178:181], v[204:207], v[12:15]
	v_mfma_f32_16x16x32_bf16 v[16:19], v[128:131], v[208:211], v[16:19]
	v_mfma_f32_16x16x32_bf16 v[16:19], v[132:135], v[212:215], v[16:19]
	v_mfma_f32_16x16x32_bf16 v[8:11], v[148:151], v[208:211], v[8:11]
	v_mfma_f32_16x16x32_bf16 v[8:11], v[152:155], v[212:215], v[8:11]
	v_mfma_f32_16x16x32_bf16 v[4:7], v[156:159], v[208:211], v[4:7]
	v_mfma_f32_16x16x32_bf16 v[4:7], v[160:163], v[212:215], v[4:7]
	v_mfma_f32_16x16x32_bf16 v[0:3], v[170:173], v[208:211], v[0:3]
	v_mfma_f32_16x16x32_bf16 v[0:3], v[178:181], v[212:215], v[0:3]
	s_setprio 0
	s_barrier
; #define PG8_STAGE(bufoff, gbase, voff) do { _Pragma("unroll") for (int _i = 0; _i < 2; ++_i) \
;         __builtin_amdgcn_global_load_lds((const unsigned*)((const char*)(gbase) + (voff)[_i]), (PG8_LAS unsigned*)(lds + (bufoff) + ldsw + _i * 8192), 16, 0, 0); } while (0)
; #define PG8_LDA(dst, b, h) do { _Pragma("unroll") for (int m = 0; m < 4; ++m) _Pragma("unroll") for (int k = 0; k < 2; ++k) dst[m][k] = *(const PG8_LAS bf16x8*)(lds + PG8_SA(b, h) + aoff + m * 2048 + k * 1024); } while (0)
; #define PG8_LDB(dst, b, h) do { _Pragma("unroll") for (int n = 0; n < 2; ++n) _Pragma("unroll") for (int k = 0; k < 2; ++k) dst[n][k] = *(const PG8_LAS bf16x8*)(lds + PG8_SB(b, h) + boff + n * 2048 + k * 1024); } while (0)
; #define PG8_MMA(ai, bj, At, Bt) do { __builtin_amdgcn_s_setprio(1); _Pragma("unroll") for (int m = 0; m < 4; ++m) _Pragma("unroll") for (int n = 0; n < 2; ++n) _Pragma("unroll") for (int k = 0; k < 2; ++k) \
;         acc[ai][bj][m][n] = __builtin_amdgcn_mfma_f32_16x16x32_bf16(Bt[n][k], At[m][k], acc[ai][bj][m][n], 0, 0, 0); __builtin_amdgcn_s_setprio(0); } while (0)
; #define PG8_WAIT_V(n) asm volatile("s_waitcnt vmcnt(" #n ")" ::: "memory")
; #define PG8_WAIT_L(n) asm volatile("s_waitcnt lgkmcnt(" #n ")" ::: "memory")
; #define PG8_BAR __builtin_amdgcn_s_barrier()
; #define PG8_SCHED __builtin_amdgcn_sched_barrier(0)
;     ...
;             PG8_LDB(B0, 1, 0); PG8_LDB(B1, 1, 1); PG8_SCHED; PG8_LDA(At, 1, 0); PG8_STAGE(PG8_SA(0, 1), a2 + hstep, voffA);
;             PG8_WAIT_V(8); PG8_WAIT_L(0); PG8_BAR; PG8_MMA(0, 0, At, B0); PG8_MMA(0, 1, At, B1); PG8_BAR; PG8_SCHED;
;             PG8_LDA(At, 1, 1); PG8_STAGE(PG8_SB(1, 0), b3, voffB); PG8_STAGE(PG8_SB(1, 1), b3 + hstep, voffB); PG8_STAGE(PG8_SA(1, 0), a3, voffA);
;             PG8_WAIT_V(8); PG8_WAIT_L(0); PG8_BAR; PG8_MMA(1, 0, At, B0); PG8_MMA(1, 1, At, B1); PG8_BAR; PG8_SCHED;
	s_add_i32 s12, 0, 0x18000
	s_add_i32 s13, 0, 0x1c000
	v_add_u32_e32 v152, s12, v166
	v_add_u32_e32 v168, s13, v166
	ds_read_b128 v[128:131], v152
	ds_read_b128 v[132:135], v152 offset:1024
	ds_read_b128 v[148:151], v152 offset:2048
	ds_read_b128 v[152:155], v152 offset:3072
	ds_read_b128 v[156:159], v168
	ds_read_b128 v[160:163], v168 offset:1024
	ds_read_b128 v[170:173], v168 offset:2048
	ds_read_b128 v[178:181], v168 offset:3072
	s_add_u32 s42, s82, 0x160000
	s_addc_u32 s43, s83, 0
	s_mov_b32 m0, s18
	ds_read_b128 v[184:187], v183 offset:32768
	ds_read_b128 v[188:191], v183 offset:33792
	ds_read_b128 v[192:195], v183 offset:34816
	ds_read_b128 v[196:199], v183 offset:35840
	ds_read_b128 v[200:203], v183 offset:36864
	ds_read_b128 v[204:207], v183 offset:37888
	ds_read_b128 v[208:211], v183 offset:38912
	ds_read_b128 v[212:215], v183 offset:39936
	global_load_lds_dwordx4 v136, s[42:43]
	s_mov_b32 m0, s19
	s_nop 0
	global_load_lds_dwordx4 v140, s[42:43]
	s_waitcnt vmcnt(8)
	s_waitcnt lgkmcnt(0)
	s_barrier
	s_setprio 1
	s_waitcnt lgkmcnt(0)
	v_mfma_f32_16x16x32_bf16 v[124:127], v[128:131], v[184:187], v[124:127]
	v_mfma_f32_16x16x32_bf16 v[124:127], v[132:135], v[188:191], v[124:127]
	v_mfma_f32_16x16x32_bf16 v[120:123], v[148:151], v[184:187], v[120:123]
	v_mfma_f32_16x16x32_bf16 v[120:123], v[152:155], v[188:191], v[120:123]
	v_mfma_f32_16x16x32_bf16 v[116:119], v[156:159], v[184:187], v[116:119]
	v_mfma_f32_16x16x32_bf16 v[116:119], v[160:163], v[188:191], v[116:119]
	v_mfma_f32_16x16x32_bf16 v[108:111], v[170:173], v[184:187], v[108:111]
	v_mfma_f32_16x16x32_bf16 v[108:111], v[178:181], v[188:191], v[108:111]
	v_mfma_f32_16x16x32_bf16 v[112:115], v[128:131], v[192:195], v[112:115]
	v_mfma_f32_16x16x32_bf16 v[112:115], v[132:135], v[196:199], v[112:115]
	v_mfma_f32_16x16x32_bf16 v[104:107], v[148:151], v[192:195], v[104:107]
	v_mfma_f32_16x16x32_bf16 v[104:107], v[152:155], v[196:199], v[104:107]
	v_mfma_f32_16x16x32_bf16 v[100:103], v[156:159], v[192:195], v[100:103]
	v_mfma_f32_16x16x32_bf16 v[100:103], v[160:163], v[196:199], v[100:103]
	v_mfma_f32_16x16x32_bf16 v[96:99], v[170:173], v[192:195], v[96:99]
	v_mfma_f32_16x16x32_bf16 v[96:99], v[178:181], v[196:199], v[96:99]
	s_setprio 0
	s_setprio 1
	v_mfma_f32_16x16x32_bf16 v[92:95], v[128:131], v[200:203], v[92:95]
	v_mfma_f32_16x16x32_bf16 v[92:95], v[132:135], v[204:207], v[92:95]
	v_mfma_f32_16x16x32_bf16 v[88:91], v[148:151], v[200:203], v[88:91]
	v_mfma_f32_16x16x32_bf16 v[88:91], v[152:155], v[204:207], v[88:91]
	v_mfma_f32_16x16x32_bf16 v[84:87], v[156:159], v[200:203], v[84:87]
	v_mfma_f32_16x16x32_bf16 v[84:87], v[160:163], v[204:207], v[84:87]
	v_mfma_f32_16x16x32_bf16 v[76:79], v[170:173], v[200:203], v[76:79]
	v_mfma_f32_16x16x32_bf16 v[76:79], v[178:181], v[204:207], v[76:79]
	v_mfma_f32_16x16x32_bf16 v[80:83], v[128:131], v[208:211], v[80:83]
	v_mfma_f32_16x16x32_bf16 v[80:83], v[132:135], v[212:215], v[80:83]
	v_mfma_f32_16x16x32_bf16 v[72:75], v[148:151], v[208:211], v[72:75]
	v_mfma_f32_16x16x32_bf16 v[72:75], v[152:155], v[212:215], v[72:75]
	v_mfma_f32_16x16x32_bf16 v[68:71], v[156:159], v[208:211], v[68:71]
	v_mfma_f32_16x16x32_bf16 v[68:71], v[160:163], v[212:215], v[68:71]
	v_mfma_f32_16x16x32_bf16 v[64:67], v[170:173], v[208:211], v[64:67]
	v_mfma_f32_16x16x32_bf16 v[64:67], v[178:181], v[212:215], v[64:67]
	s_setprio 0
	s_barrier
	s_add_i32 s12, s12, s8
	s_mov_b32 m0, s12
	ds_read_b128 v[184:187], v183 offset:49152
	ds_read_b128 v[188:191], v183 offset:50176
	ds_read_b128 v[192:195], v183 offset:51200
	ds_read_b128 v[196:199], v183 offset:52224
	ds_read_b128 v[200:203], v183 offset:53248
	ds_read_b128 v[204:207], v183 offset:54272
	ds_read_b128 v[208:211], v183 offset:55296
	ds_read_b128 v[212:215], v183 offset:56320
	s_add_u32 s100, s80, s38
	s_addc_u32 s101, s81, s39
	global_load_lds_dwordx4 v138, s[100:101]
	s_add_i32 m0, s12, 0x2000
	s_add_u32 s42, s80, 0x15ff80
	s_addc_u32 s43, s81, 0
	s_add_i32 s12, s13, s8
	global_load_lds_dwordx4 v142, s[100:101]
	s_mov_b32 m0, s12
	s_nop 0
	global_load_lds_dwordx4 v138, s[42:43]
	s_add_i32 m0, s12, 0x2000
	s_nop 0
	global_load_lds_dwordx4 v142, s[42:43]
	s_mov_b32 m0, s20
	s_nop 0
	s_add_u32 s100, s82, s38
	s_addc_u32 s101, s83, s39
	global_load_lds_dwordx4 v136, s[100:101]
	s_mov_b32 m0, s21
	s_nop 0
	global_load_lds_dwordx4 v140, s[100:101]
	s_waitcnt vmcnt(8)
	s_waitcnt lgkmcnt(0)
	s_barrier
	s_setprio 1
	s_waitcnt lgkmcnt(0)
	v_mfma_f32_16x16x32_bf16 v[60:63], v[128:131], v[184:187], v[60:63]
	v_mfma_f32_16x16x32_bf16 v[60:63], v[132:135], v[188:191], v[60:63]
	v_mfma_f32_16x16x32_bf16 v[56:59], v[148:151], v[184:187], v[56:59]
	v_mfma_f32_16x16x32_bf16 v[56:59], v[152:155], v[188:191], v[56:59]
	v_mfma_f32_16x16x32_bf16 v[52:55], v[156:159], v[184:187], v[52:55]
	v_mfma_f32_16x16x32_bf16 v[52:55], v[160:163], v[188:191], v[52:55]
	v_mfma_f32_16x16x32_bf16 v[44:47], v[170:173], v[184:187], v[44:47]
	v_mfma_f32_16x16x32_bf16 v[44:47], v[178:181], v[188:191], v[44:47]
	v_mfma_f32_16x16x32_bf16 v[48:51], v[128:131], v[192:195], v[48:51]
	v_mfma_f32_16x16x32_bf16 v[48:51], v[132:135], v[196:199], v[48:51]
	v_mfma_f32_16x16x32_bf16 v[40:43], v[148:151], v[192:195], v[40:43]
	v_mfma_f32_16x16x32_bf16 v[40:43], v[152:155], v[196:199], v[40:43]
	v_mfma_f32_16x16x32_bf16 v[36:39], v[156:159], v[192:195], v[36:39]
	v_mfma_f32_16x16x32_bf16 v[36:39], v[160:163], v[196:199], v[36:39]
	v_mfma_f32_16x16x32_bf16 v[32:35], v[170:173], v[192:195], v[32:35]
	v_mfma_f32_16x16x32_bf16 v[32:35], v[178:181], v[196:199], v[32:35]
	s_setprio 0
	s_setprio 1
	v_mfma_f32_16x16x32_bf16 v[28:31], v[128:131], v[200:203], v[28:31]
	v_mfma_f32_16x16x32_bf16 v[28:31], v[132:135], v[204:207], v[28:31]
	v_mfma_f32_16x16x32_bf16 v[24:27], v[148:151], v[200:203], v[24:27]
	v_mfma_f32_16x16x32_bf16 v[24:27], v[152:155], v[204:207], v[24:27]
	v_mfma_f32_16x16x32_bf16 v[20:23], v[156:159], v[200:203], v[20:23]
	v_mfma_f32_16x16x32_bf16 v[20:23], v[160:163], v[204:207], v[20:23]
	v_mfma_f32_16x16x32_bf16 v[12:15], v[170:173], v[200:203], v[12:15]
	v_mfma_f32_16x16x32_bf16 v[12:15], v[178:181], v[204:207], v[12:15]
	v_mfma_f32_16x16x32_bf16 v[16:19], v[128:131], v[208:211], v[16:19]
	v_mfma_f32_16x16x32_bf16 v[16:19], v[132:135], v[212:215], v[16:19]
	v_mfma_f32_16x16x32_bf16 v[8:11], v[148:151], v[208:211], v[8:11]
	v_mfma_f32_16x16x32_bf16 v[8:11], v[152:155], v[212:215], v[8:11]
	v_mfma_f32_16x16x32_bf16 v[4:7], v[156:159], v[208:211], v[4:7]
	v_mfma_f32_16x16x32_bf16 v[4:7], v[160:163], v[212:215], v[4:7]
	v_mfma_f32_16x16x32_bf16 v[0:3], v[170:173], v[208:211], v[0:3]
	v_mfma_f32_16x16x32_bf16 v[0:3], v[178:181], v[212:215], v[0:3]
	s_setprio 0
	s_barrier
	s_add_i32 s3, s3, 2
	s_add_u32 s2, s2, 0xffffff00
	s_addc_u32 s30, s30, -1
	s_cmpk_gt_u32 s3, 0x55
	s_mov_b64 s[76:77], s[78:79]
	s_cbranch_scc0 .LBB0_313
	s_and_b64 vcc, exec, s[72:73]
	s_cbranch_vccz .LBB0_316
	s_barrier

; #define PG8_STAGE(bufoff, gbase, voff) do { _Pragma("unroll") for (int _i = 0; _i < 2; ++_i) \
;         __builtin_amdgcn_global_load_lds((const unsigned*)((const char*)(gbase) + (voff)[_i]), (PG8_LAS unsigned*)(lds + (bufoff) + ldsw + _i * 8192), 16, 0, 0); } while (0)
; #define PG8_LDA(dst, b, h) do { _Pragma("unroll") for (int m = 0; m < 4; ++m) _Pragma("unroll") for (int k = 0; k < 2; ++k) dst[m][k] = *(const PG8_LAS bf16x8*)(lds + PG8_SA(b, h) + aoff + m * 2048 + k * 1024); } while (0)
; #define PG8_LDB(dst, b, h) do { _Pragma("unroll") for (int n = 0; n < 2; ++n) _Pragma("unroll") for (int k = 0; k < 2; ++k) dst[n][k] = *(const PG8_LAS bf16x8*)(lds + PG8_SB(b, h) + boff + n * 2048 + k * 1024); } while (0)
; #define PG8_MMA(ai, bj, At, Bt) do { __builtin_amdgcn_s_setprio(1); _Pragma("unroll") for (int m = 0; m < 4; ++m) _Pragma("unroll") for (int n = 0; n < 2; ++n) _Pragma("unroll") for (int k = 0; k < 2; ++k) \
;         acc[ai][bj][m][n] = __builtin_amdgcn_mfma_f32_16x16x32_bf16(Bt[n][k], At[m][k], acc[ai][bj][m][n], 0, 0, 0); __builtin_amdgcn_s_setprio(0); } while (0)
; #define PG8_WAIT_V(n) asm volatile("s_waitcnt vmcnt(" #n ")" ::: "memory")
; #define PG8_WAIT_L(n) asm volatile("s_waitcnt lgkmcnt(" #n ")" ::: "memory")
; #define PG8_BAR __builtin_amdgcn_s_barrier()
; #define PG8_SCHED __builtin_amdgcn_sched_barrier(0)
;     ...
;             const bool last = (t == nt - 2);
;             const char* a1 = PG8_KADV(cA, (size_t)(t + 1) * kstep);
;             const char* a2 = last ? nA : PG8_KADV(cA, (size_t)(t + 2) * kstep); const char* b2 = last ? nB : PG8_KADV(cB, (size_t)(t + 2) * kstep);
;             const char* a3 = PG8_KADV(a2, kstep); const char* b3 = PG8_KADV(b2, kstep);
;             if (last && has_next) S.a_ready(nxt);
;             if constexpr (SP2) {
;             PG8_LDB(B0, 0, 0); PG8_LDB(B1, 0, 1); PG8_SCHED; PG8_LDA(At, 0, 0); PG8_STAGE(PG8_SA(1, 1), a1 + hstep, voffA);
;             PG8_WAIT_V(8); PG8_WAIT_L(0); PG8_BAR; PG8_MMA(0, 0, At, B0); PG8_MMA(0, 1, At, B1); PG8_BAR; PG8_SCHED;
;             PG8_LDA(At, 0, 1); PG8_STAGE(PG8_SB(0, 0), b2, voffB); PG8_STAGE(PG8_SB(0, 1), b2 + hstep, voffB); PG8_STAGE(PG8_SA(0, 0), a2, voffA);
;             PG8_WAIT_V(8); PG8_WAIT_L(0); PG8_BAR; PG8_MMA(1, 0, At, B0); PG8_MMA(1, 1, At, B1); PG8_BAR; PG8_SCHED;
.LBB0_343:
	s_add_u32 s78, s76, 0xffffff00
	s_addc_u32 s79, s77, -1
	s_add_i32 s12, 0, 0x10000
	s_cmpk_eq_i32 s3, 0x54
	s_cselect_b32 s83, s7, s79
	s_cselect_b32 s82, s6, s78
	s_cselect_b32 s81, s75, s30
	s_cselect_b32 s80, s74, s2
	s_add_i32 s13, 0, 0x14000
	v_add_u32_e32 v140, s12, v233
	v_add_u32_e32 v156, s13, v233
	ds_read_b128 v[128:131], v140
	ds_read_b128 v[132:135], v140 offset:1024
	ds_read_b128 v[136:139], v140 offset:2048
	ds_read_b128 v[140:143], v140 offset:3072
	ds_read_b128 v[144:147], v156
	ds_read_b128 v[148:151], v156 offset:1024
	ds_read_b128 v[152:155], v156 offset:2048
	ds_read_b128 v[156:159], v156 offset:3072
	s_add_i32 m0, s9, 0xc000
	ds_read_b128 v[160:163], v236
	ds_read_b128 v[164:167], v236 offset:1024
	ds_read_b128 v[194:197], v236 offset:2048
	ds_read_b128 v[198:201], v236 offset:3072
	ds_read_b128 v[202:205], v236 offset:4096
	ds_read_b128 v[206:209], v236 offset:5120
	ds_read_b128 v[210:213], v236 offset:6144
	ds_read_b128 v[214:217], v236 offset:7168
	global_load_lds_dwordx4 v190, s[76:77]
	s_add_i32 m0, s9, 0xe000
	s_nop 0
	global_load_lds_dwordx4 v192, s[76:77]
	s_waitcnt vmcnt(8)
	s_waitcnt lgkmcnt(0)
	s_barrier
	s_setprio 1
	s_waitcnt lgkmcnt(0)
	v_mfma_f32_16x16x32_bf16 v[124:127], v[128:131], v[160:163], v[124:127]
	v_mfma_f32_16x16x32_bf16 v[124:127], v[132:135], v[164:167], v[124:127]
	v_mfma_f32_16x16x32_bf16 v[120:123], v[136:139], v[160:163], v[120:123]
	v_mfma_f32_16x16x32_bf16 v[120:123], v[140:143], v[164:167], v[120:123]
	v_mfma_f32_16x16x32_bf16 v[116:119], v[144:147], v[160:163], v[116:119]
	v_mfma_f32_16x16x32_bf16 v[116:119], v[148:151], v[164:167], v[116:119]
	v_mfma_f32_16x16x32_bf16 v[112:115], v[152:155], v[160:163], v[112:115]
	v_mfma_f32_16x16x32_bf16 v[112:115], v[156:159], v[164:167], v[112:115]
	v_mfma_f32_16x16x32_bf16 v[108:111], v[128:131], v[194:197], v[108:111]
	v_mfma_f32_16x16x32_bf16 v[108:111], v[132:135], v[198:201], v[108:111]
	v_mfma_f32_16x16x32_bf16 v[104:107], v[136:139], v[194:197], v[104:107]
	v_mfma_f32_16x16x32_bf16 v[104:107], v[140:143], v[198:201], v[104:107]
	v_mfma_f32_16x16x32_bf16 v[96:99], v[144:147], v[194:197], v[96:99]
	v_mfma_f32_16x16x32_bf16 v[96:99], v[148:151], v[198:201], v[96:99]
	v_mfma_f32_16x16x32_bf16 v[88:91], v[152:155], v[194:197], v[88:91]
	v_mfma_f32_16x16x32_bf16 v[88:91], v[156:159], v[198:201], v[88:91]
	s_setprio 0
	s_setprio 1
	v_mfma_f32_16x16x32_bf16 v[100:103], v[128:131], v[202:205], v[100:103]
	v_mfma_f32_16x16x32_bf16 v[100:103], v[132:135], v[206:209], v[100:103]
	v_mfma_f32_16x16x32_bf16 v[92:95], v[136:139], v[202:205], v[92:95]
	v_mfma_f32_16x16x32_bf16 v[92:95], v[140:143], v[206:209], v[92:95]
	v_mfma_f32_16x16x32_bf16 v[80:83], v[144:147], v[202:205], v[80:83]
	v_mfma_f32_16x16x32_bf16 v[80:83], v[148:151], v[206:209], v[80:83]
	v_mfma_f32_16x16x32_bf16 v[72:75], v[152:155], v[202:205], v[72:75]
	v_mfma_f32_16x16x32_bf16 v[72:75], v[156:159], v[206:209], v[72:75]
	v_mfma_f32_16x16x32_bf16 v[84:87], v[128:131], v[210:213], v[84:87]
	v_mfma_f32_16x16x32_bf16 v[84:87], v[132:135], v[214:217], v[84:87]
	v_mfma_f32_16x16x32_bf16 v[76:79], v[136:139], v[210:213], v[76:79]
	v_mfma_f32_16x16x32_bf16 v[76:79], v[140:143], v[214:217], v[76:79]
	v_mfma_f32_16x16x32_bf16 v[68:71], v[144:147], v[210:213], v[68:71]
	v_mfma_f32_16x16x32_bf16 v[68:71], v[148:151], v[214:217], v[68:71]
	v_mfma_f32_16x16x32_bf16 v[64:67], v[152:155], v[210:213], v[64:67]
	v_mfma_f32_16x16x32_bf16 v[64:67], v[156:159], v[214:217], v[64:67]
	s_setprio 0
	s_barrier
	s_add_i32 s12, s12, s8
	s_mov_b32 m0, s12
	ds_read_b128 v[160:163], v236 offset:16384
	ds_read_b128 v[164:167], v236 offset:17408
	ds_read_b128 v[194:197], v236 offset:18432
	ds_read_b128 v[198:201], v236 offset:19456
	ds_read_b128 v[202:205], v236 offset:20480
	ds_read_b128 v[206:209], v236 offset:21504
	ds_read_b128 v[210:213], v236 offset:22528
	ds_read_b128 v[214:217], v236 offset:23552
	global_load_lds_dwordx4 v184, s[80:81]
	s_add_i32 m0, s12, 0x2000
	s_add_u32 s42, s80, 0x160000
	s_addc_u32 s43, s81, 0
	s_add_i32 s12, s13, s8
	global_load_lds_dwordx4 v188, s[80:81]
	s_mov_b32 m0, s12
	s_nop 0
	global_load_lds_dwordx4 v184, s[42:43]
	s_add_i32 m0, s12, 0x2000
	s_nop 0
	global_load_lds_dwordx4 v188, s[42:43]
	s_mov_b32 m0, s9
	s_nop 0
	global_load_lds_dwordx4 v182, s[82:83]
	s_mov_b32 m0, s10
	s_nop 0
	global_load_lds_dwordx4 v186, s[82:83]
	s_waitcnt vmcnt(8)
	s_waitcnt lgkmcnt(0)
	s_barrier
	s_setprio 1
	s_waitcnt lgkmcnt(0)
	v_mfma_f32_16x16x32_bf16 v[60:63], v[128:131], v[160:163], v[60:63]
	v_mfma_f32_16x16x32_bf16 v[60:63], v[132:135], v[164:167], v[60:63]
	v_mfma_f32_16x16x32_bf16 v[56:59], v[136:139], v[160:163], v[56:59]
	v_mfma_f32_16x16x32_bf16 v[56:59], v[140:143], v[164:167], v[56:59]
	v_mfma_f32_16x16x32_bf16 v[48:51], v[144:147], v[160:163], v[48:51]
	v_mfma_f32_16x16x32_bf16 v[48:51], v[148:151], v[164:167], v[48:51]
	v_mfma_f32_16x16x32_bf16 v[40:43], v[152:155], v[160:163], v[40:43]
	v_mfma_f32_16x16x32_bf16 v[40:43], v[156:159], v[164:167], v[40:43]
	v_mfma_f32_16x16x32_bf16 v[52:55], v[128:131], v[194:197], v[52:55]
	v_mfma_f32_16x16x32_bf16 v[52:55], v[132:135], v[198:201], v[52:55]
	v_mfma_f32_16x16x32_bf16 v[44:47], v[136:139], v[194:197], v[44:47]
	v_mfma_f32_16x16x32_bf16 v[44:47], v[140:143], v[198:201], v[44:47]
	v_mfma_f32_16x16x32_bf16 v[32:35], v[144:147], v[194:197], v[32:35]
	v_mfma_f32_16x16x32_bf16 v[32:35], v[148:151], v[198:201], v[32:35]
	v_mfma_f32_16x16x32_bf16 v[24:27], v[152:155], v[194:197], v[24:27]
	v_mfma_f32_16x16x32_bf16 v[24:27], v[156:159], v[198:201], v[24:27]
	s_setprio 0
	s_setprio 1
	v_mfma_f32_16x16x32_bf16 v[36:39], v[128:131], v[202:205], v[36:39]
	v_mfma_f32_16x16x32_bf16 v[36:39], v[132:135], v[206:209], v[36:39]
	v_mfma_f32_16x16x32_bf16 v[28:31], v[136:139], v[202:205], v[28:31]
	v_mfma_f32_16x16x32_bf16 v[28:31], v[140:143], v[206:209], v[28:31]
	v_mfma_f32_16x16x32_bf16 v[16:19], v[144:147], v[202:205], v[16:19]
	v_mfma_f32_16x16x32_bf16 v[16:19], v[148:151], v[206:209], v[16:19]
	v_mfma_f32_16x16x32_bf16 v[8:11], v[152:155], v[202:205], v[8:11]
	v_mfma_f32_16x16x32_bf16 v[8:11], v[156:159], v[206:209], v[8:11]
	v_mfma_f32_16x16x32_bf16 v[20:23], v[128:131], v[210:213], v[20:23]
	v_mfma_f32_16x16x32_bf16 v[20:23], v[132:135], v[214:217], v[20:23]
	v_mfma_f32_16x16x32_bf16 v[12:15], v[136:139], v[210:213], v[12:15]
	v_mfma_f32_16x16x32_bf16 v[12:15], v[140:143], v[214:217], v[12:15]
	v_mfma_f32_16x16x32_bf16 v[4:7], v[144:147], v[210:213], v[4:7]
	v_mfma_f32_16x16x32_bf16 v[4:7], v[148:151], v[214:217], v[4:7]
	v_mfma_f32_16x16x32_bf16 v[0:3], v[152:155], v[210:213], v[0:3]
	v_mfma_f32_16x16x32_bf16 v[0:3], v[156:159], v[214:217], v[0:3]
	s_setprio 0
	s_barrier
; #define PG8_STAGE(bufoff, gbase, voff) do { _Pragma("unroll") for (int _i = 0; _i < 2; ++_i) \
;         __builtin_amdgcn_global_load_lds((const unsigned*)((const char*)(gbase) + (voff)[_i]), (PG8_LAS unsigned*)(lds + (bufoff) + ldsw + _i * 8192), 16, 0, 0); } while (0)
; #define PG8_LDA(dst, b, h) do { _Pragma("unroll") for (int m = 0; m < 4; ++m) _Pragma("unroll") for (int k = 0; k < 2; ++k) dst[m][k] = *(const PG8_LAS bf16x8*)(lds + PG8_SA(b, h) + aoff + m * 2048 + k * 1024); } while (0)
; #define PG8_LDB(dst, b, h) do { _Pragma("unroll") for (int n = 0; n < 2; ++n) _Pragma("unroll") for (int k = 0; k < 2; ++k) dst[n][k] = *(const PG8_LAS bf16x8*)(lds + PG8_SB(b, h) + boff + n * 2048 + k * 1024); } while (0)
; #define PG8_MMA(ai, bj, At, Bt) do { __builtin_amdgcn_s_setprio(1); _Pragma("unroll") for (int m = 0; m < 4; ++m) _Pragma("unroll") for (int n = 0; n < 2; ++n) _Pragma("unroll") for (int k = 0; k < 2; ++k) \
;         acc[ai][bj][m][n] = __builtin_amdgcn_mfma_f32_16x16x32_bf16(Bt[n][k], At[m][k], acc[ai][bj][m][n], 0, 0, 0); __builtin_amdgcn_s_setprio(0); } while (0)
; #define PG8_WAIT_V(n) asm volatile("s_waitcnt vmcnt(" #n ")" ::: "memory")
; #define PG8_WAIT_L(n) asm volatile("s_waitcnt lgkmcnt(" #n ")" ::: "memory")
; #define PG8_BAR __builtin_amdgcn_s_barrier()
; #define PG8_SCHED __builtin_amdgcn_sched_barrier(0)
;     ...
;             PG8_LDB(B0, 1, 0); PG8_LDB(B1, 1, 1); PG8_SCHED; PG8_LDA(At, 1, 0); PG8_STAGE(PG8_SA(0, 1), a2 + hstep, voffA);
;             PG8_WAIT_V(8); PG8_WAIT_L(0); PG8_BAR; PG8_MMA(0, 0, At, B0); PG8_MMA(0, 1, At, B1); PG8_BAR; PG8_SCHED;
;             PG8_LDA(At, 1, 1); PG8_STAGE(PG8_SB(1, 0), b3, voffB); PG8_STAGE(PG8_SB(1, 1), b3 + hstep, voffB); PG8_STAGE(PG8_SA(1, 0), a3, voffA);
;             PG8_WAIT_V(8); PG8_WAIT_L(0); PG8_BAR; PG8_MMA(1, 0, At, B0); PG8_MMA(1, 1, At, B1); PG8_BAR; PG8_SCHED;
	s_add_i32 s12, 0, 0x18000
	s_add_i32 s13, 0, 0x1c000
	v_add_u32_e32 v140, s12, v233
	v_add_u32_e32 v156, s13, v233
	ds_read_b128 v[128:131], v140
	ds_read_b128 v[132:135], v140 offset:1024
	ds_read_b128 v[136:139], v140 offset:2048
	ds_read_b128 v[140:143], v140 offset:3072
	ds_read_b128 v[144:147], v156
	ds_read_b128 v[148:151], v156 offset:1024
	ds_read_b128 v[152:155], v156 offset:2048
	ds_read_b128 v[156:159], v156 offset:3072
	s_add_u32 s42, s82, 0x160000
	s_addc_u32 s43, s83, 0
	s_mov_b32 m0, s18
	ds_read_b128 v[160:163], v236 offset:32768
	ds_read_b128 v[164:167], v236 offset:33792
	ds_read_b128 v[194:197], v236 offset:34816
	ds_read_b128 v[198:201], v236 offset:35840
	ds_read_b128 v[202:205], v236 offset:36864
	ds_read_b128 v[206:209], v236 offset:37888
	ds_read_b128 v[210:213], v236 offset:38912
	ds_read_b128 v[214:217], v236 offset:39936
	global_load_lds_dwordx4 v182, s[42:43]
	s_mov_b32 m0, s19
	s_nop 0
	global_load_lds_dwordx4 v186, s[42:43]
	s_waitcnt vmcnt(8)
	s_waitcnt lgkmcnt(0)
	s_barrier
	s_setprio 1
	s_waitcnt lgkmcnt(0)
	v_mfma_f32_16x16x32_bf16 v[124:127], v[128:131], v[160:163], v[124:127]
	v_mfma_f32_16x16x32_bf16 v[124:127], v[132:135], v[164:167], v[124:127]
	v_mfma_f32_16x16x32_bf16 v[120:123], v[136:139], v[160:163], v[120:123]
	v_mfma_f32_16x16x32_bf16 v[120:123], v[140:143], v[164:167], v[120:123]
	v_mfma_f32_16x16x32_bf16 v[116:119], v[144:147], v[160:163], v[116:119]
	v_mfma_f32_16x16x32_bf16 v[116:119], v[148:151], v[164:167], v[116:119]
	v_mfma_f32_16x16x32_bf16 v[112:115], v[152:155], v[160:163], v[112:115]
	v_mfma_f32_16x16x32_bf16 v[112:115], v[156:159], v[164:167], v[112:115]
	v_mfma_f32_16x16x32_bf16 v[108:111], v[128:131], v[194:197], v[108:111]
	v_mfma_f32_16x16x32_bf16 v[108:111], v[132:135], v[198:201], v[108:111]
	v_mfma_f32_16x16x32_bf16 v[104:107], v[136:139], v[194:197], v[104:107]
	v_mfma_f32_16x16x32_bf16 v[104:107], v[140:143], v[198:201], v[104:107]
	v_mfma_f32_16x16x32_bf16 v[96:99], v[144:147], v[194:197], v[96:99]
	v_mfma_f32_16x16x32_bf16 v[96:99], v[148:151], v[198:201], v[96:99]
	v_mfma_f32_16x16x32_bf16 v[88:91], v[152:155], v[194:197], v[88:91]
	v_mfma_f32_16x16x32_bf16 v[88:91], v[156:159], v[198:201], v[88:91]
	s_setprio 0
	s_setprio 1
	v_mfma_f32_16x16x32_bf16 v[100:103], v[128:131], v[202:205], v[100:103]
	v_mfma_f32_16x16x32_bf16 v[100:103], v[132:135], v[206:209], v[100:103]
	v_mfma_f32_16x16x32_bf16 v[92:95], v[136:139], v[202:205], v[92:95]
	v_mfma_f32_16x16x32_bf16 v[92:95], v[140:143], v[206:209], v[92:95]
	v_mfma_f32_16x16x32_bf16 v[80:83], v[144:147], v[202:205], v[80:83]
	v_mfma_f32_16x16x32_bf16 v[80:83], v[148:151], v[206:209], v[80:83]
	v_mfma_f32_16x16x32_bf16 v[72:75], v[152:155], v[202:205], v[72:75]
	v_mfma_f32_16x16x32_bf16 v[72:75], v[156:159], v[206:209], v[72:75]
	v_mfma_f32_16x16x32_bf16 v[84:87], v[128:131], v[210:213], v[84:87]
	v_mfma_f32_16x16x32_bf16 v[84:87], v[132:135], v[214:217], v[84:87]
	v_mfma_f32_16x16x32_bf16 v[76:79], v[136:139], v[210:213], v[76:79]
	v_mfma_f32_16x16x32_bf16 v[76:79], v[140:143], v[214:217], v[76:79]
	v_mfma_f32_16x16x32_bf16 v[68:71], v[144:147], v[210:213], v[68:71]
	v_mfma_f32_16x16x32_bf16 v[68:71], v[148:151], v[214:217], v[68:71]
	v_mfma_f32_16x16x32_bf16 v[64:67], v[152:155], v[210:213], v[64:67]
	v_mfma_f32_16x16x32_bf16 v[64:67], v[156:159], v[214:217], v[64:67]
	s_setprio 0
	s_barrier
	s_add_i32 s12, s12, s8
	s_mov_b32 m0, s12
	ds_read_b128 v[160:163], v236 offset:49152
	ds_read_b128 v[164:167], v236 offset:50176
	ds_read_b128 v[194:197], v236 offset:51200
	ds_read_b128 v[198:201], v236 offset:52224
	ds_read_b128 v[202:205], v236 offset:53248
	ds_read_b128 v[206:209], v236 offset:54272
	ds_read_b128 v[210:213], v236 offset:55296
	ds_read_b128 v[214:217], v236 offset:56320
	s_add_u32 s100, s80, s38
	s_addc_u32 s101, s81, s39
	global_load_lds_dwordx4 v184, s[100:101]
	s_add_i32 m0, s12, 0x2000
	s_add_u32 s42, s80, 0x15ff80
	s_addc_u32 s43, s81, 0
	s_add_i32 s12, s13, s8
	global_load_lds_dwordx4 v188, s[100:101]
	s_mov_b32 m0, s12
	s_nop 0
	global_load_lds_dwordx4 v184, s[42:43]
	s_add_i32 m0, s12, 0x2000
	s_nop 0
	global_load_lds_dwordx4 v188, s[42:43]
	s_mov_b32 m0, s20
	s_nop 0
	s_add_u32 s100, s82, s38
	s_addc_u32 s101, s83, s39
	global_load_lds_dwordx4 v182, s[100:101]
	s_mov_b32 m0, s21
	s_nop 0
	global_load_lds_dwordx4 v186, s[100:101]
	s_waitcnt vmcnt(8)
	s_waitcnt lgkmcnt(0)
	s_barrier
	s_setprio 1
	s_waitcnt lgkmcnt(0)
	v_mfma_f32_16x16x32_bf16 v[60:63], v[128:131], v[160:163], v[60:63]
	v_mfma_f32_16x16x32_bf16 v[60:63], v[132:135], v[164:167], v[60:63]
	v_mfma_f32_16x16x32_bf16 v[56:59], v[136:139], v[160:163], v[56:59]
	v_mfma_f32_16x16x32_bf16 v[56:59], v[140:143], v[164:167], v[56:59]
	v_mfma_f32_16x16x32_bf16 v[48:51], v[144:147], v[160:163], v[48:51]
	v_mfma_f32_16x16x32_bf16 v[48:51], v[148:151], v[164:167], v[48:51]
	v_mfma_f32_16x16x32_bf16 v[40:43], v[152:155], v[160:163], v[40:43]
	v_mfma_f32_16x16x32_bf16 v[40:43], v[156:159], v[164:167], v[40:43]
	v_mfma_f32_16x16x32_bf16 v[52:55], v[128:131], v[194:197], v[52:55]
	v_mfma_f32_16x16x32_bf16 v[52:55], v[132:135], v[198:201], v[52:55]
	v_mfma_f32_16x16x32_bf16 v[44:47], v[136:139], v[194:197], v[44:47]
	v_mfma_f32_16x16x32_bf16 v[44:47], v[140:143], v[198:201], v[44:47]
	v_mfma_f32_16x16x32_bf16 v[32:35], v[144:147], v[194:197], v[32:35]
	v_mfma_f32_16x16x32_bf16 v[32:35], v[148:151], v[198:201], v[32:35]
	v_mfma_f32_16x16x32_bf16 v[24:27], v[152:155], v[194:197], v[24:27]
	v_mfma_f32_16x16x32_bf16 v[24:27], v[156:159], v[198:201], v[24:27]
	s_setprio 0
	s_setprio 1
	v_mfma_f32_16x16x32_bf16 v[36:39], v[128:131], v[202:205], v[36:39]
	v_mfma_f32_16x16x32_bf16 v[36:39], v[132:135], v[206:209], v[36:39]
	v_mfma_f32_16x16x32_bf16 v[28:31], v[136:139], v[202:205], v[28:31]
	v_mfma_f32_16x16x32_bf16 v[28:31], v[140:143], v[206:209], v[28:31]
	v_mfma_f32_16x16x32_bf16 v[16:19], v[144:147], v[202:205], v[16:19]
	v_mfma_f32_16x16x32_bf16 v[16:19], v[148:151], v[206:209], v[16:19]
	v_mfma_f32_16x16x32_bf16 v[8:11], v[152:155], v[202:205], v[8:11]
	v_mfma_f32_16x16x32_bf16 v[8:11], v[156:159], v[206:209], v[8:11]
	v_mfma_f32_16x16x32_bf16 v[20:23], v[128:131], v[210:213], v[20:23]
	v_mfma_f32_16x16x32_bf16 v[20:23], v[132:135], v[214:217], v[20:23]
	v_mfma_f32_16x16x32_bf16 v[12:15], v[136:139], v[210:213], v[12:15]
	v_mfma_f32_16x16x32_bf16 v[12:15], v[140:143], v[214:217], v[12:15]
	v_mfma_f32_16x16x32_bf16 v[4:7], v[144:147], v[210:213], v[4:7]
	v_mfma_f32_16x16x32_bf16 v[4:7], v[148:151], v[214:217], v[4:7]
	v_mfma_f32_16x16x32_bf16 v[0:3], v[152:155], v[210:213], v[0:3]
	v_mfma_f32_16x16x32_bf16 v[0:3], v[156:159], v[214:217], v[0:3]
	s_setprio 0
	s_barrier
	s_add_i32 s3, s3, 2
	s_add_u32 s2, s2, 0xffffff00
	s_addc_u32 s30, s30, -1
	s_cmpk_gt_u32 s3, 0x55
	s_mov_b64 s[76:77], s[78:79]
	s_cbranch_scc0 .LBB0_343
	v_mov_b64_e32 v[234:235], 0x7f
	v_mov_b64_e32 v[174:175], 0x80
	v_mov_b64_e32 v[226:227], 0xb00
	s_and_b64 vcc, exec, s[72:73]
	s_cbranch_vccz .LBB0_346
	s_barrier

; #define PG8_STAGE(bufoff, gbase, voff) do { _Pragma("unroll") for (int _i = 0; _i < 2; ++_i) \
;         __builtin_amdgcn_global_load_lds((const unsigned*)((const char*)(gbase) + (voff)[_i]), (PG8_LAS unsigned*)(lds + (bufoff) + ldsw + _i * 8192), 16, 0, 0); } while (0)
; #define PG8_LDA(dst, b, h) do { _Pragma("unroll") for (int m = 0; m < 4; ++m) _Pragma("unroll") for (int k = 0; k < 2; ++k) dst[m][k] = *(const PG8_LAS bf16x8*)(lds + PG8_SA(b, h) + aoff + m * 2048 + k * 1024); } while (0)
; #define PG8_LDB(dst, b, h) do { _Pragma("unroll") for (int n = 0; n < 2; ++n) _Pragma("unroll") for (int k = 0; k < 2; ++k) dst[n][k] = *(const PG8_LAS bf16x8*)(lds + PG8_SB(b, h) + boff + n * 2048 + k * 1024); } while (0)
; #define PG8_MMA(ai, bj, At, Bt) do { __builtin_amdgcn_s_setprio(1); _Pragma("unroll") for (int m = 0; m < 4; ++m) _Pragma("unroll") for (int n = 0; n < 2; ++n) _Pragma("unroll") for (int k = 0; k < 2; ++k) \
;         acc[ai][bj][m][n] = __builtin_amdgcn_mfma_f32_16x16x32_bf16(Bt[n][k], At[m][k], acc[ai][bj][m][n], 0, 0, 0); __builtin_amdgcn_s_setprio(0); } while (0)
; #define PG8_WAIT_V(n) asm volatile("s_waitcnt vmcnt(" #n ")" ::: "memory")
; #define PG8_WAIT_L(n) asm volatile("s_waitcnt lgkmcnt(" #n ")" ::: "memory")
; #define PG8_BAR __builtin_amdgcn_s_barrier()
; #define PG8_SCHED __builtin_amdgcn_sched_barrier(0)
;     ...
;             const bool last = (t == nt - 2);
;             const char* a1 = PG8_KADV(cA, (size_t)(t + 1) * kstep);
;             const char* a2 = last ? nA : PG8_KADV(cA, (size_t)(t + 2) * kstep); const char* b2 = last ? nB : PG8_KADV(cB, (size_t)(t + 2) * kstep);
;             const char* a3 = PG8_KADV(a2, kstep); const char* b3 = PG8_KADV(b2, kstep);
;             if (last && has_next) S.a_ready(nxt);
;             if constexpr (SP2) {
;             PG8_LDB(B0, 0, 0); PG8_LDB(B1, 0, 1); PG8_SCHED; PG8_LDA(At, 0, 0); PG8_STAGE(PG8_SA(1, 1), a1 + hstep, voffA);
;             PG8_WAIT_V(8); PG8_WAIT_L(0); PG8_BAR; PG8_MMA(0, 0, At, B0); PG8_MMA(0, 1, At, B1); PG8_BAR; PG8_SCHED;
;             PG8_LDA(At, 0, 1); PG8_STAGE(PG8_SB(0, 0), b2, voffB); PG8_STAGE(PG8_SB(0, 1), b2 + hstep, voffB); PG8_STAGE(PG8_SA(0, 0), a2, voffA);
;             PG8_WAIT_V(8); PG8_WAIT_L(0); PG8_BAR; PG8_MMA(1, 0, At, B0); PG8_MMA(1, 1, At, B1); PG8_BAR; PG8_SCHED;
.LBB0_490:
	s_add_u32 s3, s86, 0xfff80080
	s_addc_u32 s12, s87, -1
	s_add_i32 s13, 0, 0x10000
	s_cmp_eq_u32 s2, 28
	s_cselect_b32 s91, s23, s12
	s_cselect_b32 s90, s25, s3
	s_cselect_b32 s89, s28, s40
	s_cselect_b32 s88, s30, s33
	s_add_i32 s3, 0, 0x14000
	v_add_u32_e32 v156, s13, v141
	v_add_u32_e32 v168, s3, v141
	ds_read_b128 v[144:147], v156
	ds_read_b128 v[148:151], v156 offset:1024
	ds_read_b128 v[152:155], v156 offset:2048
	ds_read_b128 v[156:159], v156 offset:3072
	ds_read_b128 v[160:163], v168
	ds_read_b128 v[164:167], v168 offset:1024
	ds_read_b128 v[170:173], v168 offset:2048
	ds_read_b128 v[178:181], v168 offset:3072
	s_add_i32 m0, s9, 0xc000
	ds_read_b128 v[182:185], v143
	ds_read_b128 v[186:189], v143 offset:1024
	ds_read_b128 v[190:193], v143 offset:2048
	ds_read_b128 v[194:197], v143 offset:3072
	ds_read_b128 v[198:201], v143 offset:4096
	ds_read_b128 v[202:205], v143 offset:5120
	ds_read_b128 v[206:209], v143 offset:6144
	ds_read_b128 v[210:213], v143 offset:7168
	global_load_lds_dwordx4 v136, s[86:87]
	s_add_i32 m0, s9, 0xe000
	s_nop 0
	global_load_lds_dwordx4 v138, s[86:87]
	s_waitcnt vmcnt(8)
	s_waitcnt lgkmcnt(0)
	s_barrier
	s_setprio 1
	s_waitcnt lgkmcnt(0)
	v_mfma_f32_16x16x32_bf16 v[124:127], v[144:147], v[182:185], v[124:127]
	v_mfma_f32_16x16x32_bf16 v[124:127], v[148:151], v[186:189], v[124:127]
	v_mfma_f32_16x16x32_bf16 v[120:123], v[152:155], v[182:185], v[120:123]
	v_mfma_f32_16x16x32_bf16 v[120:123], v[156:159], v[186:189], v[120:123]
	v_mfma_f32_16x16x32_bf16 v[108:111], v[160:163], v[182:185], v[108:111]
	v_mfma_f32_16x16x32_bf16 v[108:111], v[164:167], v[186:189], v[108:111]
	v_mfma_f32_16x16x32_bf16 v[104:107], v[170:173], v[182:185], v[104:107]
	v_mfma_f32_16x16x32_bf16 v[104:107], v[178:181], v[186:189], v[104:107]
	v_mfma_f32_16x16x32_bf16 v[116:119], v[144:147], v[190:193], v[116:119]
	v_mfma_f32_16x16x32_bf16 v[116:119], v[148:151], v[194:197], v[116:119]
	v_mfma_f32_16x16x32_bf16 v[112:115], v[152:155], v[190:193], v[112:115]
	v_mfma_f32_16x16x32_bf16 v[112:115], v[156:159], v[194:197], v[112:115]
	v_mfma_f32_16x16x32_bf16 v[92:95], v[160:163], v[190:193], v[92:95]
	v_mfma_f32_16x16x32_bf16 v[92:95], v[164:167], v[194:197], v[92:95]
	v_mfma_f32_16x16x32_bf16 v[88:91], v[170:173], v[190:193], v[88:91]
	v_mfma_f32_16x16x32_bf16 v[88:91], v[178:181], v[194:197], v[88:91]
	s_setprio 0
	s_setprio 1
	v_mfma_f32_16x16x32_bf16 v[100:103], v[144:147], v[198:201], v[100:103]
	v_mfma_f32_16x16x32_bf16 v[100:103], v[148:151], v[202:205], v[100:103]
	v_mfma_f32_16x16x32_bf16 v[96:99], v[152:155], v[198:201], v[96:99]
	v_mfma_f32_16x16x32_bf16 v[96:99], v[156:159], v[202:205], v[96:99]
	v_mfma_f32_16x16x32_bf16 v[76:79], v[160:163], v[198:201], v[76:79]
	v_mfma_f32_16x16x32_bf16 v[76:79], v[164:167], v[202:205], v[76:79]
	v_mfma_f32_16x16x32_bf16 v[72:75], v[170:173], v[198:201], v[72:75]
	v_mfma_f32_16x16x32_bf16 v[72:75], v[178:181], v[202:205], v[72:75]
	v_mfma_f32_16x16x32_bf16 v[84:87], v[144:147], v[206:209], v[84:87]
	v_mfma_f32_16x16x32_bf16 v[84:87], v[148:151], v[210:213], v[84:87]
	v_mfma_f32_16x16x32_bf16 v[80:83], v[152:155], v[206:209], v[80:83]
	v_mfma_f32_16x16x32_bf16 v[80:83], v[156:159], v[210:213], v[80:83]
	v_mfma_f32_16x16x32_bf16 v[68:71], v[160:163], v[206:209], v[68:71]
	v_mfma_f32_16x16x32_bf16 v[68:71], v[164:167], v[210:213], v[68:71]
	v_mfma_f32_16x16x32_bf16 v[64:67], v[170:173], v[206:209], v[64:67]
	v_mfma_f32_16x16x32_bf16 v[64:67], v[178:181], v[210:213], v[64:67]
	s_setprio 0
	s_barrier
	s_add_i32 s12, s13, s8
	s_mov_b32 m0, s12
	ds_read_b128 v[182:185], v143 offset:16384
	ds_read_b128 v[186:189], v143 offset:17408
	ds_read_b128 v[190:193], v143 offset:18432
	ds_read_b128 v[194:197], v143 offset:19456
	ds_read_b128 v[198:201], v143 offset:20480
	ds_read_b128 v[202:205], v143 offset:21504
	ds_read_b128 v[206:209], v143 offset:22528
	ds_read_b128 v[210:213], v143 offset:23552
	global_load_lds_dwordx4 v130, s[88:89]
	s_add_i32 m0, s12, 0x2000
	s_add_u32 s42, s88, 0x80000
	s_addc_u32 s43, s89, 0
	s_add_i32 s3, s3, s8
	global_load_lds_dwordx4 v134, s[88:89]
	s_mov_b32 m0, s3
	s_nop 0
	global_load_lds_dwordx4 v130, s[42:43]
	s_add_i32 m0, s3, 0x2000
	s_nop 0
	global_load_lds_dwordx4 v134, s[42:43]
	s_mov_b32 m0, s9
	s_nop 0
	global_load_lds_dwordx4 v128, s[90:91]
	s_mov_b32 m0, s10
	s_nop 0
	global_load_lds_dwordx4 v132, s[90:91]
	s_waitcnt vmcnt(8)
	s_waitcnt lgkmcnt(0)
	s_barrier
	s_setprio 1
	s_waitcnt lgkmcnt(0)
	v_mfma_f32_16x16x32_bf16 v[60:63], v[144:147], v[182:185], v[60:63]
	v_mfma_f32_16x16x32_bf16 v[60:63], v[148:151], v[186:189], v[60:63]
	v_mfma_f32_16x16x32_bf16 v[56:59], v[152:155], v[182:185], v[56:59]
	v_mfma_f32_16x16x32_bf16 v[56:59], v[156:159], v[186:189], v[56:59]
	v_mfma_f32_16x16x32_bf16 v[44:47], v[160:163], v[182:185], v[44:47]
	v_mfma_f32_16x16x32_bf16 v[44:47], v[164:167], v[186:189], v[44:47]
	v_mfma_f32_16x16x32_bf16 v[40:43], v[170:173], v[182:185], v[40:43]
	v_mfma_f32_16x16x32_bf16 v[40:43], v[178:181], v[186:189], v[40:43]
	v_mfma_f32_16x16x32_bf16 v[52:55], v[144:147], v[190:193], v[52:55]
	v_mfma_f32_16x16x32_bf16 v[52:55], v[148:151], v[194:197], v[52:55]
	v_mfma_f32_16x16x32_bf16 v[48:51], v[152:155], v[190:193], v[48:51]
	v_mfma_f32_16x16x32_bf16 v[48:51], v[156:159], v[194:197], v[48:51]
	v_mfma_f32_16x16x32_bf16 v[28:31], v[160:163], v[190:193], v[28:31]
	v_mfma_f32_16x16x32_bf16 v[28:31], v[164:167], v[194:197], v[28:31]
	v_mfma_f32_16x16x32_bf16 v[24:27], v[170:173], v[190:193], v[24:27]
	v_mfma_f32_16x16x32_bf16 v[24:27], v[178:181], v[194:197], v[24:27]
	s_setprio 0
	s_setprio 1
	v_mfma_f32_16x16x32_bf16 v[36:39], v[144:147], v[198:201], v[36:39]
	v_mfma_f32_16x16x32_bf16 v[36:39], v[148:151], v[202:205], v[36:39]
	v_mfma_f32_16x16x32_bf16 v[32:35], v[152:155], v[198:201], v[32:35]
	v_mfma_f32_16x16x32_bf16 v[32:35], v[156:159], v[202:205], v[32:35]
	v_mfma_f32_16x16x32_bf16 v[12:15], v[160:163], v[198:201], v[12:15]
	v_mfma_f32_16x16x32_bf16 v[12:15], v[164:167], v[202:205], v[12:15]
	v_mfma_f32_16x16x32_bf16 v[8:11], v[170:173], v[198:201], v[8:11]
	v_mfma_f32_16x16x32_bf16 v[8:11], v[178:181], v[202:205], v[8:11]
	v_mfma_f32_16x16x32_bf16 v[20:23], v[144:147], v[206:209], v[20:23]
	v_mfma_f32_16x16x32_bf16 v[20:23], v[148:151], v[210:213], v[20:23]
	v_mfma_f32_16x16x32_bf16 v[16:19], v[152:155], v[206:209], v[16:19]
	v_mfma_f32_16x16x32_bf16 v[16:19], v[156:159], v[210:213], v[16:19]
	v_mfma_f32_16x16x32_bf16 v[4:7], v[160:163], v[206:209], v[4:7]
	v_mfma_f32_16x16x32_bf16 v[4:7], v[164:167], v[210:213], v[4:7]
	v_mfma_f32_16x16x32_bf16 v[0:3], v[170:173], v[206:209], v[0:3]
	v_mfma_f32_16x16x32_bf16 v[0:3], v[178:181], v[210:213], v[0:3]
	s_setprio 0
	s_barrier
; #define PG8_STAGE(bufoff, gbase, voff) do { _Pragma("unroll") for (int _i = 0; _i < 2; ++_i) \
;         __builtin_amdgcn_global_load_lds((const unsigned*)((const char*)(gbase) + (voff)[_i]), (PG8_LAS unsigned*)(lds + (bufoff) + ldsw + _i * 8192), 16, 0, 0); } while (0)
; #define PG8_LDA(dst, b, h) do { _Pragma("unroll") for (int m = 0; m < 4; ++m) _Pragma("unroll") for (int k = 0; k < 2; ++k) dst[m][k] = *(const PG8_LAS bf16x8*)(lds + PG8_SA(b, h) + aoff + m * 2048 + k * 1024); } while (0)
; #define PG8_LDB(dst, b, h) do { _Pragma("unroll") for (int n = 0; n < 2; ++n) _Pragma("unroll") for (int k = 0; k < 2; ++k) dst[n][k] = *(const PG8_LAS bf16x8*)(lds + PG8_SB(b, h) + boff + n * 2048 + k * 1024); } while (0)
; #define PG8_MMA(ai, bj, At, Bt) do { __builtin_amdgcn_s_setprio(1); _Pragma("unroll") for (int m = 0; m < 4; ++m) _Pragma("unroll") for (int n = 0; n < 2; ++n) _Pragma("unroll") for (int k = 0; k < 2; ++k) \
;         acc[ai][bj][m][n] = __builtin_amdgcn_mfma_f32_16x16x32_bf16(Bt[n][k], At[m][k], acc[ai][bj][m][n], 0, 0, 0); __builtin_amdgcn_s_setprio(0); } while (0)
; #define PG8_WAIT_V(n) asm volatile("s_waitcnt vmcnt(" #n ")" ::: "memory")
; #define PG8_WAIT_L(n) asm volatile("s_waitcnt lgkmcnt(" #n ")" ::: "memory")
; #define PG8_BAR __builtin_amdgcn_s_barrier()
; #define PG8_SCHED __builtin_amdgcn_sched_barrier(0)
;     ...
;             PG8_LDB(B0, 1, 0); PG8_LDB(B1, 1, 1); PG8_SCHED; PG8_LDA(At, 1, 0); PG8_STAGE(PG8_SA(0, 1), a2 + hstep, voffA);
;             PG8_WAIT_V(8); PG8_WAIT_L(0); PG8_BAR; PG8_MMA(0, 0, At, B0); PG8_MMA(0, 1, At, B1); PG8_BAR; PG8_SCHED;
;             PG8_LDA(At, 1, 1); PG8_STAGE(PG8_SB(1, 0), b3, voffB); PG8_STAGE(PG8_SB(1, 1), b3 + hstep, voffB); PG8_STAGE(PG8_SA(1, 0), a3, voffA);
;             PG8_WAIT_V(8); PG8_WAIT_L(0); PG8_BAR; PG8_MMA(1, 0, At, B0); PG8_MMA(1, 1, At, B1); PG8_BAR; PG8_SCHED;
	s_add_i32 s3, 0, 0x18000
	s_add_i32 s12, 0, 0x1c000
	v_add_u32_e32 v156, s3, v141
	v_add_u32_e32 v168, s12, v141
	ds_read_b128 v[144:147], v156
	ds_read_b128 v[148:151], v156 offset:1024
	ds_read_b128 v[152:155], v156 offset:2048
	ds_read_b128 v[156:159], v156 offset:3072
	ds_read_b128 v[160:163], v168
	ds_read_b128 v[164:167], v168 offset:1024
	ds_read_b128 v[170:173], v168 offset:2048
	ds_read_b128 v[178:181], v168 offset:3072
	s_add_u32 s42, s90, 0x80000
	s_addc_u32 s43, s91, 0
	s_mov_b32 m0, s18
	ds_read_b128 v[182:185], v143 offset:32768
	ds_read_b128 v[186:189], v143 offset:33792
	ds_read_b128 v[190:193], v143 offset:34816
	ds_read_b128 v[194:197], v143 offset:35840
	ds_read_b128 v[198:201], v143 offset:36864
	ds_read_b128 v[202:205], v143 offset:37888
	ds_read_b128 v[206:209], v143 offset:38912
	ds_read_b128 v[210:213], v143 offset:39936
	global_load_lds_dwordx4 v128, s[42:43]
	s_mov_b32 m0, s19
	s_nop 0
	global_load_lds_dwordx4 v132, s[42:43]
	s_waitcnt vmcnt(8)
	s_waitcnt lgkmcnt(0)
	s_barrier
	s_setprio 1
	s_waitcnt lgkmcnt(0)
	v_mfma_f32_16x16x32_bf16 v[124:127], v[144:147], v[182:185], v[124:127]
	v_mfma_f32_16x16x32_bf16 v[124:127], v[148:151], v[186:189], v[124:127]
	v_mfma_f32_16x16x32_bf16 v[120:123], v[152:155], v[182:185], v[120:123]
	v_mfma_f32_16x16x32_bf16 v[120:123], v[156:159], v[186:189], v[120:123]
	v_mfma_f32_16x16x32_bf16 v[108:111], v[160:163], v[182:185], v[108:111]
	v_mfma_f32_16x16x32_bf16 v[108:111], v[164:167], v[186:189], v[108:111]
	v_mfma_f32_16x16x32_bf16 v[104:107], v[170:173], v[182:185], v[104:107]
	v_mfma_f32_16x16x32_bf16 v[104:107], v[178:181], v[186:189], v[104:107]
	v_mfma_f32_16x16x32_bf16 v[116:119], v[144:147], v[190:193], v[116:119]
	v_mfma_f32_16x16x32_bf16 v[116:119], v[148:151], v[194:197], v[116:119]
	v_mfma_f32_16x16x32_bf16 v[112:115], v[152:155], v[190:193], v[112:115]
	v_mfma_f32_16x16x32_bf16 v[112:115], v[156:159], v[194:197], v[112:115]
	v_mfma_f32_16x16x32_bf16 v[92:95], v[160:163], v[190:193], v[92:95]
	v_mfma_f32_16x16x32_bf16 v[92:95], v[164:167], v[194:197], v[92:95]
	v_mfma_f32_16x16x32_bf16 v[88:91], v[170:173], v[190:193], v[88:91]
	v_mfma_f32_16x16x32_bf16 v[88:91], v[178:181], v[194:197], v[88:91]
	s_setprio 0
	s_setprio 1
	v_mfma_f32_16x16x32_bf16 v[100:103], v[144:147], v[198:201], v[100:103]
	v_mfma_f32_16x16x32_bf16 v[100:103], v[148:151], v[202:205], v[100:103]
	v_mfma_f32_16x16x32_bf16 v[96:99], v[152:155], v[198:201], v[96:99]
	v_mfma_f32_16x16x32_bf16 v[96:99], v[156:159], v[202:205], v[96:99]
	v_mfma_f32_16x16x32_bf16 v[76:79], v[160:163], v[198:201], v[76:79]
	v_mfma_f32_16x16x32_bf16 v[76:79], v[164:167], v[202:205], v[76:79]
	v_mfma_f32_16x16x32_bf16 v[72:75], v[170:173], v[198:201], v[72:75]
	v_mfma_f32_16x16x32_bf16 v[72:75], v[178:181], v[202:205], v[72:75]
	v_mfma_f32_16x16x32_bf16 v[84:87], v[144:147], v[206:209], v[84:87]
	v_mfma_f32_16x16x32_bf16 v[84:87], v[148:151], v[210:213], v[84:87]
	v_mfma_f32_16x16x32_bf16 v[80:83], v[152:155], v[206:209], v[80:83]
	v_mfma_f32_16x16x32_bf16 v[80:83], v[156:159], v[210:213], v[80:83]
	v_mfma_f32_16x16x32_bf16 v[68:71], v[160:163], v[206:209], v[68:71]
	v_mfma_f32_16x16x32_bf16 v[68:71], v[164:167], v[210:213], v[68:71]
	v_mfma_f32_16x16x32_bf16 v[64:67], v[170:173], v[206:209], v[64:67]
	v_mfma_f32_16x16x32_bf16 v[64:67], v[178:181], v[210:213], v[64:67]
	s_setprio 0
	s_barrier
	s_add_i32 s3, s3, s8
	s_mov_b32 m0, s3
	ds_read_b128 v[182:185], v143 offset:49152
	ds_read_b128 v[186:189], v143 offset:50176
	ds_read_b128 v[190:193], v143 offset:51200
	ds_read_b128 v[194:197], v143 offset:52224
	ds_read_b128 v[198:201], v143 offset:53248
	ds_read_b128 v[202:205], v143 offset:54272
	ds_read_b128 v[206:209], v143 offset:55296
	ds_read_b128 v[210:213], v143 offset:56320
	s_add_u32 s100, s88, s16
	s_addc_u32 s101, s89, s17
	global_load_lds_dwordx4 v130, s[100:101]
	s_add_i32 m0, s3, 0x2000
	s_add_u32 s42, s88, 0x80080
	s_addc_u32 s43, s89, 0
	s_add_i32 s3, s12, s8
	global_load_lds_dwordx4 v134, s[100:101]
	s_mov_b32 m0, s3
	s_nop 0
	global_load_lds_dwordx4 v130, s[42:43]
	s_add_i32 m0, s3, 0x2000
	s_nop 0
	global_load_lds_dwordx4 v134, s[42:43]
	s_mov_b32 m0, s20
	s_nop 0
	s_add_u32 s100, s90, s16
	s_addc_u32 s101, s91, s17
	global_load_lds_dwordx4 v128, s[100:101]
	s_mov_b32 m0, s21
	s_nop 0
	global_load_lds_dwordx4 v132, s[100:101]
	s_waitcnt vmcnt(8)
	s_waitcnt lgkmcnt(0)
	s_barrier
	s_setprio 1
	s_waitcnt lgkmcnt(0)
	v_mfma_f32_16x16x32_bf16 v[60:63], v[144:147], v[182:185], v[60:63]
	v_mfma_f32_16x16x32_bf16 v[60:63], v[148:151], v[186:189], v[60:63]
	v_mfma_f32_16x16x32_bf16 v[56:59], v[152:155], v[182:185], v[56:59]
	v_mfma_f32_16x16x32_bf16 v[56:59], v[156:159], v[186:189], v[56:59]
	v_mfma_f32_16x16x32_bf16 v[44:47], v[160:163], v[182:185], v[44:47]
	v_mfma_f32_16x16x32_bf16 v[44:47], v[164:167], v[186:189], v[44:47]
	v_mfma_f32_16x16x32_bf16 v[40:43], v[170:173], v[182:185], v[40:43]
	v_mfma_f32_16x16x32_bf16 v[40:43], v[178:181], v[186:189], v[40:43]
	v_mfma_f32_16x16x32_bf16 v[52:55], v[144:147], v[190:193], v[52:55]
	v_mfma_f32_16x16x32_bf16 v[52:55], v[148:151], v[194:197], v[52:55]
	v_mfma_f32_16x16x32_bf16 v[48:51], v[152:155], v[190:193], v[48:51]
	v_mfma_f32_16x16x32_bf16 v[48:51], v[156:159], v[194:197], v[48:51]
	v_mfma_f32_16x16x32_bf16 v[28:31], v[160:163], v[190:193], v[28:31]
	v_mfma_f32_16x16x32_bf16 v[28:31], v[164:167], v[194:197], v[28:31]
	v_mfma_f32_16x16x32_bf16 v[24:27], v[170:173], v[190:193], v[24:27]
	v_mfma_f32_16x16x32_bf16 v[24:27], v[178:181], v[194:197], v[24:27]
	s_setprio 0
	s_setprio 1
	v_mfma_f32_16x16x32_bf16 v[36:39], v[144:147], v[198:201], v[36:39]
	v_mfma_f32_16x16x32_bf16 v[36:39], v[148:151], v[202:205], v[36:39]
	v_mfma_f32_16x16x32_bf16 v[32:35], v[152:155], v[198:201], v[32:35]
	v_mfma_f32_16x16x32_bf16 v[32:35], v[156:159], v[202:205], v[32:35]
	v_mfma_f32_16x16x32_bf16 v[12:15], v[160:163], v[198:201], v[12:15]
	v_mfma_f32_16x16x32_bf16 v[12:15], v[164:167], v[202:205], v[12:15]
	v_mfma_f32_16x16x32_bf16 v[8:11], v[170:173], v[198:201], v[8:11]
	v_mfma_f32_16x16x32_bf16 v[8:11], v[178:181], v[202:205], v[8:11]
	v_mfma_f32_16x16x32_bf16 v[20:23], v[144:147], v[206:209], v[20:23]
	v_mfma_f32_16x16x32_bf16 v[20:23], v[148:151], v[210:213], v[20:23]
	v_mfma_f32_16x16x32_bf16 v[16:19], v[152:155], v[206:209], v[16:19]
	v_mfma_f32_16x16x32_bf16 v[16:19], v[156:159], v[210:213], v[16:19]
	v_mfma_f32_16x16x32_bf16 v[4:7], v[160:163], v[206:209], v[4:7]
	v_mfma_f32_16x16x32_bf16 v[4:7], v[164:167], v[210:213], v[4:7]
	v_mfma_f32_16x16x32_bf16 v[0:3], v[170:173], v[206:209], v[0:3]
	v_mfma_f32_16x16x32_bf16 v[0:3], v[178:181], v[210:213], v[0:3]
	s_setprio 0
	s_barrier
	s_add_i32 s2, s2, 2
	s_add_u32 s86, s86, 0x100
	s_addc_u32 s87, s87, 0
	s_add_u32 s33, s33, 0x100
	s_addc_u32 s40, s40, 0
	s_cmp_gt_u32 s2, 29
	s_cbranch_scc0 .LBB0_490
	s_and_b64 vcc, exec, s[74:75]
	s_cbranch_vccz .LBB0_493
	s_barrier

; #define PG8_STAGE(bufoff, gbase, voff) do { _Pragma("unroll") for (int _i = 0; _i < 2; ++_i) \
;         __builtin_amdgcn_global_load_lds((const unsigned*)((const char*)(gbase) + (voff)[_i]), (PG8_LAS unsigned*)(lds + (bufoff) + ldsw + _i * 8192), 16, 0, 0); } while (0)
; #define PG8_LDA(dst, b, h) do { _Pragma("unroll") for (int m = 0; m < 4; ++m) _Pragma("unroll") for (int k = 0; k < 2; ++k) dst[m][k] = *(const PG8_LAS bf16x8*)(lds + PG8_SA(b, h) + aoff + m * 2048 + k * 1024); } while (0)
; #define PG8_LDB(dst, b, h) do { _Pragma("unroll") for (int n = 0; n < 2; ++n) _Pragma("unroll") for (int k = 0; k < 2; ++k) dst[n][k] = *(const PG8_LAS bf16x8*)(lds + PG8_SB(b, h) + boff + n * 2048 + k * 1024); } while (0)
; #define PG8_MMA(ai, bj, At, Bt) do { __builtin_amdgcn_s_setprio(1); _Pragma("unroll") for (int m = 0; m < 4; ++m) _Pragma("unroll") for (int n = 0; n < 2; ++n) _Pragma("unroll") for (int k = 0; k < 2; ++k) \
;         acc[ai][bj][m][n] = __builtin_amdgcn_mfma_f32_16x16x32_bf16(Bt[n][k], At[m][k], acc[ai][bj][m][n], 0, 0, 0); __builtin_amdgcn_s_setprio(0); } while (0)
; #define PG8_WAIT_V(n) asm volatile("s_waitcnt vmcnt(" #n ")" ::: "memory")
; #define PG8_WAIT_L(n) asm volatile("s_waitcnt lgkmcnt(" #n ")" ::: "memory")
; #define PG8_BAR __builtin_amdgcn_s_barrier()
; #define PG8_SCHED __builtin_amdgcn_sched_barrier(0)
;     ...
;             const bool last = (t == nt - 2);
;             const char* a1 = PG8_KADV(cA, (size_t)(t + 1) * kstep);
;             const char* a2 = last ? nA : PG8_KADV(cA, (size_t)(t + 2) * kstep); const char* b2 = last ? nB : PG8_KADV(cB, (size_t)(t + 2) * kstep);
;             const char* a3 = PG8_KADV(a2, kstep); const char* b3 = PG8_KADV(b2, kstep);
;             if (last && has_next) S.a_ready(nxt);
;             if constexpr (SP2) {
;             PG8_LDB(B0, 0, 0); PG8_LDB(B1, 0, 1); PG8_SCHED; PG8_LDA(At, 0, 0); PG8_STAGE(PG8_SA(1, 1), a1 + hstep, voffA);
;             PG8_WAIT_V(8); PG8_WAIT_L(0); PG8_BAR; PG8_MMA(0, 0, At, B0); PG8_MMA(0, 1, At, B1); PG8_BAR; PG8_SCHED;
;             PG8_LDA(At, 0, 1); PG8_STAGE(PG8_SB(0, 0), b2, voffB); PG8_STAGE(PG8_SB(0, 1), b2 + hstep, voffB); PG8_STAGE(PG8_SA(0, 0), a2, voffA);
.LBB0_514:
	s_add_u32 s3, s86, 0xfff80080
	s_addc_u32 s12, s87, -1
	s_add_i32 s13, 0, 0x10000
	s_cmp_eq_u32 s2, 28
	s_cselect_b32 s91, s28, s12
	s_cselect_b32 s90, s30, s3
	s_cselect_b32 s89, s33, s43
	s_cselect_b32 s88, s40, s42
	s_add_i32 s3, 0, 0x14000
	v_add_u32_e32 v156, s13, v141
	v_add_u32_e32 v168, s3, v141
	ds_read_b128 v[144:147], v156
	ds_read_b128 v[148:151], v156 offset:1024
	ds_read_b128 v[152:155], v156 offset:2048
	ds_read_b128 v[156:159], v156 offset:3072
	ds_read_b128 v[160:163], v168
	ds_read_b128 v[164:167], v168 offset:1024
	ds_read_b128 v[170:173], v168 offset:2048
	ds_read_b128 v[178:181], v168 offset:3072
	s_add_i32 m0, s18, 0xc000
	ds_read_b128 v[182:185], v143
	ds_read_b128 v[186:189], v143 offset:1024
	ds_read_b128 v[190:193], v143 offset:2048
	ds_read_b128 v[194:197], v143 offset:3072
	ds_read_b128 v[198:201], v143 offset:4096
	ds_read_b128 v[202:205], v143 offset:5120
	ds_read_b128 v[206:209], v143 offset:6144
	ds_read_b128 v[210:213], v143 offset:7168
	global_load_lds_dwordx4 v136, s[86:87]
	s_add_i32 m0, s18, 0xe000
	s_nop 0
	global_load_lds_dwordx4 v138, s[86:87]
	s_waitcnt vmcnt(8)
	s_waitcnt lgkmcnt(0)
	s_barrier
	s_setprio 1
	s_waitcnt lgkmcnt(0)
	v_mfma_f32_16x16x32_bf16 v[124:127], v[144:147], v[182:185], v[124:127]
	v_mfma_f32_16x16x32_bf16 v[124:127], v[148:151], v[186:189], v[124:127]
	v_mfma_f32_16x16x32_bf16 v[120:123], v[152:155], v[182:185], v[120:123]
	v_mfma_f32_16x16x32_bf16 v[120:123], v[156:159], v[186:189], v[120:123]
	v_mfma_f32_16x16x32_bf16 v[108:111], v[160:163], v[182:185], v[108:111]
	v_mfma_f32_16x16x32_bf16 v[108:111], v[164:167], v[186:189], v[108:111]
	v_mfma_f32_16x16x32_bf16 v[104:107], v[170:173], v[182:185], v[104:107]
	v_mfma_f32_16x16x32_bf16 v[104:107], v[178:181], v[186:189], v[104:107]
	v_mfma_f32_16x16x32_bf16 v[116:119], v[144:147], v[190:193], v[116:119]
	v_mfma_f32_16x16x32_bf16 v[116:119], v[148:151], v[194:197], v[116:119]
	v_mfma_f32_16x16x32_bf16 v[112:115], v[152:155], v[190:193], v[112:115]
	v_mfma_f32_16x16x32_bf16 v[112:115], v[156:159], v[194:197], v[112:115]
	v_mfma_f32_16x16x32_bf16 v[92:95], v[160:163], v[190:193], v[92:95]
	v_mfma_f32_16x16x32_bf16 v[92:95], v[164:167], v[194:197], v[92:95]
	v_mfma_f32_16x16x32_bf16 v[88:91], v[170:173], v[190:193], v[88:91]
	v_mfma_f32_16x16x32_bf16 v[88:91], v[178:181], v[194:197], v[88:91]
	s_setprio 0
	s_setprio 1
	v_mfma_f32_16x16x32_bf16 v[100:103], v[144:147], v[198:201], v[100:103]
	v_mfma_f32_16x16x32_bf16 v[100:103], v[148:151], v[202:205], v[100:103]
	v_mfma_f32_16x16x32_bf16 v[96:99], v[152:155], v[198:201], v[96:99]
	v_mfma_f32_16x16x32_bf16 v[96:99], v[156:159], v[202:205], v[96:99]
	v_mfma_f32_16x16x32_bf16 v[76:79], v[160:163], v[198:201], v[76:79]
	v_mfma_f32_16x16x32_bf16 v[76:79], v[164:167], v[202:205], v[76:79]
	v_mfma_f32_16x16x32_bf16 v[72:75], v[170:173], v[198:201], v[72:75]
	v_mfma_f32_16x16x32_bf16 v[72:75], v[178:181], v[202:205], v[72:75]
	v_mfma_f32_16x16x32_bf16 v[84:87], v[144:147], v[206:209], v[84:87]
	v_mfma_f32_16x16x32_bf16 v[84:87], v[148:151], v[210:213], v[84:87]
	v_mfma_f32_16x16x32_bf16 v[80:83], v[152:155], v[206:209], v[80:83]
	v_mfma_f32_16x16x32_bf16 v[80:83], v[156:159], v[210:213], v[80:83]
	v_mfma_f32_16x16x32_bf16 v[68:71], v[160:163], v[206:209], v[68:71]
	v_mfma_f32_16x16x32_bf16 v[68:71], v[164:167], v[210:213], v[68:71]
	v_mfma_f32_16x16x32_bf16 v[64:67], v[170:173], v[206:209], v[64:67]
	v_mfma_f32_16x16x32_bf16 v[64:67], v[178:181], v[210:213], v[64:67]
	s_setprio 0
	s_barrier
	s_add_i32 s12, s13, s10
	s_mov_b32 m0, s12
	ds_read_b128 v[182:185], v143 offset:16384
	ds_read_b128 v[186:189], v143 offset:17408
	ds_read_b128 v[190:193], v143 offset:18432
	ds_read_b128 v[194:197], v143 offset:19456
	ds_read_b128 v[198:201], v143 offset:20480
	ds_read_b128 v[202:205], v143 offset:21504
	ds_read_b128 v[206:209], v143 offset:22528
	ds_read_b128 v[210:213], v143 offset:23552
	global_load_lds_dwordx4 v130, s[88:89]
	s_add_i32 m0, s12, 0x2000
	s_add_u32 vcc_lo, s88, 0x80000
	v_lshl_add_u64 v[216:217], s[88:89], 0, v[134:135]
	s_addc_u32 vcc_hi, s89, 0
	s_add_i32 s3, s3, s10
	global_load_lds_dwordx4 v134, s[88:89]
	s_mov_b32 m0, s3
	v_lshl_add_u64 v[220:221], s[90:91], 0, v[132:133]
	global_load_lds_dwordx4 v130, vcc
	s_add_i32 m0, s3, 0x2000
	s_nop 0
	global_load_lds_dwordx4 v134, vcc
	v_lshl_add_u64 v[218:219], s[90:91], 0, v[128:129]
	s_mov_b32 m0, s18
	s_nop 0
	global_load_lds_dwordx4 v128, s[90:91]
	s_mov_b32 m0, s19
	s_nop 0
	global_load_lds_dwordx4 v132, s[90:91]
	s_waitcnt vmcnt(8)
	s_waitcnt lgkmcnt(0)
	s_barrier
; #define PG8_STAGE(bufoff, gbase, voff) do { _Pragma("unroll") for (int _i = 0; _i < 2; ++_i) \
;         __builtin_amdgcn_global_load_lds((const unsigned*)((const char*)(gbase) + (voff)[_i]), (PG8_LAS unsigned*)(lds + (bufoff) + ldsw + _i * 8192), 16, 0, 0); } while (0)
; #define PG8_LDA(dst, b, h) do { _Pragma("unroll") for (int m = 0; m < 4; ++m) _Pragma("unroll") for (int k = 0; k < 2; ++k) dst[m][k] = *(const PG8_LAS bf16x8*)(lds + PG8_SA(b, h) + aoff + m * 2048 + k * 1024); } while (0)
; #define PG8_LDB(dst, b, h) do { _Pragma("unroll") for (int n = 0; n < 2; ++n) _Pragma("unroll") for (int k = 0; k < 2; ++k) dst[n][k] = *(const PG8_LAS bf16x8*)(lds + PG8_SB(b, h) + boff + n * 2048 + k * 1024); } while (0)
; #define PG8_MMA(ai, bj, At, Bt) do { __builtin_amdgcn_s_setprio(1); _Pragma("unroll") for (int m = 0; m < 4; ++m) _Pragma("unroll") for (int n = 0; n < 2; ++n) _Pragma("unroll") for (int k = 0; k < 2; ++k) \
;         acc[ai][bj][m][n] = __builtin_amdgcn_mfma_f32_16x16x32_bf16(Bt[n][k], At[m][k], acc[ai][bj][m][n], 0, 0, 0); __builtin_amdgcn_s_setprio(0); } while (0)
; #define PG8_WAIT_V(n) asm volatile("s_waitcnt vmcnt(" #n ")" ::: "memory")
; #define PG8_WAIT_L(n) asm volatile("s_waitcnt lgkmcnt(" #n ")" ::: "memory")
; #define PG8_BAR __builtin_amdgcn_s_barrier()
; #define PG8_SCHED __builtin_amdgcn_sched_barrier(0)
;     ...
;             PG8_WAIT_V(8); PG8_WAIT_L(0); PG8_BAR; PG8_MMA(1, 0, At, B0); PG8_MMA(1, 1, At, B1); PG8_BAR; PG8_SCHED;
;             PG8_LDB(B0, 1, 0); PG8_LDB(B1, 1, 1); PG8_SCHED; PG8_LDA(At, 1, 0); PG8_STAGE(PG8_SA(0, 1), a2 + hstep, voffA);
;             PG8_WAIT_V(8); PG8_WAIT_L(0); PG8_BAR; PG8_MMA(0, 0, At, B0); PG8_MMA(0, 1, At, B1); PG8_BAR; PG8_SCHED;
	s_setprio 1
	s_waitcnt lgkmcnt(0)
	v_mfma_f32_16x16x32_bf16 v[60:63], v[144:147], v[182:185], v[60:63]
	v_mfma_f32_16x16x32_bf16 v[60:63], v[148:151], v[186:189], v[60:63]
	v_mfma_f32_16x16x32_bf16 v[56:59], v[152:155], v[182:185], v[56:59]
	v_mfma_f32_16x16x32_bf16 v[56:59], v[156:159], v[186:189], v[56:59]
	v_mfma_f32_16x16x32_bf16 v[44:47], v[160:163], v[182:185], v[44:47]
	v_mfma_f32_16x16x32_bf16 v[44:47], v[164:167], v[186:189], v[44:47]
	v_mfma_f32_16x16x32_bf16 v[40:43], v[170:173], v[182:185], v[40:43]
	v_mfma_f32_16x16x32_bf16 v[40:43], v[178:181], v[186:189], v[40:43]
	v_mfma_f32_16x16x32_bf16 v[52:55], v[144:147], v[190:193], v[52:55]
	v_mfma_f32_16x16x32_bf16 v[52:55], v[148:151], v[194:197], v[52:55]
	v_mfma_f32_16x16x32_bf16 v[48:51], v[152:155], v[190:193], v[48:51]
	v_mfma_f32_16x16x32_bf16 v[48:51], v[156:159], v[194:197], v[48:51]
	v_mfma_f32_16x16x32_bf16 v[28:31], v[160:163], v[190:193], v[28:31]
	v_mfma_f32_16x16x32_bf16 v[28:31], v[164:167], v[194:197], v[28:31]
	v_mfma_f32_16x16x32_bf16 v[24:27], v[170:173], v[190:193], v[24:27]
	v_mfma_f32_16x16x32_bf16 v[24:27], v[178:181], v[194:197], v[24:27]
	s_setprio 0
	s_setprio 1
	v_mfma_f32_16x16x32_bf16 v[36:39], v[144:147], v[198:201], v[36:39]
	v_mfma_f32_16x16x32_bf16 v[36:39], v[148:151], v[202:205], v[36:39]
	v_mfma_f32_16x16x32_bf16 v[32:35], v[152:155], v[198:201], v[32:35]
	v_mfma_f32_16x16x32_bf16 v[32:35], v[156:159], v[202:205], v[32:35]
	v_mfma_f32_16x16x32_bf16 v[12:15], v[160:163], v[198:201], v[12:15]
	v_mfma_f32_16x16x32_bf16 v[12:15], v[164:167], v[202:205], v[12:15]
	v_mfma_f32_16x16x32_bf16 v[8:11], v[170:173], v[198:201], v[8:11]
	v_mfma_f32_16x16x32_bf16 v[8:11], v[178:181], v[202:205], v[8:11]
	v_mfma_f32_16x16x32_bf16 v[20:23], v[144:147], v[206:209], v[20:23]
	v_mfma_f32_16x16x32_bf16 v[20:23], v[148:151], v[210:213], v[20:23]
	v_mfma_f32_16x16x32_bf16 v[16:19], v[152:155], v[206:209], v[16:19]
	v_mfma_f32_16x16x32_bf16 v[16:19], v[156:159], v[210:213], v[16:19]
	v_mfma_f32_16x16x32_bf16 v[4:7], v[160:163], v[206:209], v[4:7]
	v_mfma_f32_16x16x32_bf16 v[4:7], v[164:167], v[210:213], v[4:7]
	v_mfma_f32_16x16x32_bf16 v[0:3], v[170:173], v[206:209], v[0:3]
	v_mfma_f32_16x16x32_bf16 v[0:3], v[178:181], v[210:213], v[0:3]
	s_setprio 0
	s_barrier
	s_add_i32 s3, 0, 0x18000
	s_add_i32 s12, 0, 0x1c000
	v_add_u32_e32 v156, s3, v141
	v_add_u32_e32 v168, s12, v141
	ds_read_b128 v[144:147], v156
	ds_read_b128 v[148:151], v156 offset:1024
	ds_read_b128 v[152:155], v156 offset:2048
	ds_read_b128 v[156:159], v156 offset:3072
	ds_read_b128 v[160:163], v168
	ds_read_b128 v[164:167], v168 offset:1024
	ds_read_b128 v[170:173], v168 offset:2048
	ds_read_b128 v[178:181], v168 offset:3072
	s_add_u32 s90, s90, 0x80000
	s_addc_u32 s91, s91, 0
	s_mov_b32 m0, s20
	ds_read_b128 v[182:185], v143 offset:32768
	ds_read_b128 v[186:189], v143 offset:33792
	ds_read_b128 v[190:193], v143 offset:34816
	ds_read_b128 v[194:197], v143 offset:35840
	ds_read_b128 v[198:201], v143 offset:36864
	ds_read_b128 v[202:205], v143 offset:37888
	ds_read_b128 v[206:209], v143 offset:38912
	ds_read_b128 v[210:213], v143 offset:39936
	global_load_lds_dwordx4 v128, s[90:91]
	s_mov_b32 m0, s21
	s_nop 0
	global_load_lds_dwordx4 v132, s[90:91]
	s_waitcnt vmcnt(8)
	s_waitcnt lgkmcnt(0)
	s_barrier
	s_setprio 1
	s_waitcnt lgkmcnt(0)
	v_mfma_f32_16x16x32_bf16 v[124:127], v[144:147], v[182:185], v[124:127]
	v_mfma_f32_16x16x32_bf16 v[124:127], v[148:151], v[186:189], v[124:127]
	v_mfma_f32_16x16x32_bf16 v[120:123], v[152:155], v[182:185], v[120:123]
	v_mfma_f32_16x16x32_bf16 v[120:123], v[156:159], v[186:189], v[120:123]
	v_mfma_f32_16x16x32_bf16 v[108:111], v[160:163], v[182:185], v[108:111]
	v_mfma_f32_16x16x32_bf16 v[108:111], v[164:167], v[186:189], v[108:111]
	v_mfma_f32_16x16x32_bf16 v[104:107], v[170:173], v[182:185], v[104:107]
	v_mfma_f32_16x16x32_bf16 v[104:107], v[178:181], v[186:189], v[104:107]
	v_mfma_f32_16x16x32_bf16 v[116:119], v[144:147], v[190:193], v[116:119]
	v_mfma_f32_16x16x32_bf16 v[116:119], v[148:151], v[194:197], v[116:119]
	v_mfma_f32_16x16x32_bf16 v[112:115], v[152:155], v[190:193], v[112:115]
	v_mfma_f32_16x16x32_bf16 v[112:115], v[156:159], v[194:197], v[112:115]
	v_mfma_f32_16x16x32_bf16 v[92:95], v[160:163], v[190:193], v[92:95]
	v_mfma_f32_16x16x32_bf16 v[92:95], v[164:167], v[194:197], v[92:95]
	v_mfma_f32_16x16x32_bf16 v[88:91], v[170:173], v[190:193], v[88:91]
	v_mfma_f32_16x16x32_bf16 v[88:91], v[178:181], v[194:197], v[88:91]
	s_setprio 0
	s_setprio 1
	v_mfma_f32_16x16x32_bf16 v[100:103], v[144:147], v[198:201], v[100:103]
	v_mfma_f32_16x16x32_bf16 v[100:103], v[148:151], v[202:205], v[100:103]
	v_mfma_f32_16x16x32_bf16 v[96:99], v[152:155], v[198:201], v[96:99]
	v_mfma_f32_16x16x32_bf16 v[96:99], v[156:159], v[202:205], v[96:99]
	v_mfma_f32_16x16x32_bf16 v[76:79], v[160:163], v[198:201], v[76:79]
	v_mfma_f32_16x16x32_bf16 v[76:79], v[164:167], v[202:205], v[76:79]
	v_mfma_f32_16x16x32_bf16 v[72:75], v[170:173], v[198:201], v[72:75]
	v_mfma_f32_16x16x32_bf16 v[72:75], v[178:181], v[202:205], v[72:75]
	v_mfma_f32_16x16x32_bf16 v[84:87], v[144:147], v[206:209], v[84:87]
	v_mfma_f32_16x16x32_bf16 v[84:87], v[148:151], v[210:213], v[84:87]
	v_mfma_f32_16x16x32_bf16 v[80:83], v[152:155], v[206:209], v[80:83]
	v_mfma_f32_16x16x32_bf16 v[80:83], v[156:159], v[210:213], v[80:83]
	v_mfma_f32_16x16x32_bf16 v[68:71], v[160:163], v[206:209], v[68:71]
	v_mfma_f32_16x16x32_bf16 v[68:71], v[164:167], v[210:213], v[68:71]
	v_mfma_f32_16x16x32_bf16 v[64:67], v[170:173], v[206:209], v[64:67]
	v_mfma_f32_16x16x32_bf16 v[64:67], v[178:181], v[210:213], v[64:67]
	s_setprio 0
	s_barrier
; #define PG8_STAGE(bufoff, gbase, voff) do { _Pragma("unroll") for (int _i = 0; _i < 2; ++_i) \
;         __builtin_amdgcn_global_load_lds((const unsigned*)((const char*)(gbase) + (voff)[_i]), (PG8_LAS unsigned*)(lds + (bufoff) + ldsw + _i * 8192), 16, 0, 0); } while (0)
; #define PG8_LDA(dst, b, h) do { _Pragma("unroll") for (int m = 0; m < 4; ++m) _Pragma("unroll") for (int k = 0; k < 2; ++k) dst[m][k] = *(const PG8_LAS bf16x8*)(lds + PG8_SA(b, h) + aoff + m * 2048 + k * 1024); } while (0)
; #define PG8_MMA(ai, bj, At, Bt) do { __builtin_amdgcn_s_setprio(1); _Pragma("unroll") for (int m = 0; m < 4; ++m) _Pragma("unroll") for (int n = 0; n < 2; ++n) _Pragma("unroll") for (int k = 0; k < 2; ++k) \
;         acc[ai][bj][m][n] = __builtin_amdgcn_mfma_f32_16x16x32_bf16(Bt[n][k], At[m][k], acc[ai][bj][m][n], 0, 0, 0); __builtin_amdgcn_s_setprio(0); } while (0)
; #define PG8_WAIT_V(n) asm volatile("s_waitcnt vmcnt(" #n ")" ::: "memory")
; #define PG8_WAIT_L(n) asm volatile("s_waitcnt lgkmcnt(" #n ")" ::: "memory")
; #define PG8_BAR __builtin_amdgcn_s_barrier()
; #define PG8_SCHED __builtin_amdgcn_sched_barrier(0)
;     ...
;             PG8_LDA(At, 1, 1); PG8_STAGE(PG8_SB(1, 0), b3, voffB); PG8_STAGE(PG8_SB(1, 1), b3 + hstep, voffB); PG8_STAGE(PG8_SA(1, 0), a3, voffA);
;             PG8_WAIT_V(8); PG8_WAIT_L(0); PG8_BAR; PG8_MMA(1, 0, At, B0); PG8_MMA(1, 1, At, B1); PG8_BAR; PG8_SCHED;
	s_add_i32 s3, s3, s10
	s_mov_b32 m0, s3
	ds_read_b128 v[182:185], v143 offset:49152
	ds_read_b128 v[186:189], v143 offset:50176
	ds_read_b128 v[190:193], v143 offset:51200
	ds_read_b128 v[194:197], v143 offset:52224
	ds_read_b128 v[198:201], v143 offset:53248
	ds_read_b128 v[202:205], v143 offset:54272
	ds_read_b128 v[206:209], v143 offset:55296
	ds_read_b128 v[210:213], v143 offset:56320
	s_add_u32 s100, s88, s16
	s_addc_u32 s101, s89, s17
	global_load_lds_dwordx4 v130, s[100:101]
	s_add_i32 m0, s3, 0x2000
	s_add_u32 s88, s88, 0x80080
	v_lshl_add_u64 v[214:215], v[216:217], 0, s[16:17]
	s_addc_u32 s89, s89, 0
	s_add_i32 s3, s12, s10
	global_load_lds_dwordx4 v[214:215], off
	s_mov_b32 m0, s3
	s_nop 0
	global_load_lds_dwordx4 v130, s[88:89]
	s_add_i32 m0, s3, 0x2000
	s_nop 0
	global_load_lds_dwordx4 v134, s[88:89]
	v_lshl_add_u64 v[214:215], v[218:219], 0, s[16:17]
	s_mov_b32 m0, s22
	s_nop 0
	global_load_lds_dwordx4 v[214:215], off
	v_lshl_add_u64 v[214:215], v[220:221], 0, s[16:17]
	s_mov_b32 m0, s23
	s_nop 0
	global_load_lds_dwordx4 v[214:215], off
	s_waitcnt vmcnt(8)
	s_waitcnt lgkmcnt(0)
	s_barrier
	s_setprio 1
	s_waitcnt lgkmcnt(0)
	v_mfma_f32_16x16x32_bf16 v[60:63], v[144:147], v[182:185], v[60:63]
	v_mfma_f32_16x16x32_bf16 v[60:63], v[148:151], v[186:189], v[60:63]
	v_mfma_f32_16x16x32_bf16 v[56:59], v[152:155], v[182:185], v[56:59]
	v_mfma_f32_16x16x32_bf16 v[56:59], v[156:159], v[186:189], v[56:59]
	v_mfma_f32_16x16x32_bf16 v[44:47], v[160:163], v[182:185], v[44:47]
	v_mfma_f32_16x16x32_bf16 v[44:47], v[164:167], v[186:189], v[44:47]
	v_mfma_f32_16x16x32_bf16 v[40:43], v[170:173], v[182:185], v[40:43]
	v_mfma_f32_16x16x32_bf16 v[40:43], v[178:181], v[186:189], v[40:43]
	v_mfma_f32_16x16x32_bf16 v[52:55], v[144:147], v[190:193], v[52:55]
	v_mfma_f32_16x16x32_bf16 v[52:55], v[148:151], v[194:197], v[52:55]
	v_mfma_f32_16x16x32_bf16 v[48:51], v[152:155], v[190:193], v[48:51]
	v_mfma_f32_16x16x32_bf16 v[48:51], v[156:159], v[194:197], v[48:51]
	v_mfma_f32_16x16x32_bf16 v[28:31], v[160:163], v[190:193], v[28:31]
	v_mfma_f32_16x16x32_bf16 v[28:31], v[164:167], v[194:197], v[28:31]
	v_mfma_f32_16x16x32_bf16 v[24:27], v[170:173], v[190:193], v[24:27]
	v_mfma_f32_16x16x32_bf16 v[24:27], v[178:181], v[194:197], v[24:27]
	s_setprio 0
	s_setprio 1
	v_mfma_f32_16x16x32_bf16 v[36:39], v[144:147], v[198:201], v[36:39]
	v_mfma_f32_16x16x32_bf16 v[36:39], v[148:151], v[202:205], v[36:39]
	v_mfma_f32_16x16x32_bf16 v[32:35], v[152:155], v[198:201], v[32:35]
	v_mfma_f32_16x16x32_bf16 v[32:35], v[156:159], v[202:205], v[32:35]
	v_mfma_f32_16x16x32_bf16 v[12:15], v[160:163], v[198:201], v[12:15]
	v_mfma_f32_16x16x32_bf16 v[12:15], v[164:167], v[202:205], v[12:15]
	v_mfma_f32_16x16x32_bf16 v[8:11], v[170:173], v[198:201], v[8:11]
	v_mfma_f32_16x16x32_bf16 v[8:11], v[178:181], v[202:205], v[8:11]
	v_mfma_f32_16x16x32_bf16 v[20:23], v[144:147], v[206:209], v[20:23]
	v_mfma_f32_16x16x32_bf16 v[20:23], v[148:151], v[210:213], v[20:23]
	v_mfma_f32_16x16x32_bf16 v[16:19], v[152:155], v[206:209], v[16:19]
	v_mfma_f32_16x16x32_bf16 v[16:19], v[156:159], v[210:213], v[16:19]
	v_mfma_f32_16x16x32_bf16 v[4:7], v[160:163], v[206:209], v[4:7]
	v_mfma_f32_16x16x32_bf16 v[4:7], v[164:167], v[210:213], v[4:7]
	v_mfma_f32_16x16x32_bf16 v[0:3], v[170:173], v[206:209], v[0:3]
	v_mfma_f32_16x16x32_bf16 v[0:3], v[178:181], v[210:213], v[0:3]
	s_setprio 0
	s_barrier
	s_add_i32 s2, s2, 2
	s_add_u32 s86, s86, 0x100
	s_addc_u32 s87, s87, 0
	s_add_u32 s42, s42, 0x100
	s_addc_u32 s43, s43, 0
	s_cmp_gt_u32 s2, 29
	s_cbranch_scc0 .LBB0_514
	s_and_b64 vcc, exec, s[74:75]
	s_cbranch_vccz .LBB0_517
	s_barrier

; #define PG8_STAGE(bufoff, gbase, voff) do { _Pragma("unroll") for (int _i = 0; _i < 2; ++_i) \
;         __builtin_amdgcn_global_load_lds((const unsigned*)((const char*)(gbase) + (voff)[_i]), (PG8_LAS unsigned*)(lds + (bufoff) + ldsw + _i * 8192), 16, 0, 0); } while (0)
; #define PG8_LDA(dst, b, h) do { _Pragma("unroll") for (int m = 0; m < 4; ++m) _Pragma("unroll") for (int k = 0; k < 2; ++k) dst[m][k] = *(const PG8_LAS bf16x8*)(lds + PG8_SA(b, h) + aoff + m * 2048 + k * 1024); } while (0)
; #define PG8_LDB(dst, b, h) do { _Pragma("unroll") for (int n = 0; n < 2; ++n) _Pragma("unroll") for (int k = 0; k < 2; ++k) dst[n][k] = *(const PG8_LAS bf16x8*)(lds + PG8_SB(b, h) + boff + n * 2048 + k * 1024); } while (0)
; #define PG8_MMA(ai, bj, At, Bt) do { __builtin_amdgcn_s_setprio(1); _Pragma("unroll") for (int m = 0; m < 4; ++m) _Pragma("unroll") for (int n = 0; n < 2; ++n) _Pragma("unroll") for (int k = 0; k < 2; ++k) \
;         acc[ai][bj][m][n] = __builtin_amdgcn_mfma_f32_16x16x32_bf16(Bt[n][k], At[m][k], acc[ai][bj][m][n], 0, 0, 0); __builtin_amdgcn_s_setprio(0); } while (0)
; #define PG8_WAIT_V(n) asm volatile("s_waitcnt vmcnt(" #n ")" ::: "memory")
; #define PG8_WAIT_L(n) asm volatile("s_waitcnt lgkmcnt(" #n ")" ::: "memory")
; #define PG8_BAR __builtin_amdgcn_s_barrier()
; #define PG8_SCHED __builtin_amdgcn_sched_barrier(0)
;     ...
;             const bool last = (t == nt - 2);
;             const char* a1 = PG8_KADV(cA, (size_t)(t + 1) * kstep);
;             const char* a2 = last ? nA : PG8_KADV(cA, (size_t)(t + 2) * kstep); const char* b2 = last ? nB : PG8_KADV(cB, (size_t)(t + 2) * kstep);
;             const char* a3 = PG8_KADV(a2, kstep); const char* b3 = PG8_KADV(b2, kstep);
;             if (last && has_next) S.a_ready(nxt);
;             if constexpr (SP2) {
;             PG8_LDB(B0, 0, 0); PG8_LDB(B1, 0, 1); PG8_SCHED; PG8_LDA(At, 0, 0); PG8_STAGE(PG8_SA(1, 1), a1 + hstep, voffA);
;             PG8_WAIT_V(8); PG8_WAIT_L(0); PG8_BAR; PG8_MMA(0, 0, At, B0); PG8_MMA(0, 1, At, B1); PG8_BAR; PG8_SCHED;
;             PG8_LDA(At, 0, 1); PG8_STAGE(PG8_SB(0, 0), b2, voffB); PG8_STAGE(PG8_SB(0, 1), b2 + hstep, voffB); PG8_STAGE(PG8_SA(0, 0), a2, voffA);
.LBB0_541:
	s_add_u32 s3, s88, 0xfff80080
	s_addc_u32 s12, s89, -1
	s_add_i32 s13, 0, 0x10000
	s_cmp_eq_u32 s2, 28
	s_cselect_b32 s93, s15, s12
	s_cselect_b32 s92, s30, s3
	v_add_u32_e32 v140, s13, v142
	s_cselect_b32 s91, s33, s43
	s_cselect_b32 s90, s40, s42
	s_add_i32 s3, 0, 0x14000
	ds_read_b128 v[146:149], v140
	ds_read_b128 v[150:153], v140 offset:1024
	ds_read_b128 v[154:157], v140 offset:2048
	ds_read_b128 v[158:161], v140 offset:3072
	v_add_u32_e32 v140, s3, v142
	ds_read_b128 v[162:165], v140
	ds_read_b128 v[170:173], v140 offset:1024
	ds_read_b128 v[178:181], v140 offset:2048
	ds_read_b128 v[182:185], v140 offset:3072
	s_add_i32 m0, s21, 0xc000
	ds_read_b128 v[186:189], v145
	ds_read_b128 v[190:193], v145 offset:1024
	ds_read_b128 v[194:197], v145 offset:2048
	ds_read_b128 v[198:201], v145 offset:3072
	ds_read_b128 v[202:205], v145 offset:4096
	ds_read_b128 v[206:209], v145 offset:5120
	ds_read_b128 v[210:213], v145 offset:6144
	ds_read_b128 v[214:217], v145 offset:7168
	global_load_lds_dwordx4 v136, s[88:89]
	s_add_i32 m0, s21, 0xe000
	s_nop 0
	global_load_lds_dwordx4 v138, s[88:89]
	s_waitcnt vmcnt(8)
	s_waitcnt lgkmcnt(0)
	s_barrier
	s_setprio 1
	s_waitcnt lgkmcnt(0)
	v_mfma_f32_16x16x32_bf16 v[124:127], v[146:149], v[186:189], v[124:127]
	v_mfma_f32_16x16x32_bf16 v[124:127], v[150:153], v[190:193], v[124:127]
	v_mfma_f32_16x16x32_bf16 v[120:123], v[154:157], v[186:189], v[120:123]
	v_mfma_f32_16x16x32_bf16 v[120:123], v[158:161], v[190:193], v[120:123]
	v_mfma_f32_16x16x32_bf16 v[108:111], v[162:165], v[186:189], v[108:111]
	v_mfma_f32_16x16x32_bf16 v[108:111], v[170:173], v[190:193], v[108:111]
	v_mfma_f32_16x16x32_bf16 v[104:107], v[178:181], v[186:189], v[104:107]
	v_mfma_f32_16x16x32_bf16 v[104:107], v[182:185], v[190:193], v[104:107]
	v_mfma_f32_16x16x32_bf16 v[116:119], v[146:149], v[194:197], v[116:119]
	v_mfma_f32_16x16x32_bf16 v[116:119], v[150:153], v[198:201], v[116:119]
	v_mfma_f32_16x16x32_bf16 v[112:115], v[154:157], v[194:197], v[112:115]
	v_mfma_f32_16x16x32_bf16 v[112:115], v[158:161], v[198:201], v[112:115]
	v_mfma_f32_16x16x32_bf16 v[92:95], v[162:165], v[194:197], v[92:95]
	v_mfma_f32_16x16x32_bf16 v[92:95], v[170:173], v[198:201], v[92:95]
	v_mfma_f32_16x16x32_bf16 v[88:91], v[178:181], v[194:197], v[88:91]
	v_mfma_f32_16x16x32_bf16 v[88:91], v[182:185], v[198:201], v[88:91]
	s_setprio 0
	s_setprio 1
	v_mfma_f32_16x16x32_bf16 v[100:103], v[146:149], v[202:205], v[100:103]
	v_mfma_f32_16x16x32_bf16 v[100:103], v[150:153], v[206:209], v[100:103]
	v_mfma_f32_16x16x32_bf16 v[96:99], v[154:157], v[202:205], v[96:99]
	v_mfma_f32_16x16x32_bf16 v[96:99], v[158:161], v[206:209], v[96:99]
	v_mfma_f32_16x16x32_bf16 v[76:79], v[162:165], v[202:205], v[76:79]
	v_mfma_f32_16x16x32_bf16 v[76:79], v[170:173], v[206:209], v[76:79]
	v_mfma_f32_16x16x32_bf16 v[72:75], v[178:181], v[202:205], v[72:75]
	v_mfma_f32_16x16x32_bf16 v[72:75], v[182:185], v[206:209], v[72:75]
	v_mfma_f32_16x16x32_bf16 v[84:87], v[146:149], v[210:213], v[84:87]
	v_mfma_f32_16x16x32_bf16 v[84:87], v[150:153], v[214:217], v[84:87]
	v_mfma_f32_16x16x32_bf16 v[80:83], v[154:157], v[210:213], v[80:83]
	v_mfma_f32_16x16x32_bf16 v[80:83], v[158:161], v[214:217], v[80:83]
	v_mfma_f32_16x16x32_bf16 v[68:71], v[162:165], v[210:213], v[68:71]
	v_mfma_f32_16x16x32_bf16 v[68:71], v[170:173], v[214:217], v[68:71]
	v_mfma_f32_16x16x32_bf16 v[64:67], v[178:181], v[210:213], v[64:67]
	v_mfma_f32_16x16x32_bf16 v[64:67], v[182:185], v[214:217], v[64:67]
	s_setprio 0
	s_barrier
	s_add_i32 s12, s13, s20
	s_mov_b32 m0, s12
	ds_read_b128 v[186:189], v145 offset:16384
	ds_read_b128 v[190:193], v145 offset:17408
	ds_read_b128 v[194:197], v145 offset:18432
	ds_read_b128 v[198:201], v145 offset:19456
	ds_read_b128 v[202:205], v145 offset:20480
	ds_read_b128 v[206:209], v145 offset:21504
	ds_read_b128 v[210:213], v145 offset:22528
	ds_read_b128 v[214:217], v145 offset:23552
	global_load_lds_dwordx4 v132, s[90:91]
	s_add_i32 m0, s12, 0x2000
	s_add_u32 vcc_lo, s90, 0x80000
	v_lshl_add_u64 v[218:219], s[90:91], 0, v[128:129]
	s_addc_u32 vcc_hi, s91, 0
	s_add_i32 s3, s3, s20
	global_load_lds_dwordx4 v128, s[90:91]
	s_mov_b32 m0, s3
	v_lshl_add_u64 v[222:223], s[92:93], 0, v[130:131]
	global_load_lds_dwordx4 v132, vcc
	s_add_i32 m0, s3, 0x2000
	s_nop 0
	global_load_lds_dwordx4 v128, vcc
	v_lshl_add_u64 v[220:221], s[92:93], 0, v[134:135]
	s_mov_b32 m0, s21
	s_nop 0
	global_load_lds_dwordx4 v134, s[92:93]
	s_mov_b32 m0, s22
	s_nop 0
	global_load_lds_dwordx4 v130, s[92:93]
	s_waitcnt vmcnt(8)
	s_waitcnt lgkmcnt(0)
	s_barrier
; #define PG8_STAGE(bufoff, gbase, voff) do { _Pragma("unroll") for (int _i = 0; _i < 2; ++_i) \
;         __builtin_amdgcn_global_load_lds((const unsigned*)((const char*)(gbase) + (voff)[_i]), (PG8_LAS unsigned*)(lds + (bufoff) + ldsw + _i * 8192), 16, 0, 0); } while (0)
; #define PG8_LDA(dst, b, h) do { _Pragma("unroll") for (int m = 0; m < 4; ++m) _Pragma("unroll") for (int k = 0; k < 2; ++k) dst[m][k] = *(const PG8_LAS bf16x8*)(lds + PG8_SA(b, h) + aoff + m * 2048 + k * 1024); } while (0)
; #define PG8_LDB(dst, b, h) do { _Pragma("unroll") for (int n = 0; n < 2; ++n) _Pragma("unroll") for (int k = 0; k < 2; ++k) dst[n][k] = *(const PG8_LAS bf16x8*)(lds + PG8_SB(b, h) + boff + n * 2048 + k * 1024); } while (0)
; #define PG8_MMA(ai, bj, At, Bt) do { __builtin_amdgcn_s_setprio(1); _Pragma("unroll") for (int m = 0; m < 4; ++m) _Pragma("unroll") for (int n = 0; n < 2; ++n) _Pragma("unroll") for (int k = 0; k < 2; ++k) \
;         acc[ai][bj][m][n] = __builtin_amdgcn_mfma_f32_16x16x32_bf16(Bt[n][k], At[m][k], acc[ai][bj][m][n], 0, 0, 0); __builtin_amdgcn_s_setprio(0); } while (0)
; #define PG8_WAIT_V(n) asm volatile("s_waitcnt vmcnt(" #n ")" ::: "memory")
; #define PG8_WAIT_L(n) asm volatile("s_waitcnt lgkmcnt(" #n ")" ::: "memory")
; #define PG8_BAR __builtin_amdgcn_s_barrier()
; #define PG8_SCHED __builtin_amdgcn_sched_barrier(0)
;     ...
;             PG8_WAIT_V(8); PG8_WAIT_L(0); PG8_BAR; PG8_MMA(1, 0, At, B0); PG8_MMA(1, 1, At, B1); PG8_BAR; PG8_SCHED;
;             PG8_LDB(B0, 1, 0); PG8_LDB(B1, 1, 1); PG8_SCHED; PG8_LDA(At, 1, 0); PG8_STAGE(PG8_SA(0, 1), a2 + hstep, voffA);
;             PG8_WAIT_V(8); PG8_WAIT_L(0); PG8_BAR; PG8_MMA(0, 0, At, B0); PG8_MMA(0, 1, At, B1); PG8_BAR; PG8_SCHED;
	s_setprio 1
	s_waitcnt lgkmcnt(0)
	v_mfma_f32_16x16x32_bf16 v[60:63], v[146:149], v[186:189], v[60:63]
	v_mfma_f32_16x16x32_bf16 v[60:63], v[150:153], v[190:193], v[60:63]
	v_mfma_f32_16x16x32_bf16 v[56:59], v[154:157], v[186:189], v[56:59]
	v_mfma_f32_16x16x32_bf16 v[56:59], v[158:161], v[190:193], v[56:59]
	v_mfma_f32_16x16x32_bf16 v[44:47], v[162:165], v[186:189], v[44:47]
	v_mfma_f32_16x16x32_bf16 v[44:47], v[170:173], v[190:193], v[44:47]
	v_mfma_f32_16x16x32_bf16 v[40:43], v[178:181], v[186:189], v[40:43]
	v_mfma_f32_16x16x32_bf16 v[40:43], v[182:185], v[190:193], v[40:43]
	v_mfma_f32_16x16x32_bf16 v[52:55], v[146:149], v[194:197], v[52:55]
	v_mfma_f32_16x16x32_bf16 v[52:55], v[150:153], v[198:201], v[52:55]
	v_mfma_f32_16x16x32_bf16 v[48:51], v[154:157], v[194:197], v[48:51]
	v_mfma_f32_16x16x32_bf16 v[48:51], v[158:161], v[198:201], v[48:51]
	v_mfma_f32_16x16x32_bf16 v[28:31], v[162:165], v[194:197], v[28:31]
	v_mfma_f32_16x16x32_bf16 v[28:31], v[170:173], v[198:201], v[28:31]
	v_mfma_f32_16x16x32_bf16 v[24:27], v[178:181], v[194:197], v[24:27]
	v_mfma_f32_16x16x32_bf16 v[24:27], v[182:185], v[198:201], v[24:27]
	s_setprio 0
	s_setprio 1
	v_mfma_f32_16x16x32_bf16 v[36:39], v[146:149], v[202:205], v[36:39]
	v_mfma_f32_16x16x32_bf16 v[36:39], v[150:153], v[206:209], v[36:39]
	v_mfma_f32_16x16x32_bf16 v[32:35], v[154:157], v[202:205], v[32:35]
	v_mfma_f32_16x16x32_bf16 v[32:35], v[158:161], v[206:209], v[32:35]
	v_mfma_f32_16x16x32_bf16 v[12:15], v[162:165], v[202:205], v[12:15]
	v_mfma_f32_16x16x32_bf16 v[12:15], v[170:173], v[206:209], v[12:15]
	v_mfma_f32_16x16x32_bf16 v[8:11], v[178:181], v[202:205], v[8:11]
	v_mfma_f32_16x16x32_bf16 v[8:11], v[182:185], v[206:209], v[8:11]
	v_mfma_f32_16x16x32_bf16 v[20:23], v[146:149], v[210:213], v[20:23]
	v_mfma_f32_16x16x32_bf16 v[20:23], v[150:153], v[214:217], v[20:23]
	v_mfma_f32_16x16x32_bf16 v[16:19], v[154:157], v[210:213], v[16:19]
	v_mfma_f32_16x16x32_bf16 v[16:19], v[158:161], v[214:217], v[16:19]
	v_mfma_f32_16x16x32_bf16 v[4:7], v[162:165], v[210:213], v[4:7]
	v_mfma_f32_16x16x32_bf16 v[4:7], v[170:173], v[214:217], v[4:7]
	v_mfma_f32_16x16x32_bf16 v[0:3], v[178:181], v[210:213], v[0:3]
	v_mfma_f32_16x16x32_bf16 v[0:3], v[182:185], v[214:217], v[0:3]
	s_setprio 0
	s_barrier
	s_add_i32 s3, 0, 0x18000
	v_add_u32_e32 v140, s3, v142
	s_add_i32 s12, 0, 0x1c000
	ds_read_b128 v[146:149], v140
	ds_read_b128 v[150:153], v140 offset:1024
	ds_read_b128 v[154:157], v140 offset:2048
	ds_read_b128 v[158:161], v140 offset:3072
	v_add_u32_e32 v140, s12, v142
	ds_read_b128 v[162:165], v140
	ds_read_b128 v[170:173], v140 offset:1024
	ds_read_b128 v[178:181], v140 offset:2048
	ds_read_b128 v[182:185], v140 offset:3072
	s_add_u32 s92, s92, 0x80000
	s_addc_u32 s93, s93, 0
	s_mov_b32 m0, s23
	ds_read_b128 v[186:189], v145 offset:32768
	ds_read_b128 v[190:193], v145 offset:33792
	ds_read_b128 v[194:197], v145 offset:34816
	ds_read_b128 v[198:201], v145 offset:35840
	ds_read_b128 v[202:205], v145 offset:36864
	ds_read_b128 v[206:209], v145 offset:37888
	ds_read_b128 v[210:213], v145 offset:38912
	ds_read_b128 v[214:217], v145 offset:39936
	global_load_lds_dwordx4 v134, s[92:93]
	s_mov_b32 m0, s57
	s_nop 0
	global_load_lds_dwordx4 v130, s[92:93]
	s_waitcnt vmcnt(8)
	s_waitcnt lgkmcnt(0)
	s_barrier
	s_setprio 1
	s_waitcnt lgkmcnt(0)
	v_mfma_f32_16x16x32_bf16 v[124:127], v[146:149], v[186:189], v[124:127]
	v_mfma_f32_16x16x32_bf16 v[124:127], v[150:153], v[190:193], v[124:127]
	v_mfma_f32_16x16x32_bf16 v[120:123], v[154:157], v[186:189], v[120:123]
	v_mfma_f32_16x16x32_bf16 v[120:123], v[158:161], v[190:193], v[120:123]
	v_mfma_f32_16x16x32_bf16 v[108:111], v[162:165], v[186:189], v[108:111]
	v_mfma_f32_16x16x32_bf16 v[108:111], v[170:173], v[190:193], v[108:111]
	v_mfma_f32_16x16x32_bf16 v[104:107], v[178:181], v[186:189], v[104:107]
	v_mfma_f32_16x16x32_bf16 v[104:107], v[182:185], v[190:193], v[104:107]
	v_mfma_f32_16x16x32_bf16 v[116:119], v[146:149], v[194:197], v[116:119]
	v_mfma_f32_16x16x32_bf16 v[116:119], v[150:153], v[198:201], v[116:119]
	v_mfma_f32_16x16x32_bf16 v[112:115], v[154:157], v[194:197], v[112:115]
	v_mfma_f32_16x16x32_bf16 v[112:115], v[158:161], v[198:201], v[112:115]
	v_mfma_f32_16x16x32_bf16 v[92:95], v[162:165], v[194:197], v[92:95]
	v_mfma_f32_16x16x32_bf16 v[92:95], v[170:173], v[198:201], v[92:95]
	v_mfma_f32_16x16x32_bf16 v[88:91], v[178:181], v[194:197], v[88:91]
	v_mfma_f32_16x16x32_bf16 v[88:91], v[182:185], v[198:201], v[88:91]
	s_setprio 0
	s_setprio 1
	v_mfma_f32_16x16x32_bf16 v[100:103], v[146:149], v[202:205], v[100:103]
	v_mfma_f32_16x16x32_bf16 v[100:103], v[150:153], v[206:209], v[100:103]
	v_mfma_f32_16x16x32_bf16 v[96:99], v[154:157], v[202:205], v[96:99]
	v_mfma_f32_16x16x32_bf16 v[96:99], v[158:161], v[206:209], v[96:99]
	v_mfma_f32_16x16x32_bf16 v[76:79], v[162:165], v[202:205], v[76:79]
	v_mfma_f32_16x16x32_bf16 v[76:79], v[170:173], v[206:209], v[76:79]
	v_mfma_f32_16x16x32_bf16 v[72:75], v[178:181], v[202:205], v[72:75]
	v_mfma_f32_16x16x32_bf16 v[72:75], v[182:185], v[206:209], v[72:75]
	v_mfma_f32_16x16x32_bf16 v[84:87], v[146:149], v[210:213], v[84:87]
	v_mfma_f32_16x16x32_bf16 v[84:87], v[150:153], v[214:217], v[84:87]
	v_mfma_f32_16x16x32_bf16 v[80:83], v[154:157], v[210:213], v[80:83]
	v_mfma_f32_16x16x32_bf16 v[80:83], v[158:161], v[214:217], v[80:83]
	v_mfma_f32_16x16x32_bf16 v[68:71], v[162:165], v[210:213], v[68:71]
	v_mfma_f32_16x16x32_bf16 v[68:71], v[170:173], v[214:217], v[68:71]
	v_mfma_f32_16x16x32_bf16 v[64:67], v[178:181], v[210:213], v[64:67]
	v_mfma_f32_16x16x32_bf16 v[64:67], v[182:185], v[214:217], v[64:67]
	s_setprio 0
	s_barrier
; #define PG8_STAGE(bufoff, gbase, voff) do { _Pragma("unroll") for (int _i = 0; _i < 2; ++_i) \
;         __builtin_amdgcn_global_load_lds((const unsigned*)((const char*)(gbase) + (voff)[_i]), (PG8_LAS unsigned*)(lds + (bufoff) + ldsw + _i * 8192), 16, 0, 0); } while (0)
; #define PG8_LDA(dst, b, h) do { _Pragma("unroll") for (int m = 0; m < 4; ++m) _Pragma("unroll") for (int k = 0; k < 2; ++k) dst[m][k] = *(const PG8_LAS bf16x8*)(lds + PG8_SA(b, h) + aoff + m * 2048 + k * 1024); } while (0)
; #define PG8_MMA(ai, bj, At, Bt) do { __builtin_amdgcn_s_setprio(1); _Pragma("unroll") for (int m = 0; m < 4; ++m) _Pragma("unroll") for (int n = 0; n < 2; ++n) _Pragma("unroll") for (int k = 0; k < 2; ++k) \
;         acc[ai][bj][m][n] = __builtin_amdgcn_mfma_f32_16x16x32_bf16(Bt[n][k], At[m][k], acc[ai][bj][m][n], 0, 0, 0); __builtin_amdgcn_s_setprio(0); } while (0)
; #define PG8_WAIT_V(n) asm volatile("s_waitcnt vmcnt(" #n ")" ::: "memory")
; #define PG8_WAIT_L(n) asm volatile("s_waitcnt lgkmcnt(" #n ")" ::: "memory")
; #define PG8_BAR __builtin_amdgcn_s_barrier()
; #define PG8_SCHED __builtin_amdgcn_sched_barrier(0)
;     ...
;             PG8_LDA(At, 1, 1); PG8_STAGE(PG8_SB(1, 0), b3, voffB); PG8_STAGE(PG8_SB(1, 1), b3 + hstep, voffB); PG8_STAGE(PG8_SA(1, 0), a3, voffA);
;             PG8_WAIT_V(8); PG8_WAIT_L(0); PG8_BAR; PG8_MMA(1, 0, At, B0); PG8_MMA(1, 1, At, B1); PG8_BAR; PG8_SCHED;
	s_add_i32 s3, s3, s20
	s_mov_b32 m0, s3
	ds_read_b128 v[186:189], v145 offset:49152
	ds_read_b128 v[190:193], v145 offset:50176
	ds_read_b128 v[194:197], v145 offset:51200
	ds_read_b128 v[198:201], v145 offset:52224
	ds_read_b128 v[202:205], v145 offset:53248
	ds_read_b128 v[206:209], v145 offset:54272
	ds_read_b128 v[210:213], v145 offset:55296
	ds_read_b128 v[214:217], v145 offset:56320
	s_add_u32 s100, s90, s16
	s_addc_u32 s101, s91, s17
	global_load_lds_dwordx4 v132, s[100:101]
	s_add_i32 m0, s3, 0x2000
	s_add_u32 s90, s90, 0x80080
	v_lshl_add_u64 v[166:167], v[218:219], 0, s[16:17]
	s_addc_u32 s91, s91, 0
	s_add_i32 s3, s12, s20
	global_load_lds_dwordx4 v[166:167], off
	s_mov_b32 m0, s3
	s_nop 0
	global_load_lds_dwordx4 v132, s[90:91]
	s_add_i32 m0, s3, 0x2000
	s_nop 0
	global_load_lds_dwordx4 v128, s[90:91]
	v_lshl_add_u64 v[166:167], v[220:221], 0, s[16:17]
	s_mov_b32 m0, s59
	s_nop 0
	global_load_lds_dwordx4 v[166:167], off
	v_lshl_add_u64 v[166:167], v[222:223], 0, s[16:17]
	s_mov_b32 m0, s8
	s_nop 0
	global_load_lds_dwordx4 v[166:167], off
	s_waitcnt vmcnt(8)
	s_waitcnt lgkmcnt(0)
	s_barrier
	s_setprio 1
	s_waitcnt lgkmcnt(0)
	v_mfma_f32_16x16x32_bf16 v[60:63], v[146:149], v[186:189], v[60:63]
	v_mfma_f32_16x16x32_bf16 v[60:63], v[150:153], v[190:193], v[60:63]
	v_mfma_f32_16x16x32_bf16 v[56:59], v[154:157], v[186:189], v[56:59]
	v_mfma_f32_16x16x32_bf16 v[56:59], v[158:161], v[190:193], v[56:59]
	v_mfma_f32_16x16x32_bf16 v[44:47], v[162:165], v[186:189], v[44:47]
	v_mfma_f32_16x16x32_bf16 v[44:47], v[170:173], v[190:193], v[44:47]
	v_mfma_f32_16x16x32_bf16 v[40:43], v[178:181], v[186:189], v[40:43]
	v_mfma_f32_16x16x32_bf16 v[40:43], v[182:185], v[190:193], v[40:43]
	v_mfma_f32_16x16x32_bf16 v[52:55], v[146:149], v[194:197], v[52:55]
	v_mfma_f32_16x16x32_bf16 v[52:55], v[150:153], v[198:201], v[52:55]
	v_mfma_f32_16x16x32_bf16 v[48:51], v[154:157], v[194:197], v[48:51]
	v_mfma_f32_16x16x32_bf16 v[48:51], v[158:161], v[198:201], v[48:51]
	v_mfma_f32_16x16x32_bf16 v[28:31], v[162:165], v[194:197], v[28:31]
	v_mfma_f32_16x16x32_bf16 v[28:31], v[170:173], v[198:201], v[28:31]
	v_mfma_f32_16x16x32_bf16 v[24:27], v[178:181], v[194:197], v[24:27]
	v_mfma_f32_16x16x32_bf16 v[24:27], v[182:185], v[198:201], v[24:27]
	s_setprio 0
	s_setprio 1
	v_mfma_f32_16x16x32_bf16 v[36:39], v[146:149], v[202:205], v[36:39]
	v_mfma_f32_16x16x32_bf16 v[36:39], v[150:153], v[206:209], v[36:39]
	v_mfma_f32_16x16x32_bf16 v[32:35], v[154:157], v[202:205], v[32:35]
	v_mfma_f32_16x16x32_bf16 v[32:35], v[158:161], v[206:209], v[32:35]
	v_mfma_f32_16x16x32_bf16 v[12:15], v[162:165], v[202:205], v[12:15]
	v_mfma_f32_16x16x32_bf16 v[12:15], v[170:173], v[206:209], v[12:15]
	v_mfma_f32_16x16x32_bf16 v[8:11], v[178:181], v[202:205], v[8:11]
	v_mfma_f32_16x16x32_bf16 v[8:11], v[182:185], v[206:209], v[8:11]
	v_mfma_f32_16x16x32_bf16 v[20:23], v[146:149], v[210:213], v[20:23]
	v_mfma_f32_16x16x32_bf16 v[20:23], v[150:153], v[214:217], v[20:23]
	v_mfma_f32_16x16x32_bf16 v[16:19], v[154:157], v[210:213], v[16:19]
	v_mfma_f32_16x16x32_bf16 v[16:19], v[158:161], v[214:217], v[16:19]
	v_mfma_f32_16x16x32_bf16 v[4:7], v[162:165], v[210:213], v[4:7]
	v_mfma_f32_16x16x32_bf16 v[4:7], v[170:173], v[214:217], v[4:7]
	v_mfma_f32_16x16x32_bf16 v[0:3], v[178:181], v[210:213], v[0:3]
	v_mfma_f32_16x16x32_bf16 v[0:3], v[182:185], v[214:217], v[0:3]
	s_setprio 0
	s_barrier
	s_add_i32 s2, s2, 2
	s_add_u32 s88, s88, 0x100
	s_addc_u32 s89, s89, 0
	s_add_u32 s42, s42, 0x100
	s_addc_u32 s43, s43, 0
	s_cmp_gt_u32 s2, 29
	s_cbranch_scc0 .LBB0_541
	s_and_b64 vcc, exec, s[76:77]
	s_cbranch_vccz .LBB0_544
	s_barrier

; #define PG8_STAGE(bufoff, gbase, voff) do { _Pragma("unroll") for (int _i = 0; _i < 2; ++_i) \
;         __builtin_amdgcn_global_load_lds((const unsigned*)((const char*)(gbase) + (voff)[_i]), (PG8_LAS unsigned*)(lds + (bufoff) + ldsw + _i * 8192), 16, 0, 0); } while (0)
; #define PG8_LDA(dst, b, h) do { _Pragma("unroll") for (int m = 0; m < 4; ++m) _Pragma("unroll") for (int k = 0; k < 2; ++k) dst[m][k] = *(const PG8_LAS bf16x8*)(lds + PG8_SA(b, h) + aoff + m * 2048 + k * 1024); } while (0)
; #define PG8_LDB(dst, b, h) do { _Pragma("unroll") for (int n = 0; n < 2; ++n) _Pragma("unroll") for (int k = 0; k < 2; ++k) dst[n][k] = *(const PG8_LAS bf16x8*)(lds + PG8_SB(b, h) + boff + n * 2048 + k * 1024); } while (0)
; #define PG8_MMA(ai, bj, At, Bt) do { __builtin_amdgcn_s_setprio(1); _Pragma("unroll") for (int m = 0; m < 4; ++m) _Pragma("unroll") for (int n = 0; n < 2; ++n) _Pragma("unroll") for (int k = 0; k < 2; ++k) \
;         acc[ai][bj][m][n] = __builtin_amdgcn_mfma_f32_16x16x32_bf16(Bt[n][k], At[m][k], acc[ai][bj][m][n], 0, 0, 0); __builtin_amdgcn_s_setprio(0); } while (0)
; #define PG8_WAIT_V(n) asm volatile("s_waitcnt vmcnt(" #n ")" ::: "memory")
; #define PG8_WAIT_L(n) asm volatile("s_waitcnt lgkmcnt(" #n ")" ::: "memory")
; #define PG8_BAR __builtin_amdgcn_s_barrier()
; #define PG8_SCHED __builtin_amdgcn_sched_barrier(0)
;     ...
;             const bool last = (t == nt - 2);
;             const char* a1 = PG8_KADV(cA, (size_t)(t + 1) * kstep);
;             const char* a2 = last ? nA : PG8_KADV(cA, (size_t)(t + 2) * kstep); const char* b2 = last ? nB : PG8_KADV(cB, (size_t)(t + 2) * kstep);
;             const char* a3 = PG8_KADV(a2, kstep); const char* b3 = PG8_KADV(b2, kstep);
;             if (last && has_next) S.a_ready(nxt);
;             if constexpr (SP2) {
;             PG8_LDB(B0, 0, 0); PG8_LDB(B1, 0, 1); PG8_SCHED; PG8_LDA(At, 0, 0); PG8_STAGE(PG8_SA(1, 1), a1 + hstep, voffA);
;             PG8_WAIT_V(8); PG8_WAIT_L(0); PG8_BAR; PG8_MMA(0, 0, At, B0); PG8_MMA(0, 1, At, B1); PG8_BAR; PG8_SCHED;
;             PG8_LDA(At, 0, 1); PG8_STAGE(PG8_SB(0, 0), b2, voffB); PG8_STAGE(PG8_SB(0, 1), b2 + hstep, voffB); PG8_STAGE(PG8_SA(0, 0), a2, voffA);
;             PG8_WAIT_V(8); PG8_WAIT_L(0); PG8_BAR; PG8_MMA(1, 0, At, B0); PG8_MMA(1, 1, At, B1); PG8_BAR; PG8_SCHED;
.LBB0_626:
	s_add_u32 s12, s86, 0xfffc0080
	s_addc_u32 s13, s87, -1
	s_add_i32 s96, 0, 0x10000
	s_cmp_eq_u32 s3, 12
	s_cselect_b32 s91, s75, s13
	s_cselect_b32 s90, s81, s12
	v_add_u32_e32 v143, s96, v140
	s_cselect_b32 s89, s79, s2
	s_cselect_b32 s88, vcc_lo, vcc_hi
	s_add_i32 s31, 0, 0x14000
	ds_read_b128 v[144:147], v143
	ds_read_b128 v[148:151], v143 offset:1024
	ds_read_b128 v[152:155], v143 offset:2048
	ds_read_b128 v[156:159], v143 offset:3072
	v_add_u32_e32 v143, s31, v140
	ds_read_b128 v[160:163], v143
	ds_read_b128 v[164:167], v143 offset:1024
	ds_read_b128 v[170:173], v143 offset:2048
	ds_read_b128 v[178:181], v143 offset:3072
	s_add_i32 m0, s97, 0xc000
	ds_read_b128 v[182:185], v142
	ds_read_b128 v[186:189], v142 offset:1024
	ds_read_b128 v[190:193], v142 offset:2048
	ds_read_b128 v[194:197], v142 offset:3072
	ds_read_b128 v[198:201], v142 offset:4096
	ds_read_b128 v[202:205], v142 offset:5120
	ds_read_b128 v[206:209], v142 offset:6144
	ds_read_b128 v[210:213], v142 offset:7168
	global_load_lds_dwordx4 v136, s[86:87]
	s_add_i32 m0, s97, 0xe000
	s_nop 0
	global_load_lds_dwordx4 v138, s[86:87]
	s_waitcnt vmcnt(8)
	s_waitcnt lgkmcnt(0)
	s_barrier
	s_setprio 1
	s_waitcnt lgkmcnt(0)
	v_mfma_f32_16x16x32_bf16 v[124:127], v[144:147], v[182:185], v[124:127]
	v_mfma_f32_16x16x32_bf16 v[124:127], v[148:151], v[186:189], v[124:127]
	v_mfma_f32_16x16x32_bf16 v[120:123], v[152:155], v[182:185], v[120:123]
	v_mfma_f32_16x16x32_bf16 v[120:123], v[156:159], v[186:189], v[120:123]
	v_mfma_f32_16x16x32_bf16 v[108:111], v[160:163], v[182:185], v[108:111]
	v_mfma_f32_16x16x32_bf16 v[108:111], v[164:167], v[186:189], v[108:111]
	v_mfma_f32_16x16x32_bf16 v[104:107], v[170:173], v[182:185], v[104:107]
	v_mfma_f32_16x16x32_bf16 v[104:107], v[178:181], v[186:189], v[104:107]
	v_mfma_f32_16x16x32_bf16 v[116:119], v[144:147], v[190:193], v[116:119]
	v_mfma_f32_16x16x32_bf16 v[116:119], v[148:151], v[194:197], v[116:119]
	v_mfma_f32_16x16x32_bf16 v[112:115], v[152:155], v[190:193], v[112:115]
	v_mfma_f32_16x16x32_bf16 v[112:115], v[156:159], v[194:197], v[112:115]
	v_mfma_f32_16x16x32_bf16 v[92:95], v[160:163], v[190:193], v[92:95]
	v_mfma_f32_16x16x32_bf16 v[92:95], v[164:167], v[194:197], v[92:95]
	v_mfma_f32_16x16x32_bf16 v[88:91], v[170:173], v[190:193], v[88:91]
	v_mfma_f32_16x16x32_bf16 v[88:91], v[178:181], v[194:197], v[88:91]
	s_setprio 0
	s_setprio 1
	v_mfma_f32_16x16x32_bf16 v[100:103], v[144:147], v[198:201], v[100:103]
	v_mfma_f32_16x16x32_bf16 v[100:103], v[148:151], v[202:205], v[100:103]
	v_mfma_f32_16x16x32_bf16 v[96:99], v[152:155], v[198:201], v[96:99]
	v_mfma_f32_16x16x32_bf16 v[96:99], v[156:159], v[202:205], v[96:99]
	v_mfma_f32_16x16x32_bf16 v[76:79], v[160:163], v[198:201], v[76:79]
	v_mfma_f32_16x16x32_bf16 v[76:79], v[164:167], v[202:205], v[76:79]
	v_mfma_f32_16x16x32_bf16 v[72:75], v[170:173], v[198:201], v[72:75]
	v_mfma_f32_16x16x32_bf16 v[72:75], v[178:181], v[202:205], v[72:75]
	v_mfma_f32_16x16x32_bf16 v[84:87], v[144:147], v[206:209], v[84:87]
	v_mfma_f32_16x16x32_bf16 v[84:87], v[148:151], v[210:213], v[84:87]
	v_mfma_f32_16x16x32_bf16 v[80:83], v[152:155], v[206:209], v[80:83]
	v_mfma_f32_16x16x32_bf16 v[80:83], v[156:159], v[210:213], v[80:83]
	v_mfma_f32_16x16x32_bf16 v[68:71], v[160:163], v[206:209], v[68:71]
	v_mfma_f32_16x16x32_bf16 v[68:71], v[164:167], v[210:213], v[68:71]
	v_mfma_f32_16x16x32_bf16 v[64:67], v[170:173], v[206:209], v[64:67]
	v_mfma_f32_16x16x32_bf16 v[64:67], v[178:181], v[210:213], v[64:67]
	s_setprio 0
	s_barrier
	s_add_i32 s12, s96, s93
	s_mov_b32 m0, s12
	ds_read_b128 v[182:185], v142 offset:16384
	ds_read_b128 v[186:189], v142 offset:17408
	ds_read_b128 v[190:193], v142 offset:18432
	ds_read_b128 v[194:197], v142 offset:19456
	ds_read_b128 v[198:201], v142 offset:20480
	ds_read_b128 v[202:205], v142 offset:21504
	ds_read_b128 v[206:209], v142 offset:22528
	ds_read_b128 v[210:213], v142 offset:23552
	global_load_lds_dwordx4 v130, s[88:89]
	s_add_i32 m0, s12, 0x2000
	s_add_u32 s12, s88, 0x40000
	s_addc_u32 s13, s89, 0
	s_add_i32 s31, s31, s93
	global_load_lds_dwordx4 v134, s[88:89]
	s_mov_b32 m0, s31
	s_nop 0
	global_load_lds_dwordx4 v130, s[12:13]
	s_add_i32 m0, s31, 0x2000
	s_nop 0
	global_load_lds_dwordx4 v134, s[12:13]
	s_mov_b32 m0, s97
	s_nop 0
	global_load_lds_dwordx4 v128, s[90:91]
	s_mov_b32 m0, s40
	s_nop 0
	global_load_lds_dwordx4 v132, s[90:91]
	s_waitcnt vmcnt(8)
	s_waitcnt lgkmcnt(0)
	s_barrier
	s_setprio 1
	s_waitcnt lgkmcnt(0)
	v_mfma_f32_16x16x32_bf16 v[60:63], v[144:147], v[182:185], v[60:63]
	v_mfma_f32_16x16x32_bf16 v[60:63], v[148:151], v[186:189], v[60:63]
	v_mfma_f32_16x16x32_bf16 v[56:59], v[152:155], v[182:185], v[56:59]
	v_mfma_f32_16x16x32_bf16 v[56:59], v[156:159], v[186:189], v[56:59]
	v_mfma_f32_16x16x32_bf16 v[44:47], v[160:163], v[182:185], v[44:47]
	v_mfma_f32_16x16x32_bf16 v[44:47], v[164:167], v[186:189], v[44:47]
	v_mfma_f32_16x16x32_bf16 v[40:43], v[170:173], v[182:185], v[40:43]
	v_mfma_f32_16x16x32_bf16 v[40:43], v[178:181], v[186:189], v[40:43]
	v_mfma_f32_16x16x32_bf16 v[52:55], v[144:147], v[190:193], v[52:55]
	v_mfma_f32_16x16x32_bf16 v[52:55], v[148:151], v[194:197], v[52:55]
	v_mfma_f32_16x16x32_bf16 v[48:51], v[152:155], v[190:193], v[48:51]
	v_mfma_f32_16x16x32_bf16 v[48:51], v[156:159], v[194:197], v[48:51]
	v_mfma_f32_16x16x32_bf16 v[28:31], v[160:163], v[190:193], v[28:31]
	v_mfma_f32_16x16x32_bf16 v[28:31], v[164:167], v[194:197], v[28:31]
	v_mfma_f32_16x16x32_bf16 v[24:27], v[170:173], v[190:193], v[24:27]
	v_mfma_f32_16x16x32_bf16 v[24:27], v[178:181], v[194:197], v[24:27]
	s_setprio 0
	s_setprio 1
	v_mfma_f32_16x16x32_bf16 v[36:39], v[144:147], v[198:201], v[36:39]
	v_mfma_f32_16x16x32_bf16 v[36:39], v[148:151], v[202:205], v[36:39]
	v_mfma_f32_16x16x32_bf16 v[32:35], v[152:155], v[198:201], v[32:35]
	v_mfma_f32_16x16x32_bf16 v[32:35], v[156:159], v[202:205], v[32:35]
	v_mfma_f32_16x16x32_bf16 v[12:15], v[160:163], v[198:201], v[12:15]
	v_mfma_f32_16x16x32_bf16 v[12:15], v[164:167], v[202:205], v[12:15]
	v_mfma_f32_16x16x32_bf16 v[8:11], v[170:173], v[198:201], v[8:11]
	v_mfma_f32_16x16x32_bf16 v[8:11], v[178:181], v[202:205], v[8:11]
	v_mfma_f32_16x16x32_bf16 v[20:23], v[144:147], v[206:209], v[20:23]
	v_mfma_f32_16x16x32_bf16 v[20:23], v[148:151], v[210:213], v[20:23]
	v_mfma_f32_16x16x32_bf16 v[16:19], v[152:155], v[206:209], v[16:19]
	v_mfma_f32_16x16x32_bf16 v[16:19], v[156:159], v[210:213], v[16:19]
	v_mfma_f32_16x16x32_bf16 v[4:7], v[160:163], v[206:209], v[4:7]
	v_mfma_f32_16x16x32_bf16 v[4:7], v[164:167], v[210:213], v[4:7]
	v_mfma_f32_16x16x32_bf16 v[0:3], v[170:173], v[206:209], v[0:3]
	v_mfma_f32_16x16x32_bf16 v[0:3], v[178:181], v[210:213], v[0:3]
	s_setprio 0
	s_barrier
; #define PG8_STAGE(bufoff, gbase, voff) do { _Pragma("unroll") for (int _i = 0; _i < 2; ++_i) \
;         __builtin_amdgcn_global_load_lds((const unsigned*)((const char*)(gbase) + (voff)[_i]), (PG8_LAS unsigned*)(lds + (bufoff) + ldsw + _i * 8192), 16, 0, 0); } while (0)
; #define PG8_LDA(dst, b, h) do { _Pragma("unroll") for (int m = 0; m < 4; ++m) _Pragma("unroll") for (int k = 0; k < 2; ++k) dst[m][k] = *(const PG8_LAS bf16x8*)(lds + PG8_SA(b, h) + aoff + m * 2048 + k * 1024); } while (0)
; #define PG8_LDB(dst, b, h) do { _Pragma("unroll") for (int n = 0; n < 2; ++n) _Pragma("unroll") for (int k = 0; k < 2; ++k) dst[n][k] = *(const PG8_LAS bf16x8*)(lds + PG8_SB(b, h) + boff + n * 2048 + k * 1024); } while (0)
; #define PG8_MMA(ai, bj, At, Bt) do { __builtin_amdgcn_s_setprio(1); _Pragma("unroll") for (int m = 0; m < 4; ++m) _Pragma("unroll") for (int n = 0; n < 2; ++n) _Pragma("unroll") for (int k = 0; k < 2; ++k) \
;         acc[ai][bj][m][n] = __builtin_amdgcn_mfma_f32_16x16x32_bf16(Bt[n][k], At[m][k], acc[ai][bj][m][n], 0, 0, 0); __builtin_amdgcn_s_setprio(0); } while (0)
; #define PG8_WAIT_V(n) asm volatile("s_waitcnt vmcnt(" #n ")" ::: "memory")
; #define PG8_WAIT_L(n) asm volatile("s_waitcnt lgkmcnt(" #n ")" ::: "memory")
; #define PG8_BAR __builtin_amdgcn_s_barrier()
; #define PG8_SCHED __builtin_amdgcn_sched_barrier(0)
;     ...
;             PG8_LDB(B0, 1, 0); PG8_LDB(B1, 1, 1); PG8_SCHED; PG8_LDA(At, 1, 0); PG8_STAGE(PG8_SA(0, 1), a2 + hstep, voffA);
;             PG8_WAIT_V(8); PG8_WAIT_L(0); PG8_BAR; PG8_MMA(0, 0, At, B0); PG8_MMA(0, 1, At, B1); PG8_BAR; PG8_SCHED;
;             PG8_LDA(At, 1, 1); PG8_STAGE(PG8_SB(1, 0), b3, voffB); PG8_STAGE(PG8_SB(1, 1), b3 + hstep, voffB); PG8_STAGE(PG8_SA(1, 0), a3, voffA);
;             PG8_WAIT_V(8); PG8_WAIT_L(0); PG8_BAR; PG8_MMA(1, 0, At, B0); PG8_MMA(1, 1, At, B1); PG8_BAR; PG8_SCHED;
	s_add_i32 s31, 0, 0x18000
	v_add_u32_e32 v143, s31, v140
	s_add_i32 s96, 0, 0x1c000
	ds_read_b128 v[144:147], v143
	ds_read_b128 v[148:151], v143 offset:1024
	ds_read_b128 v[152:155], v143 offset:2048
	ds_read_b128 v[156:159], v143 offset:3072
	v_add_u32_e32 v143, s96, v140
	ds_read_b128 v[160:163], v143
	ds_read_b128 v[164:167], v143 offset:1024
	ds_read_b128 v[170:173], v143 offset:2048
	ds_read_b128 v[178:181], v143 offset:3072
	s_add_u32 s12, s90, 0x40000
	s_addc_u32 s13, s91, 0
	s_mov_b32 m0, s33
	ds_read_b128 v[182:185], v142 offset:32768
	ds_read_b128 v[186:189], v142 offset:33792
	ds_read_b128 v[190:193], v142 offset:34816
	ds_read_b128 v[194:197], v142 offset:35840
	ds_read_b128 v[198:201], v142 offset:36864
	ds_read_b128 v[202:205], v142 offset:37888
	ds_read_b128 v[206:209], v142 offset:38912
	ds_read_b128 v[210:213], v142 offset:39936
	global_load_lds_dwordx4 v128, s[12:13]
	s_mov_b32 m0, s30
	s_nop 0
	global_load_lds_dwordx4 v132, s[12:13]
	s_waitcnt vmcnt(8)
	s_waitcnt lgkmcnt(0)
	s_barrier
	s_setprio 1
	s_waitcnt lgkmcnt(0)
	v_mfma_f32_16x16x32_bf16 v[124:127], v[144:147], v[182:185], v[124:127]
	v_mfma_f32_16x16x32_bf16 v[124:127], v[148:151], v[186:189], v[124:127]
	v_mfma_f32_16x16x32_bf16 v[120:123], v[152:155], v[182:185], v[120:123]
	v_mfma_f32_16x16x32_bf16 v[120:123], v[156:159], v[186:189], v[120:123]
	v_mfma_f32_16x16x32_bf16 v[108:111], v[160:163], v[182:185], v[108:111]
	v_mfma_f32_16x16x32_bf16 v[108:111], v[164:167], v[186:189], v[108:111]
	v_mfma_f32_16x16x32_bf16 v[104:107], v[170:173], v[182:185], v[104:107]
	v_mfma_f32_16x16x32_bf16 v[104:107], v[178:181], v[186:189], v[104:107]
	v_mfma_f32_16x16x32_bf16 v[116:119], v[144:147], v[190:193], v[116:119]
	v_mfma_f32_16x16x32_bf16 v[116:119], v[148:151], v[194:197], v[116:119]
	v_mfma_f32_16x16x32_bf16 v[112:115], v[152:155], v[190:193], v[112:115]
	v_mfma_f32_16x16x32_bf16 v[112:115], v[156:159], v[194:197], v[112:115]
	v_mfma_f32_16x16x32_bf16 v[92:95], v[160:163], v[190:193], v[92:95]
	v_mfma_f32_16x16x32_bf16 v[92:95], v[164:167], v[194:197], v[92:95]
	v_mfma_f32_16x16x32_bf16 v[88:91], v[170:173], v[190:193], v[88:91]
	v_mfma_f32_16x16x32_bf16 v[88:91], v[178:181], v[194:197], v[88:91]
	s_setprio 0
	s_setprio 1
	v_mfma_f32_16x16x32_bf16 v[100:103], v[144:147], v[198:201], v[100:103]
	v_mfma_f32_16x16x32_bf16 v[100:103], v[148:151], v[202:205], v[100:103]
	v_mfma_f32_16x16x32_bf16 v[96:99], v[152:155], v[198:201], v[96:99]
	v_mfma_f32_16x16x32_bf16 v[96:99], v[156:159], v[202:205], v[96:99]
	v_mfma_f32_16x16x32_bf16 v[76:79], v[160:163], v[198:201], v[76:79]
	v_mfma_f32_16x16x32_bf16 v[76:79], v[164:167], v[202:205], v[76:79]
	v_mfma_f32_16x16x32_bf16 v[72:75], v[170:173], v[198:201], v[72:75]
	v_mfma_f32_16x16x32_bf16 v[72:75], v[178:181], v[202:205], v[72:75]
	v_mfma_f32_16x16x32_bf16 v[84:87], v[144:147], v[206:209], v[84:87]
	v_mfma_f32_16x16x32_bf16 v[84:87], v[148:151], v[210:213], v[84:87]
	v_mfma_f32_16x16x32_bf16 v[80:83], v[152:155], v[206:209], v[80:83]
	v_mfma_f32_16x16x32_bf16 v[80:83], v[156:159], v[210:213], v[80:83]
	v_mfma_f32_16x16x32_bf16 v[68:71], v[160:163], v[206:209], v[68:71]
	v_mfma_f32_16x16x32_bf16 v[68:71], v[164:167], v[210:213], v[68:71]
	v_mfma_f32_16x16x32_bf16 v[64:67], v[170:173], v[206:209], v[64:67]
	v_mfma_f32_16x16x32_bf16 v[64:67], v[178:181], v[210:213], v[64:67]
	s_setprio 0
	s_barrier
	s_add_i32 s12, s31, s93
	s_mov_b32 m0, s12
	ds_read_b128 v[182:185], v142 offset:49152
	ds_read_b128 v[186:189], v142 offset:50176
	ds_read_b128 v[190:193], v142 offset:51200
	ds_read_b128 v[194:197], v142 offset:52224
	ds_read_b128 v[198:201], v142 offset:53248
	ds_read_b128 v[202:205], v142 offset:54272
	ds_read_b128 v[206:209], v142 offset:55296
	ds_read_b128 v[210:213], v142 offset:56320
	s_add_u32 s100, s88, s16
	s_addc_u32 s101, s89, s17
	global_load_lds_dwordx4 v130, s[100:101]
	s_add_i32 m0, s12, 0x2000
	s_add_u32 s12, s88, 0x40080
	s_addc_u32 s13, s89, 0
	s_add_i32 s31, s96, s93
	global_load_lds_dwordx4 v134, s[100:101]
	s_mov_b32 m0, s31
	s_nop 0
	global_load_lds_dwordx4 v130, s[12:13]
	s_add_i32 m0, s31, 0x2000
	s_nop 0
	global_load_lds_dwordx4 v134, s[12:13]
	s_mov_b32 m0, s14
	s_nop 0
	s_add_u32 s100, s90, s16
	s_addc_u32 s101, s91, s17
	global_load_lds_dwordx4 v128, s[100:101]
	s_mov_b32 m0, s15
	s_nop 0
	global_load_lds_dwordx4 v132, s[100:101]
	s_waitcnt vmcnt(8)
	s_waitcnt lgkmcnt(0)
	s_barrier
	s_setprio 1
	s_waitcnt lgkmcnt(0)
	v_mfma_f32_16x16x32_bf16 v[60:63], v[144:147], v[182:185], v[60:63]
	v_mfma_f32_16x16x32_bf16 v[60:63], v[148:151], v[186:189], v[60:63]
	v_mfma_f32_16x16x32_bf16 v[56:59], v[152:155], v[182:185], v[56:59]
	v_mfma_f32_16x16x32_bf16 v[56:59], v[156:159], v[186:189], v[56:59]
	v_mfma_f32_16x16x32_bf16 v[44:47], v[160:163], v[182:185], v[44:47]
	v_mfma_f32_16x16x32_bf16 v[44:47], v[164:167], v[186:189], v[44:47]
	v_mfma_f32_16x16x32_bf16 v[40:43], v[170:173], v[182:185], v[40:43]
	v_mfma_f32_16x16x32_bf16 v[40:43], v[178:181], v[186:189], v[40:43]
	v_mfma_f32_16x16x32_bf16 v[52:55], v[144:147], v[190:193], v[52:55]
	v_mfma_f32_16x16x32_bf16 v[52:55], v[148:151], v[194:197], v[52:55]
	v_mfma_f32_16x16x32_bf16 v[48:51], v[152:155], v[190:193], v[48:51]
	v_mfma_f32_16x16x32_bf16 v[48:51], v[156:159], v[194:197], v[48:51]
	v_mfma_f32_16x16x32_bf16 v[28:31], v[160:163], v[190:193], v[28:31]
	v_mfma_f32_16x16x32_bf16 v[28:31], v[164:167], v[194:197], v[28:31]
	v_mfma_f32_16x16x32_bf16 v[24:27], v[170:173], v[190:193], v[24:27]
	v_mfma_f32_16x16x32_bf16 v[24:27], v[178:181], v[194:197], v[24:27]
	s_setprio 0
	s_setprio 1
	v_mfma_f32_16x16x32_bf16 v[36:39], v[144:147], v[198:201], v[36:39]
	v_mfma_f32_16x16x32_bf16 v[36:39], v[148:151], v[202:205], v[36:39]
	v_mfma_f32_16x16x32_bf16 v[32:35], v[152:155], v[198:201], v[32:35]
	v_mfma_f32_16x16x32_bf16 v[32:35], v[156:159], v[202:205], v[32:35]
	v_mfma_f32_16x16x32_bf16 v[12:15], v[160:163], v[198:201], v[12:15]
	v_mfma_f32_16x16x32_bf16 v[12:15], v[164:167], v[202:205], v[12:15]
	v_mfma_f32_16x16x32_bf16 v[8:11], v[170:173], v[198:201], v[8:11]
	v_mfma_f32_16x16x32_bf16 v[8:11], v[178:181], v[202:205], v[8:11]
	v_mfma_f32_16x16x32_bf16 v[20:23], v[144:147], v[206:209], v[20:23]
	v_mfma_f32_16x16x32_bf16 v[20:23], v[148:151], v[210:213], v[20:23]
	v_mfma_f32_16x16x32_bf16 v[16:19], v[152:155], v[206:209], v[16:19]
	v_mfma_f32_16x16x32_bf16 v[16:19], v[156:159], v[210:213], v[16:19]
	v_mfma_f32_16x16x32_bf16 v[4:7], v[160:163], v[206:209], v[4:7]
	v_mfma_f32_16x16x32_bf16 v[4:7], v[164:167], v[210:213], v[4:7]
	v_mfma_f32_16x16x32_bf16 v[0:3], v[170:173], v[206:209], v[0:3]
	v_mfma_f32_16x16x32_bf16 v[0:3], v[178:181], v[210:213], v[0:3]
	s_setprio 0
	s_barrier
	s_add_i32 s3, s3, 2
	s_add_u32 s86, s86, 0x100
	s_addc_u32 s87, s87, 0
	s_add_u32 vcc_hi, vcc_hi, 0x100
	s_addc_u32 s2, s2, 0
	s_cmp_gt_u32 s3, 13
	s_cbranch_scc0 .LBB0_626
	s_and_b64 vcc, exec, s[72:73]
	s_cbranch_vccz .LBB0_629
	s_barrier

; #define PG8_STAGE(bufoff, gbase, voff) do { _Pragma("unroll") for (int _i = 0; _i < 2; ++_i) \
;         __builtin_amdgcn_global_load_lds((const unsigned*)((const char*)(gbase) + (voff)[_i]), (PG8_LAS unsigned*)(lds + (bufoff) + ldsw + _i * 8192), 16, 0, 0); } while (0)
; #define PG8_LDA(dst, b, h) do { _Pragma("unroll") for (int m = 0; m < 4; ++m) _Pragma("unroll") for (int k = 0; k < 2; ++k) dst[m][k] = *(const PG8_LAS bf16x8*)(lds + PG8_SA(b, h) + aoff + m * 2048 + k * 1024); } while (0)
; #define PG8_LDB(dst, b, h) do { _Pragma("unroll") for (int n = 0; n < 2; ++n) _Pragma("unroll") for (int k = 0; k < 2; ++k) dst[n][k] = *(const PG8_LAS bf16x8*)(lds + PG8_SB(b, h) + boff + n * 2048 + k * 1024); } while (0)
; #define PG8_MMA(ai, bj, At, Bt) do { __builtin_amdgcn_s_setprio(1); _Pragma("unroll") for (int m = 0; m < 4; ++m) _Pragma("unroll") for (int n = 0; n < 2; ++n) _Pragma("unroll") for (int k = 0; k < 2; ++k) \
;         acc[ai][bj][m][n] = __builtin_amdgcn_mfma_f32_16x16x32_bf16(Bt[n][k], At[m][k], acc[ai][bj][m][n], 0, 0, 0); __builtin_amdgcn_s_setprio(0); } while (0)
; #define PG8_WAIT_V(n) asm volatile("s_waitcnt vmcnt(" #n ")" ::: "memory")
; #define PG8_WAIT_L(n) asm volatile("s_waitcnt lgkmcnt(" #n ")" ::: "memory")
; #define PG8_BAR __builtin_amdgcn_s_barrier()
; #define PG8_SCHED __builtin_amdgcn_sched_barrier(0)
;     ...
;             const bool last = (t == nt - 2);
;             const char* a1 = PG8_KADV(cA, (size_t)(t + 1) * kstep);
;             const char* a2 = last ? nA : PG8_KADV(cA, (size_t)(t + 2) * kstep); const char* b2 = last ? nB : PG8_KADV(cB, (size_t)(t + 2) * kstep);
;             const char* a3 = PG8_KADV(a2, kstep); const char* b3 = PG8_KADV(b2, kstep);
;             if (last && has_next) S.a_ready(nxt);
;             if constexpr (SP2) {
;             PG8_LDB(B0, 0, 0); PG8_LDB(B1, 0, 1); PG8_SCHED; PG8_LDA(At, 0, 0); PG8_STAGE(PG8_SA(1, 1), a1 + hstep, voffA);
;             PG8_WAIT_V(8); PG8_WAIT_L(0); PG8_BAR; PG8_MMA(0, 0, At, B0); PG8_MMA(0, 1, At, B1); PG8_BAR; PG8_SCHED;
;             PG8_LDA(At, 0, 1); PG8_STAGE(PG8_SB(0, 0), b2, voffB); PG8_STAGE(PG8_SB(0, 1), b2 + hstep, voffB); PG8_STAGE(PG8_SA(0, 0), a2, voffA);
;             PG8_WAIT_V(8); PG8_WAIT_L(0); PG8_BAR; PG8_MMA(1, 0, At, B0); PG8_MMA(1, 1, At, B1); PG8_BAR; PG8_SCHED;
.LBB0_856:
	s_add_u32 s12, s82, 0xfff80080
	s_addc_u32 s13, s83, -1
	s_add_i32 s31, 0, 0x10000
	s_cmp_eq_u32 s3, 28
	s_cselect_b32 s87, s15, s13
	s_cselect_b32 s86, s23, s12
	s_cselect_b32 s85, s25, s2
	s_cselect_b32 s84, s28, s30
	s_add_i32 s33, 0, 0x14000
	v_add_u32_e32 v140, s31, v166
	v_add_u32_e32 v164, s33, v166
	ds_read_b128 v[128:131], v140
	ds_read_b128 v[132:135], v140 offset:1024
	ds_read_b128 v[136:139], v140 offset:2048
	ds_read_b128 v[140:143], v140 offset:3072
	ds_read_b128 v[144:147], v164
	ds_read_b128 v[148:151], v164 offset:1024
	ds_read_b128 v[170:173], v164 offset:2048
	ds_read_b128 v[178:181], v164 offset:3072
	s_add_i32 m0, s9, 0xc000
	ds_read_b128 v[184:187], v183
	ds_read_b128 v[188:191], v183 offset:1024
	ds_read_b128 v[192:195], v183 offset:2048
	ds_read_b128 v[196:199], v183 offset:3072
	ds_read_b128 v[200:203], v183 offset:4096
	ds_read_b128 v[204:207], v183 offset:5120
	ds_read_b128 v[208:211], v183 offset:6144
	ds_read_b128 v[212:215], v183 offset:7168
	global_load_lds_dwordx4 v160, s[82:83]
	s_add_i32 m0, s9, 0xe000
	s_nop 0
	global_load_lds_dwordx4 v162, s[82:83]
	s_waitcnt vmcnt(8)
	s_waitcnt lgkmcnt(0)
	s_barrier
	s_setprio 1
	s_waitcnt lgkmcnt(0)
	v_mfma_f32_16x16x32_bf16 v[124:127], v[128:131], v[184:187], v[124:127]
	v_mfma_f32_16x16x32_bf16 v[124:127], v[132:135], v[188:191], v[124:127]
	v_mfma_f32_16x16x32_bf16 v[120:123], v[136:139], v[184:187], v[120:123]
	v_mfma_f32_16x16x32_bf16 v[120:123], v[140:143], v[188:191], v[120:123]
	v_mfma_f32_16x16x32_bf16 v[116:119], v[144:147], v[184:187], v[116:119]
	v_mfma_f32_16x16x32_bf16 v[116:119], v[148:151], v[188:191], v[116:119]
	v_mfma_f32_16x16x32_bf16 v[108:111], v[170:173], v[184:187], v[108:111]
	v_mfma_f32_16x16x32_bf16 v[108:111], v[178:181], v[188:191], v[108:111]
	v_mfma_f32_16x16x32_bf16 v[112:115], v[128:131], v[192:195], v[112:115]
	v_mfma_f32_16x16x32_bf16 v[112:115], v[132:135], v[196:199], v[112:115]
	v_mfma_f32_16x16x32_bf16 v[104:107], v[136:139], v[192:195], v[104:107]
	v_mfma_f32_16x16x32_bf16 v[104:107], v[140:143], v[196:199], v[104:107]
	v_mfma_f32_16x16x32_bf16 v[100:103], v[144:147], v[192:195], v[100:103]
	v_mfma_f32_16x16x32_bf16 v[100:103], v[148:151], v[196:199], v[100:103]
	v_mfma_f32_16x16x32_bf16 v[96:99], v[170:173], v[192:195], v[96:99]
	v_mfma_f32_16x16x32_bf16 v[96:99], v[178:181], v[196:199], v[96:99]
	s_setprio 0
	s_setprio 1
	v_mfma_f32_16x16x32_bf16 v[92:95], v[128:131], v[200:203], v[92:95]
	v_mfma_f32_16x16x32_bf16 v[92:95], v[132:135], v[204:207], v[92:95]
	v_mfma_f32_16x16x32_bf16 v[88:91], v[136:139], v[200:203], v[88:91]
	v_mfma_f32_16x16x32_bf16 v[88:91], v[140:143], v[204:207], v[88:91]
	v_mfma_f32_16x16x32_bf16 v[84:87], v[144:147], v[200:203], v[84:87]
	v_mfma_f32_16x16x32_bf16 v[84:87], v[148:151], v[204:207], v[84:87]
	v_mfma_f32_16x16x32_bf16 v[76:79], v[170:173], v[200:203], v[76:79]
	v_mfma_f32_16x16x32_bf16 v[76:79], v[178:181], v[204:207], v[76:79]
	v_mfma_f32_16x16x32_bf16 v[80:83], v[128:131], v[208:211], v[80:83]
	v_mfma_f32_16x16x32_bf16 v[80:83], v[132:135], v[212:215], v[80:83]
	v_mfma_f32_16x16x32_bf16 v[72:75], v[136:139], v[208:211], v[72:75]
	v_mfma_f32_16x16x32_bf16 v[72:75], v[140:143], v[212:215], v[72:75]
	v_mfma_f32_16x16x32_bf16 v[68:71], v[144:147], v[208:211], v[68:71]
	v_mfma_f32_16x16x32_bf16 v[68:71], v[148:151], v[212:215], v[68:71]
	v_mfma_f32_16x16x32_bf16 v[64:67], v[170:173], v[208:211], v[64:67]
	v_mfma_f32_16x16x32_bf16 v[64:67], v[178:181], v[212:215], v[64:67]
	s_setprio 0
	s_barrier
	s_add_i32 s12, s31, s8
	s_mov_b32 m0, s12
	ds_read_b128 v[184:187], v183 offset:16384
	ds_read_b128 v[188:191], v183 offset:17408
	ds_read_b128 v[192:195], v183 offset:18432
	ds_read_b128 v[196:199], v183 offset:19456
	ds_read_b128 v[200:203], v183 offset:20480
	ds_read_b128 v[204:207], v183 offset:21504
	ds_read_b128 v[208:211], v183 offset:22528
	ds_read_b128 v[212:215], v183 offset:23552
	global_load_lds_dwordx4 v154, s[84:85]
	s_add_i32 m0, s12, 0x2000
	s_add_u32 s12, s84, 0x80000
	s_addc_u32 s13, s85, 0
	s_add_i32 s31, s33, s8
	global_load_lds_dwordx4 v158, s[84:85]
	s_mov_b32 m0, s31
	s_nop 0
	global_load_lds_dwordx4 v154, s[12:13]
	s_add_i32 m0, s31, 0x2000
	s_nop 0
	global_load_lds_dwordx4 v158, s[12:13]
	s_mov_b32 m0, s9
	s_nop 0
	global_load_lds_dwordx4 v152, s[86:87]
	s_mov_b32 m0, s10
	s_nop 0
	global_load_lds_dwordx4 v156, s[86:87]
	s_waitcnt vmcnt(8)
	s_waitcnt lgkmcnt(0)
	s_barrier
	s_setprio 1
	s_waitcnt lgkmcnt(0)
	v_mfma_f32_16x16x32_bf16 v[60:63], v[128:131], v[184:187], v[60:63]
	v_mfma_f32_16x16x32_bf16 v[60:63], v[132:135], v[188:191], v[60:63]
	v_mfma_f32_16x16x32_bf16 v[56:59], v[136:139], v[184:187], v[56:59]
	v_mfma_f32_16x16x32_bf16 v[56:59], v[140:143], v[188:191], v[56:59]
	v_mfma_f32_16x16x32_bf16 v[52:55], v[144:147], v[184:187], v[52:55]
	v_mfma_f32_16x16x32_bf16 v[52:55], v[148:151], v[188:191], v[52:55]
	v_mfma_f32_16x16x32_bf16 v[44:47], v[170:173], v[184:187], v[44:47]
	v_mfma_f32_16x16x32_bf16 v[44:47], v[178:181], v[188:191], v[44:47]
	v_mfma_f32_16x16x32_bf16 v[48:51], v[128:131], v[192:195], v[48:51]
	v_mfma_f32_16x16x32_bf16 v[48:51], v[132:135], v[196:199], v[48:51]
	v_mfma_f32_16x16x32_bf16 v[40:43], v[136:139], v[192:195], v[40:43]
	v_mfma_f32_16x16x32_bf16 v[40:43], v[140:143], v[196:199], v[40:43]
	v_mfma_f32_16x16x32_bf16 v[36:39], v[144:147], v[192:195], v[36:39]
	v_mfma_f32_16x16x32_bf16 v[36:39], v[148:151], v[196:199], v[36:39]
	v_mfma_f32_16x16x32_bf16 v[32:35], v[170:173], v[192:195], v[32:35]
	v_mfma_f32_16x16x32_bf16 v[32:35], v[178:181], v[196:199], v[32:35]
	s_setprio 0
	s_setprio 1
	v_mfma_f32_16x16x32_bf16 v[28:31], v[128:131], v[200:203], v[28:31]
	v_mfma_f32_16x16x32_bf16 v[28:31], v[132:135], v[204:207], v[28:31]
	v_mfma_f32_16x16x32_bf16 v[24:27], v[136:139], v[200:203], v[24:27]
	v_mfma_f32_16x16x32_bf16 v[24:27], v[140:143], v[204:207], v[24:27]
	v_mfma_f32_16x16x32_bf16 v[20:23], v[144:147], v[200:203], v[20:23]
	v_mfma_f32_16x16x32_bf16 v[20:23], v[148:151], v[204:207], v[20:23]
	v_mfma_f32_16x16x32_bf16 v[12:15], v[170:173], v[200:203], v[12:15]
	v_mfma_f32_16x16x32_bf16 v[12:15], v[178:181], v[204:207], v[12:15]
	v_mfma_f32_16x16x32_bf16 v[16:19], v[128:131], v[208:211], v[16:19]
	v_mfma_f32_16x16x32_bf16 v[16:19], v[132:135], v[212:215], v[16:19]
	v_mfma_f32_16x16x32_bf16 v[8:11], v[136:139], v[208:211], v[8:11]
	v_mfma_f32_16x16x32_bf16 v[8:11], v[140:143], v[212:215], v[8:11]
	v_mfma_f32_16x16x32_bf16 v[4:7], v[144:147], v[208:211], v[4:7]
	v_mfma_f32_16x16x32_bf16 v[4:7], v[148:151], v[212:215], v[4:7]
	v_mfma_f32_16x16x32_bf16 v[0:3], v[170:173], v[208:211], v[0:3]
	v_mfma_f32_16x16x32_bf16 v[0:3], v[178:181], v[212:215], v[0:3]
	s_setprio 0
	s_barrier
; #define PG8_STAGE(bufoff, gbase, voff) do { _Pragma("unroll") for (int _i = 0; _i < 2; ++_i) \
;         __builtin_amdgcn_global_load_lds((const unsigned*)((const char*)(gbase) + (voff)[_i]), (PG8_LAS unsigned*)(lds + (bufoff) + ldsw + _i * 8192), 16, 0, 0); } while (0)
; #define PG8_LDA(dst, b, h) do { _Pragma("unroll") for (int m = 0; m < 4; ++m) _Pragma("unroll") for (int k = 0; k < 2; ++k) dst[m][k] = *(const PG8_LAS bf16x8*)(lds + PG8_SA(b, h) + aoff + m * 2048 + k * 1024); } while (0)
; #define PG8_LDB(dst, b, h) do { _Pragma("unroll") for (int n = 0; n < 2; ++n) _Pragma("unroll") for (int k = 0; k < 2; ++k) dst[n][k] = *(const PG8_LAS bf16x8*)(lds + PG8_SB(b, h) + boff + n * 2048 + k * 1024); } while (0)
; #define PG8_MMA(ai, bj, At, Bt) do { __builtin_amdgcn_s_setprio(1); _Pragma("unroll") for (int m = 0; m < 4; ++m) _Pragma("unroll") for (int n = 0; n < 2; ++n) _Pragma("unroll") for (int k = 0; k < 2; ++k) \
;         acc[ai][bj][m][n] = __builtin_amdgcn_mfma_f32_16x16x32_bf16(Bt[n][k], At[m][k], acc[ai][bj][m][n], 0, 0, 0); __builtin_amdgcn_s_setprio(0); } while (0)
; #define PG8_WAIT_V(n) asm volatile("s_waitcnt vmcnt(" #n ")" ::: "memory")
; #define PG8_WAIT_L(n) asm volatile("s_waitcnt lgkmcnt(" #n ")" ::: "memory")
; #define PG8_BAR __builtin_amdgcn_s_barrier()
; #define PG8_SCHED __builtin_amdgcn_sched_barrier(0)
;     ...
;             PG8_LDB(B0, 1, 0); PG8_LDB(B1, 1, 1); PG8_SCHED; PG8_LDA(At, 1, 0); PG8_STAGE(PG8_SA(0, 1), a2 + hstep, voffA);
;             PG8_WAIT_V(8); PG8_WAIT_L(0); PG8_BAR; PG8_MMA(0, 0, At, B0); PG8_MMA(0, 1, At, B1); PG8_BAR; PG8_SCHED;
;             PG8_LDA(At, 1, 1); PG8_STAGE(PG8_SB(1, 0), b3, voffB); PG8_STAGE(PG8_SB(1, 1), b3 + hstep, voffB); PG8_STAGE(PG8_SA(1, 0), a3, voffA);
;             PG8_WAIT_V(8); PG8_WAIT_L(0); PG8_BAR; PG8_MMA(1, 0, At, B0); PG8_MMA(1, 1, At, B1); PG8_BAR; PG8_SCHED;
	s_add_i32 s31, 0, 0x18000
	s_add_i32 s33, 0, 0x1c000
	v_add_u32_e32 v140, s31, v166
	v_add_u32_e32 v168, s33, v166
	ds_read_b128 v[128:131], v140
	ds_read_b128 v[132:135], v140 offset:1024
	ds_read_b128 v[136:139], v140 offset:2048
	ds_read_b128 v[140:143], v140 offset:3072
	ds_read_b128 v[144:147], v168
	ds_read_b128 v[148:151], v168 offset:1024
	ds_read_b128 v[170:173], v168 offset:2048
	ds_read_b128 v[178:181], v168 offset:3072
	s_add_u32 s12, s86, 0x80000
	s_addc_u32 s13, s87, 0
	s_mov_b32 m0, s18
	ds_read_b128 v[184:187], v183 offset:32768
	ds_read_b128 v[188:191], v183 offset:33792
	ds_read_b128 v[192:195], v183 offset:34816
	ds_read_b128 v[196:199], v183 offset:35840
	ds_read_b128 v[200:203], v183 offset:36864
	ds_read_b128 v[204:207], v183 offset:37888
	ds_read_b128 v[208:211], v183 offset:38912
	ds_read_b128 v[212:215], v183 offset:39936
	global_load_lds_dwordx4 v152, s[12:13]
	s_mov_b32 m0, s19
	s_nop 0
	global_load_lds_dwordx4 v156, s[12:13]
	s_waitcnt vmcnt(8)
	s_waitcnt lgkmcnt(0)
	s_barrier
	s_setprio 1
	s_waitcnt lgkmcnt(0)
	v_mfma_f32_16x16x32_bf16 v[124:127], v[128:131], v[184:187], v[124:127]
	v_mfma_f32_16x16x32_bf16 v[124:127], v[132:135], v[188:191], v[124:127]
	v_mfma_f32_16x16x32_bf16 v[120:123], v[136:139], v[184:187], v[120:123]
	v_mfma_f32_16x16x32_bf16 v[120:123], v[140:143], v[188:191], v[120:123]
	v_mfma_f32_16x16x32_bf16 v[116:119], v[144:147], v[184:187], v[116:119]
	v_mfma_f32_16x16x32_bf16 v[116:119], v[148:151], v[188:191], v[116:119]
	v_mfma_f32_16x16x32_bf16 v[108:111], v[170:173], v[184:187], v[108:111]
	v_mfma_f32_16x16x32_bf16 v[108:111], v[178:181], v[188:191], v[108:111]
	v_mfma_f32_16x16x32_bf16 v[112:115], v[128:131], v[192:195], v[112:115]
	v_mfma_f32_16x16x32_bf16 v[112:115], v[132:135], v[196:199], v[112:115]
	v_mfma_f32_16x16x32_bf16 v[104:107], v[136:139], v[192:195], v[104:107]
	v_mfma_f32_16x16x32_bf16 v[104:107], v[140:143], v[196:199], v[104:107]
	v_mfma_f32_16x16x32_bf16 v[100:103], v[144:147], v[192:195], v[100:103]
	v_mfma_f32_16x16x32_bf16 v[100:103], v[148:151], v[196:199], v[100:103]
	v_mfma_f32_16x16x32_bf16 v[96:99], v[170:173], v[192:195], v[96:99]
	v_mfma_f32_16x16x32_bf16 v[96:99], v[178:181], v[196:199], v[96:99]
	s_setprio 0
	s_setprio 1
	v_mfma_f32_16x16x32_bf16 v[92:95], v[128:131], v[200:203], v[92:95]
	v_mfma_f32_16x16x32_bf16 v[92:95], v[132:135], v[204:207], v[92:95]
	v_mfma_f32_16x16x32_bf16 v[88:91], v[136:139], v[200:203], v[88:91]
	v_mfma_f32_16x16x32_bf16 v[88:91], v[140:143], v[204:207], v[88:91]
	v_mfma_f32_16x16x32_bf16 v[84:87], v[144:147], v[200:203], v[84:87]
	v_mfma_f32_16x16x32_bf16 v[84:87], v[148:151], v[204:207], v[84:87]
	v_mfma_f32_16x16x32_bf16 v[76:79], v[170:173], v[200:203], v[76:79]
	v_mfma_f32_16x16x32_bf16 v[76:79], v[178:181], v[204:207], v[76:79]
	v_mfma_f32_16x16x32_bf16 v[80:83], v[128:131], v[208:211], v[80:83]
	v_mfma_f32_16x16x32_bf16 v[80:83], v[132:135], v[212:215], v[80:83]
	v_mfma_f32_16x16x32_bf16 v[72:75], v[136:139], v[208:211], v[72:75]
	v_mfma_f32_16x16x32_bf16 v[72:75], v[140:143], v[212:215], v[72:75]
	v_mfma_f32_16x16x32_bf16 v[68:71], v[144:147], v[208:211], v[68:71]
	v_mfma_f32_16x16x32_bf16 v[68:71], v[148:151], v[212:215], v[68:71]
	v_mfma_f32_16x16x32_bf16 v[64:67], v[170:173], v[208:211], v[64:67]
	v_mfma_f32_16x16x32_bf16 v[64:67], v[178:181], v[212:215], v[64:67]
	s_setprio 0
	s_barrier
	s_add_i32 s12, s31, s8
	s_mov_b32 m0, s12
	ds_read_b128 v[184:187], v183 offset:49152
	ds_read_b128 v[188:191], v183 offset:50176
	ds_read_b128 v[192:195], v183 offset:51200
	ds_read_b128 v[196:199], v183 offset:52224
	ds_read_b128 v[200:203], v183 offset:53248
	ds_read_b128 v[204:207], v183 offset:54272
	ds_read_b128 v[208:211], v183 offset:55296
	ds_read_b128 v[212:215], v183 offset:56320
	s_add_u32 s100, s84, s16
	s_addc_u32 s101, s85, s17
	global_load_lds_dwordx4 v154, s[100:101]
	s_add_i32 m0, s12, 0x2000
	s_add_u32 s12, s84, 0x80080
	s_addc_u32 s13, s85, 0
	s_add_i32 s31, s33, s8
	global_load_lds_dwordx4 v158, s[100:101]
	s_mov_b32 m0, s31
	s_nop 0
	global_load_lds_dwordx4 v154, s[12:13]
	s_add_i32 m0, s31, 0x2000
	s_nop 0
	global_load_lds_dwordx4 v158, s[12:13]
	s_mov_b32 m0, s20
	s_nop 0
	s_add_u32 s100, s86, s16
	s_addc_u32 s101, s87, s17
	global_load_lds_dwordx4 v152, s[100:101]
	s_mov_b32 m0, s21
	s_nop 0
	global_load_lds_dwordx4 v156, s[100:101]
	s_waitcnt vmcnt(8)
	s_waitcnt lgkmcnt(0)
	s_barrier
	s_setprio 1
	s_waitcnt lgkmcnt(0)
	v_mfma_f32_16x16x32_bf16 v[60:63], v[128:131], v[184:187], v[60:63]
	v_mfma_f32_16x16x32_bf16 v[60:63], v[132:135], v[188:191], v[60:63]
	v_mfma_f32_16x16x32_bf16 v[56:59], v[136:139], v[184:187], v[56:59]
	v_mfma_f32_16x16x32_bf16 v[56:59], v[140:143], v[188:191], v[56:59]
	v_mfma_f32_16x16x32_bf16 v[52:55], v[144:147], v[184:187], v[52:55]
	v_mfma_f32_16x16x32_bf16 v[52:55], v[148:151], v[188:191], v[52:55]
	v_mfma_f32_16x16x32_bf16 v[44:47], v[170:173], v[184:187], v[44:47]
	v_mfma_f32_16x16x32_bf16 v[44:47], v[178:181], v[188:191], v[44:47]
	v_mfma_f32_16x16x32_bf16 v[48:51], v[128:131], v[192:195], v[48:51]
	v_mfma_f32_16x16x32_bf16 v[48:51], v[132:135], v[196:199], v[48:51]
	v_mfma_f32_16x16x32_bf16 v[40:43], v[136:139], v[192:195], v[40:43]
	v_mfma_f32_16x16x32_bf16 v[40:43], v[140:143], v[196:199], v[40:43]
	v_mfma_f32_16x16x32_bf16 v[36:39], v[144:147], v[192:195], v[36:39]
	v_mfma_f32_16x16x32_bf16 v[36:39], v[148:151], v[196:199], v[36:39]
	v_mfma_f32_16x16x32_bf16 v[32:35], v[170:173], v[192:195], v[32:35]
	v_mfma_f32_16x16x32_bf16 v[32:35], v[178:181], v[196:199], v[32:35]
	s_setprio 0
	s_setprio 1
	v_mfma_f32_16x16x32_bf16 v[28:31], v[128:131], v[200:203], v[28:31]
	v_mfma_f32_16x16x32_bf16 v[28:31], v[132:135], v[204:207], v[28:31]
	v_mfma_f32_16x16x32_bf16 v[24:27], v[136:139], v[200:203], v[24:27]
	v_mfma_f32_16x16x32_bf16 v[24:27], v[140:143], v[204:207], v[24:27]
	v_mfma_f32_16x16x32_bf16 v[20:23], v[144:147], v[200:203], v[20:23]
	v_mfma_f32_16x16x32_bf16 v[20:23], v[148:151], v[204:207], v[20:23]
	v_mfma_f32_16x16x32_bf16 v[12:15], v[170:173], v[200:203], v[12:15]
	v_mfma_f32_16x16x32_bf16 v[12:15], v[178:181], v[204:207], v[12:15]
	v_mfma_f32_16x16x32_bf16 v[16:19], v[128:131], v[208:211], v[16:19]
	v_mfma_f32_16x16x32_bf16 v[16:19], v[132:135], v[212:215], v[16:19]
	v_mfma_f32_16x16x32_bf16 v[8:11], v[136:139], v[208:211], v[8:11]
	v_mfma_f32_16x16x32_bf16 v[8:11], v[140:143], v[212:215], v[8:11]
	v_mfma_f32_16x16x32_bf16 v[4:7], v[144:147], v[208:211], v[4:7]
	v_mfma_f32_16x16x32_bf16 v[4:7], v[148:151], v[212:215], v[4:7]
	v_mfma_f32_16x16x32_bf16 v[0:3], v[170:173], v[208:211], v[0:3]
	v_mfma_f32_16x16x32_bf16 v[0:3], v[178:181], v[212:215], v[0:3]
	s_setprio 0
	s_barrier
	s_add_i32 s3, s3, 2
	s_add_u32 s82, s82, 0x100
	s_addc_u32 s83, s83, 0
	s_add_u32 s30, s30, 0x100
	s_addc_u32 s2, s2, 0
	s_cmp_gt_u32 s3, 29
	s_cbranch_scc0 .LBB0_856
	s_and_b64 vcc, exec, s[70:71]
	s_cbranch_vccz .LBB0_859
	s_barrier

; #define PG8_STAGE(bufoff, gbase, voff) do { _Pragma("unroll") for (int _i = 0; _i < 2; ++_i) \
;         __builtin_amdgcn_global_load_lds((const unsigned*)((const char*)(gbase) + (voff)[_i]), (PG8_LAS unsigned*)(lds + (bufoff) + ldsw + _i * 8192), 16, 0, 0); } while (0)
; #define PG8_LDA(dst, b, h) do { _Pragma("unroll") for (int m = 0; m < 4; ++m) _Pragma("unroll") for (int k = 0; k < 2; ++k) dst[m][k] = *(const PG8_LAS bf16x8*)(lds + PG8_SA(b, h) + aoff + m * 2048 + k * 1024); } while (0)
; #define PG8_LDB(dst, b, h) do { _Pragma("unroll") for (int n = 0; n < 2; ++n) _Pragma("unroll") for (int k = 0; k < 2; ++k) dst[n][k] = *(const PG8_LAS bf16x8*)(lds + PG8_SB(b, h) + boff + n * 2048 + k * 1024); } while (0)
; #define PG8_MMA(ai, bj, At, Bt) do { __builtin_amdgcn_s_setprio(1); _Pragma("unroll") for (int m = 0; m < 4; ++m) _Pragma("unroll") for (int n = 0; n < 2; ++n) _Pragma("unroll") for (int k = 0; k < 2; ++k) \
;         acc[ai][bj][m][n] = __builtin_amdgcn_mfma_f32_16x16x32_bf16(Bt[n][k], At[m][k], acc[ai][bj][m][n], 0, 0, 0); __builtin_amdgcn_s_setprio(0); } while (0)
; #define PG8_WAIT_V(n) asm volatile("s_waitcnt vmcnt(" #n ")" ::: "memory")
; #define PG8_WAIT_L(n) asm volatile("s_waitcnt lgkmcnt(" #n ")" ::: "memory")
; #define PG8_BAR __builtin_amdgcn_s_barrier()
; #define PG8_SCHED __builtin_amdgcn_sched_barrier(0)
;     ...
;             const bool last = (t == nt - 2);
;             const char* a1 = PG8_KADV(cA, (size_t)(t + 1) * kstep);
;             const char* a2 = last ? nA : PG8_KADV(cA, (size_t)(t + 2) * kstep); const char* b2 = last ? nB : PG8_KADV(cB, (size_t)(t + 2) * kstep);
;             const char* a3 = PG8_KADV(a2, kstep); const char* b3 = PG8_KADV(b2, kstep);
;             if (last && has_next) S.a_ready(nxt);
;             if constexpr (SP2) {
;             PG8_LDB(B0, 0, 0); PG8_LDB(B1, 0, 1); PG8_SCHED; PG8_LDA(At, 0, 0); PG8_STAGE(PG8_SA(1, 1), a1 + hstep, voffA);
;             PG8_WAIT_V(8); PG8_WAIT_L(0); PG8_BAR; PG8_MMA(0, 0, At, B0); PG8_MMA(0, 1, At, B1); PG8_BAR; PG8_SCHED;
;             PG8_LDA(At, 0, 1); PG8_STAGE(PG8_SB(0, 0), b2, voffB); PG8_STAGE(PG8_SB(0, 1), b2 + hstep, voffB); PG8_STAGE(PG8_SA(0, 0), a2, voffA);
;             PG8_WAIT_V(8); PG8_WAIT_L(0); PG8_BAR; PG8_MMA(1, 0, At, B0); PG8_MMA(1, 1, At, B1); PG8_BAR; PG8_SCHED;
.LBB0_983:
	s_add_u32 s12, s70, 0xfff80080
	s_addc_u32 s13, s71, -1
	s_add_i32 s31, 0, 0x10000
	s_cmp_eq_u32 s3, 28
	s_cselect_b32 s75, s15, s13
	s_cselect_b32 s74, s28, s12
	s_cselect_b32 s73, s30, s2
	s_cselect_b32 s72, s33, s40
	s_add_i32 s42, 0, 0x14000
	v_add_u32_e32 v156, s31, v141
	v_add_u32_e32 v168, s42, v141
	ds_read_b128 v[144:147], v156
	ds_read_b128 v[148:151], v156 offset:1024
	ds_read_b128 v[152:155], v156 offset:2048
	ds_read_b128 v[156:159], v156 offset:3072
	ds_read_b128 v[160:163], v168
	ds_read_b128 v[164:167], v168 offset:1024
	ds_read_b128 v[170:173], v168 offset:2048
	ds_read_b128 v[178:181], v168 offset:3072
	s_add_i32 m0, s18, 0xc000
	ds_read_b128 v[182:185], v143
	ds_read_b128 v[186:189], v143 offset:1024
	ds_read_b128 v[190:193], v143 offset:2048
	ds_read_b128 v[194:197], v143 offset:3072
	ds_read_b128 v[198:201], v143 offset:4096
	ds_read_b128 v[202:205], v143 offset:5120
	ds_read_b128 v[206:209], v143 offset:6144
	ds_read_b128 v[210:213], v143 offset:7168
	global_load_lds_dwordx4 v136, s[70:71]
	s_add_i32 m0, s18, 0xe000
	s_nop 0
	global_load_lds_dwordx4 v138, s[70:71]
	s_waitcnt vmcnt(8)
	s_waitcnt lgkmcnt(0)
	s_barrier
	s_setprio 1
	s_waitcnt lgkmcnt(0)
	v_mfma_f32_16x16x32_bf16 v[124:127], v[144:147], v[182:185], v[124:127]
	v_mfma_f32_16x16x32_bf16 v[124:127], v[148:151], v[186:189], v[124:127]
	v_mfma_f32_16x16x32_bf16 v[120:123], v[152:155], v[182:185], v[120:123]
	v_mfma_f32_16x16x32_bf16 v[120:123], v[156:159], v[186:189], v[120:123]
	v_mfma_f32_16x16x32_bf16 v[116:119], v[160:163], v[182:185], v[116:119]
	v_mfma_f32_16x16x32_bf16 v[116:119], v[164:167], v[186:189], v[116:119]
	v_mfma_f32_16x16x32_bf16 v[112:115], v[170:173], v[182:185], v[112:115]
	v_mfma_f32_16x16x32_bf16 v[112:115], v[178:181], v[186:189], v[112:115]
	v_mfma_f32_16x16x32_bf16 v[108:111], v[144:147], v[190:193], v[108:111]
	v_mfma_f32_16x16x32_bf16 v[108:111], v[148:151], v[194:197], v[108:111]
	v_mfma_f32_16x16x32_bf16 v[104:107], v[152:155], v[190:193], v[104:107]
	v_mfma_f32_16x16x32_bf16 v[104:107], v[156:159], v[194:197], v[104:107]
	v_mfma_f32_16x16x32_bf16 v[100:103], v[160:163], v[190:193], v[100:103]
	v_mfma_f32_16x16x32_bf16 v[100:103], v[164:167], v[194:197], v[100:103]
	v_mfma_f32_16x16x32_bf16 v[96:99], v[170:173], v[190:193], v[96:99]
	v_mfma_f32_16x16x32_bf16 v[96:99], v[178:181], v[194:197], v[96:99]
	s_setprio 0
	s_setprio 1
	v_mfma_f32_16x16x32_bf16 v[92:95], v[144:147], v[198:201], v[92:95]
	v_mfma_f32_16x16x32_bf16 v[92:95], v[148:151], v[202:205], v[92:95]
	v_mfma_f32_16x16x32_bf16 v[88:91], v[152:155], v[198:201], v[88:91]
	v_mfma_f32_16x16x32_bf16 v[88:91], v[156:159], v[202:205], v[88:91]
	v_mfma_f32_16x16x32_bf16 v[84:87], v[160:163], v[198:201], v[84:87]
	v_mfma_f32_16x16x32_bf16 v[84:87], v[164:167], v[202:205], v[84:87]
	v_mfma_f32_16x16x32_bf16 v[80:83], v[170:173], v[198:201], v[80:83]
	v_mfma_f32_16x16x32_bf16 v[80:83], v[178:181], v[202:205], v[80:83]
	v_mfma_f32_16x16x32_bf16 v[76:79], v[144:147], v[206:209], v[76:79]
	v_mfma_f32_16x16x32_bf16 v[76:79], v[148:151], v[210:213], v[76:79]
	v_mfma_f32_16x16x32_bf16 v[72:75], v[152:155], v[206:209], v[72:75]
	v_mfma_f32_16x16x32_bf16 v[72:75], v[156:159], v[210:213], v[72:75]
	v_mfma_f32_16x16x32_bf16 v[68:71], v[160:163], v[206:209], v[68:71]
	v_mfma_f32_16x16x32_bf16 v[68:71], v[164:167], v[210:213], v[68:71]
	v_mfma_f32_16x16x32_bf16 v[64:67], v[170:173], v[206:209], v[64:67]
	v_mfma_f32_16x16x32_bf16 v[64:67], v[178:181], v[210:213], v[64:67]
	s_setprio 0
	s_barrier
	s_add_i32 s12, s31, s10
	s_mov_b32 m0, s12
	ds_read_b128 v[182:185], v143 offset:16384
	ds_read_b128 v[186:189], v143 offset:17408
	ds_read_b128 v[190:193], v143 offset:18432
	ds_read_b128 v[194:197], v143 offset:19456
	ds_read_b128 v[198:201], v143 offset:20480
	ds_read_b128 v[202:205], v143 offset:21504
	ds_read_b128 v[206:209], v143 offset:22528
	ds_read_b128 v[210:213], v143 offset:23552
	global_load_lds_dwordx4 v132, s[72:73]
	s_add_i32 m0, s12, 0x2000
	s_add_u32 s12, s72, 0x80000
	s_addc_u32 s13, s73, 0
	s_add_i32 s31, s42, s10
	global_load_lds_dwordx4 v128, s[72:73]
	s_mov_b32 m0, s31
	s_nop 0
	global_load_lds_dwordx4 v132, s[12:13]
	s_add_i32 m0, s31, 0x2000
	s_nop 0
	global_load_lds_dwordx4 v128, s[12:13]
	s_mov_b32 m0, s18
	s_nop 0
	global_load_lds_dwordx4 v134, s[74:75]
	s_mov_b32 m0, s19
	s_nop 0
	global_load_lds_dwordx4 v130, s[74:75]
	s_waitcnt vmcnt(8)
	s_waitcnt lgkmcnt(0)
	s_barrier
	s_setprio 1
	s_waitcnt lgkmcnt(0)
	v_mfma_f32_16x16x32_bf16 v[60:63], v[144:147], v[182:185], v[60:63]
	v_mfma_f32_16x16x32_bf16 v[60:63], v[148:151], v[186:189], v[60:63]
	v_mfma_f32_16x16x32_bf16 v[56:59], v[152:155], v[182:185], v[56:59]
	v_mfma_f32_16x16x32_bf16 v[56:59], v[156:159], v[186:189], v[56:59]
	v_mfma_f32_16x16x32_bf16 v[52:55], v[160:163], v[182:185], v[52:55]
	v_mfma_f32_16x16x32_bf16 v[52:55], v[164:167], v[186:189], v[52:55]
	v_mfma_f32_16x16x32_bf16 v[48:51], v[170:173], v[182:185], v[48:51]
	v_mfma_f32_16x16x32_bf16 v[48:51], v[178:181], v[186:189], v[48:51]
	v_mfma_f32_16x16x32_bf16 v[44:47], v[144:147], v[190:193], v[44:47]
	v_mfma_f32_16x16x32_bf16 v[44:47], v[148:151], v[194:197], v[44:47]
	v_mfma_f32_16x16x32_bf16 v[40:43], v[152:155], v[190:193], v[40:43]
	v_mfma_f32_16x16x32_bf16 v[40:43], v[156:159], v[194:197], v[40:43]
	v_mfma_f32_16x16x32_bf16 v[36:39], v[160:163], v[190:193], v[36:39]
	v_mfma_f32_16x16x32_bf16 v[36:39], v[164:167], v[194:197], v[36:39]
	v_mfma_f32_16x16x32_bf16 v[32:35], v[170:173], v[190:193], v[32:35]
	v_mfma_f32_16x16x32_bf16 v[32:35], v[178:181], v[194:197], v[32:35]
	s_setprio 0
	s_setprio 1
	v_mfma_f32_16x16x32_bf16 v[28:31], v[144:147], v[198:201], v[28:31]
	v_mfma_f32_16x16x32_bf16 v[28:31], v[148:151], v[202:205], v[28:31]
	v_mfma_f32_16x16x32_bf16 v[24:27], v[152:155], v[198:201], v[24:27]
	v_mfma_f32_16x16x32_bf16 v[24:27], v[156:159], v[202:205], v[24:27]
	v_mfma_f32_16x16x32_bf16 v[20:23], v[160:163], v[198:201], v[20:23]
	v_mfma_f32_16x16x32_bf16 v[20:23], v[164:167], v[202:205], v[20:23]
	v_mfma_f32_16x16x32_bf16 v[16:19], v[170:173], v[198:201], v[16:19]
	v_mfma_f32_16x16x32_bf16 v[16:19], v[178:181], v[202:205], v[16:19]
	v_mfma_f32_16x16x32_bf16 v[12:15], v[144:147], v[206:209], v[12:15]
	v_mfma_f32_16x16x32_bf16 v[12:15], v[148:151], v[210:213], v[12:15]
	v_mfma_f32_16x16x32_bf16 v[8:11], v[152:155], v[206:209], v[8:11]
	v_mfma_f32_16x16x32_bf16 v[8:11], v[156:159], v[210:213], v[8:11]
	v_mfma_f32_16x16x32_bf16 v[4:7], v[160:163], v[206:209], v[4:7]
	v_mfma_f32_16x16x32_bf16 v[4:7], v[164:167], v[210:213], v[4:7]
	v_mfma_f32_16x16x32_bf16 v[0:3], v[170:173], v[206:209], v[0:3]
	v_mfma_f32_16x16x32_bf16 v[0:3], v[178:181], v[210:213], v[0:3]
	s_setprio 0
	s_barrier
; #define PG8_STAGE(bufoff, gbase, voff) do { _Pragma("unroll") for (int _i = 0; _i < 2; ++_i) \
;         __builtin_amdgcn_global_load_lds((const unsigned*)((const char*)(gbase) + (voff)[_i]), (PG8_LAS unsigned*)(lds + (bufoff) + ldsw + _i * 8192), 16, 0, 0); } while (0)
; #define PG8_LDA(dst, b, h) do { _Pragma("unroll") for (int m = 0; m < 4; ++m) _Pragma("unroll") for (int k = 0; k < 2; ++k) dst[m][k] = *(const PG8_LAS bf16x8*)(lds + PG8_SA(b, h) + aoff + m * 2048 + k * 1024); } while (0)
; #define PG8_LDB(dst, b, h) do { _Pragma("unroll") for (int n = 0; n < 2; ++n) _Pragma("unroll") for (int k = 0; k < 2; ++k) dst[n][k] = *(const PG8_LAS bf16x8*)(lds + PG8_SB(b, h) + boff + n * 2048 + k * 1024); } while (0)
; #define PG8_MMA(ai, bj, At, Bt) do { __builtin_amdgcn_s_setprio(1); _Pragma("unroll") for (int m = 0; m < 4; ++m) _Pragma("unroll") for (int n = 0; n < 2; ++n) _Pragma("unroll") for (int k = 0; k < 2; ++k) \
;         acc[ai][bj][m][n] = __builtin_amdgcn_mfma_f32_16x16x32_bf16(Bt[n][k], At[m][k], acc[ai][bj][m][n], 0, 0, 0); __builtin_amdgcn_s_setprio(0); } while (0)
; #define PG8_WAIT_V(n) asm volatile("s_waitcnt vmcnt(" #n ")" ::: "memory")
; #define PG8_WAIT_L(n) asm volatile("s_waitcnt lgkmcnt(" #n ")" ::: "memory")
; #define PG8_BAR __builtin_amdgcn_s_barrier()
; #define PG8_SCHED __builtin_amdgcn_sched_barrier(0)
;     ...
;             PG8_LDB(B0, 1, 0); PG8_LDB(B1, 1, 1); PG8_SCHED; PG8_LDA(At, 1, 0); PG8_STAGE(PG8_SA(0, 1), a2 + hstep, voffA);
;             PG8_WAIT_V(8); PG8_WAIT_L(0); PG8_BAR; PG8_MMA(0, 0, At, B0); PG8_MMA(0, 1, At, B1); PG8_BAR; PG8_SCHED;
;             PG8_LDA(At, 1, 1); PG8_STAGE(PG8_SB(1, 0), b3, voffB); PG8_STAGE(PG8_SB(1, 1), b3 + hstep, voffB); PG8_STAGE(PG8_SA(1, 0), a3, voffA);
;             PG8_WAIT_V(8); PG8_WAIT_L(0); PG8_BAR; PG8_MMA(1, 0, At, B0); PG8_MMA(1, 1, At, B1); PG8_BAR; PG8_SCHED;
	s_add_i32 s31, 0, 0x18000
	s_add_i32 s42, 0, 0x1c000
	v_add_u32_e32 v156, s31, v141
	v_add_u32_e32 v168, s42, v141
	ds_read_b128 v[144:147], v156
	ds_read_b128 v[148:151], v156 offset:1024
	ds_read_b128 v[152:155], v156 offset:2048
	ds_read_b128 v[156:159], v156 offset:3072
	ds_read_b128 v[160:163], v168
	ds_read_b128 v[164:167], v168 offset:1024
	ds_read_b128 v[170:173], v168 offset:2048
	ds_read_b128 v[178:181], v168 offset:3072
	s_add_u32 s12, s74, 0x80000
	s_addc_u32 s13, s75, 0
	s_mov_b32 m0, s20
	ds_read_b128 v[182:185], v143 offset:32768
	ds_read_b128 v[186:189], v143 offset:33792
	ds_read_b128 v[190:193], v143 offset:34816
	ds_read_b128 v[194:197], v143 offset:35840
	ds_read_b128 v[198:201], v143 offset:36864
	ds_read_b128 v[202:205], v143 offset:37888
	ds_read_b128 v[206:209], v143 offset:38912
	ds_read_b128 v[210:213], v143 offset:39936
	global_load_lds_dwordx4 v134, s[12:13]
	s_mov_b32 m0, s21
	s_nop 0
	global_load_lds_dwordx4 v130, s[12:13]
	s_waitcnt vmcnt(8)
	s_waitcnt lgkmcnt(0)
	s_barrier
	s_setprio 1
	s_waitcnt lgkmcnt(0)
	v_mfma_f32_16x16x32_bf16 v[124:127], v[144:147], v[182:185], v[124:127]
	v_mfma_f32_16x16x32_bf16 v[124:127], v[148:151], v[186:189], v[124:127]
	v_mfma_f32_16x16x32_bf16 v[120:123], v[152:155], v[182:185], v[120:123]
	v_mfma_f32_16x16x32_bf16 v[120:123], v[156:159], v[186:189], v[120:123]
	v_mfma_f32_16x16x32_bf16 v[116:119], v[160:163], v[182:185], v[116:119]
	v_mfma_f32_16x16x32_bf16 v[116:119], v[164:167], v[186:189], v[116:119]
	v_mfma_f32_16x16x32_bf16 v[112:115], v[170:173], v[182:185], v[112:115]
	v_mfma_f32_16x16x32_bf16 v[112:115], v[178:181], v[186:189], v[112:115]
	v_mfma_f32_16x16x32_bf16 v[108:111], v[144:147], v[190:193], v[108:111]
	v_mfma_f32_16x16x32_bf16 v[108:111], v[148:151], v[194:197], v[108:111]
	v_mfma_f32_16x16x32_bf16 v[104:107], v[152:155], v[190:193], v[104:107]
	v_mfma_f32_16x16x32_bf16 v[104:107], v[156:159], v[194:197], v[104:107]
	v_mfma_f32_16x16x32_bf16 v[100:103], v[160:163], v[190:193], v[100:103]
	v_mfma_f32_16x16x32_bf16 v[100:103], v[164:167], v[194:197], v[100:103]
	v_mfma_f32_16x16x32_bf16 v[96:99], v[170:173], v[190:193], v[96:99]
	v_mfma_f32_16x16x32_bf16 v[96:99], v[178:181], v[194:197], v[96:99]
	s_setprio 0
	s_setprio 1
	v_mfma_f32_16x16x32_bf16 v[92:95], v[144:147], v[198:201], v[92:95]
	v_mfma_f32_16x16x32_bf16 v[92:95], v[148:151], v[202:205], v[92:95]
	v_mfma_f32_16x16x32_bf16 v[88:91], v[152:155], v[198:201], v[88:91]
	v_mfma_f32_16x16x32_bf16 v[88:91], v[156:159], v[202:205], v[88:91]
	v_mfma_f32_16x16x32_bf16 v[84:87], v[160:163], v[198:201], v[84:87]
	v_mfma_f32_16x16x32_bf16 v[84:87], v[164:167], v[202:205], v[84:87]
	v_mfma_f32_16x16x32_bf16 v[80:83], v[170:173], v[198:201], v[80:83]
	v_mfma_f32_16x16x32_bf16 v[80:83], v[178:181], v[202:205], v[80:83]
	v_mfma_f32_16x16x32_bf16 v[76:79], v[144:147], v[206:209], v[76:79]
	v_mfma_f32_16x16x32_bf16 v[76:79], v[148:151], v[210:213], v[76:79]
	v_mfma_f32_16x16x32_bf16 v[72:75], v[152:155], v[206:209], v[72:75]
	v_mfma_f32_16x16x32_bf16 v[72:75], v[156:159], v[210:213], v[72:75]
	v_mfma_f32_16x16x32_bf16 v[68:71], v[160:163], v[206:209], v[68:71]
	v_mfma_f32_16x16x32_bf16 v[68:71], v[164:167], v[210:213], v[68:71]
	v_mfma_f32_16x16x32_bf16 v[64:67], v[170:173], v[206:209], v[64:67]
	v_mfma_f32_16x16x32_bf16 v[64:67], v[178:181], v[210:213], v[64:67]
	s_setprio 0
	s_barrier
	s_add_i32 s12, s31, s10
	s_mov_b32 m0, s12
	ds_read_b128 v[182:185], v143 offset:49152
	ds_read_b128 v[186:189], v143 offset:50176
	ds_read_b128 v[190:193], v143 offset:51200
	ds_read_b128 v[194:197], v143 offset:52224
	ds_read_b128 v[198:201], v143 offset:53248
	ds_read_b128 v[202:205], v143 offset:54272
	ds_read_b128 v[206:209], v143 offset:55296
	ds_read_b128 v[210:213], v143 offset:56320
	s_add_u32 s100, s72, s16
	s_addc_u32 s101, s73, s17
	global_load_lds_dwordx4 v132, s[100:101]
	s_add_i32 m0, s12, 0x2000
	s_add_u32 s12, s72, 0x80080
	s_addc_u32 s13, s73, 0
	s_add_i32 s31, s42, s10
	global_load_lds_dwordx4 v128, s[100:101]
	s_mov_b32 m0, s31
	s_nop 0
	global_load_lds_dwordx4 v132, s[12:13]
	s_add_i32 m0, s31, 0x2000
	s_nop 0
	global_load_lds_dwordx4 v128, s[12:13]
	s_mov_b32 m0, s22
	s_nop 0
	s_add_u32 s100, s74, s16
	s_addc_u32 s101, s75, s17
	global_load_lds_dwordx4 v134, s[100:101]
	s_mov_b32 m0, s23
	s_nop 0
	global_load_lds_dwordx4 v130, s[100:101]
	s_waitcnt vmcnt(8)
	s_waitcnt lgkmcnt(0)
	s_barrier
	s_setprio 1
	s_waitcnt lgkmcnt(0)
	v_mfma_f32_16x16x32_bf16 v[60:63], v[144:147], v[182:185], v[60:63]
	v_mfma_f32_16x16x32_bf16 v[60:63], v[148:151], v[186:189], v[60:63]
	v_mfma_f32_16x16x32_bf16 v[56:59], v[152:155], v[182:185], v[56:59]
	v_mfma_f32_16x16x32_bf16 v[56:59], v[156:159], v[186:189], v[56:59]
	v_mfma_f32_16x16x32_bf16 v[52:55], v[160:163], v[182:185], v[52:55]
	v_mfma_f32_16x16x32_bf16 v[52:55], v[164:167], v[186:189], v[52:55]
	v_mfma_f32_16x16x32_bf16 v[48:51], v[170:173], v[182:185], v[48:51]
	v_mfma_f32_16x16x32_bf16 v[48:51], v[178:181], v[186:189], v[48:51]
	v_mfma_f32_16x16x32_bf16 v[44:47], v[144:147], v[190:193], v[44:47]
	v_mfma_f32_16x16x32_bf16 v[44:47], v[148:151], v[194:197], v[44:47]
	v_mfma_f32_16x16x32_bf16 v[40:43], v[152:155], v[190:193], v[40:43]
	v_mfma_f32_16x16x32_bf16 v[40:43], v[156:159], v[194:197], v[40:43]
	v_mfma_f32_16x16x32_bf16 v[36:39], v[160:163], v[190:193], v[36:39]
	v_mfma_f32_16x16x32_bf16 v[36:39], v[164:167], v[194:197], v[36:39]
	v_mfma_f32_16x16x32_bf16 v[32:35], v[170:173], v[190:193], v[32:35]
	v_mfma_f32_16x16x32_bf16 v[32:35], v[178:181], v[194:197], v[32:35]
	s_setprio 0
	s_setprio 1
	v_mfma_f32_16x16x32_bf16 v[28:31], v[144:147], v[198:201], v[28:31]
	v_mfma_f32_16x16x32_bf16 v[28:31], v[148:151], v[202:205], v[28:31]
	v_mfma_f32_16x16x32_bf16 v[24:27], v[152:155], v[198:201], v[24:27]
	v_mfma_f32_16x16x32_bf16 v[24:27], v[156:159], v[202:205], v[24:27]
	v_mfma_f32_16x16x32_bf16 v[20:23], v[160:163], v[198:201], v[20:23]
	v_mfma_f32_16x16x32_bf16 v[20:23], v[164:167], v[202:205], v[20:23]
	v_mfma_f32_16x16x32_bf16 v[16:19], v[170:173], v[198:201], v[16:19]
	v_mfma_f32_16x16x32_bf16 v[16:19], v[178:181], v[202:205], v[16:19]
	v_mfma_f32_16x16x32_bf16 v[12:15], v[144:147], v[206:209], v[12:15]
	v_mfma_f32_16x16x32_bf16 v[12:15], v[148:151], v[210:213], v[12:15]
	v_mfma_f32_16x16x32_bf16 v[8:11], v[152:155], v[206:209], v[8:11]
	v_mfma_f32_16x16x32_bf16 v[8:11], v[156:159], v[210:213], v[8:11]
	v_mfma_f32_16x16x32_bf16 v[4:7], v[160:163], v[206:209], v[4:7]
	v_mfma_f32_16x16x32_bf16 v[4:7], v[164:167], v[210:213], v[4:7]
	v_mfma_f32_16x16x32_bf16 v[0:3], v[170:173], v[206:209], v[0:3]
	v_mfma_f32_16x16x32_bf16 v[0:3], v[178:181], v[210:213], v[0:3]
	s_setprio 0
	s_barrier
	s_add_i32 s3, s3, 2
	s_add_u32 s70, s70, 0x100
	s_addc_u32 s71, s71, 0
	s_add_u32 s40, s40, 0x100
	s_addc_u32 s2, s2, 0
	s_cmp_gt_u32 s3, 29
	s_cbranch_scc0 .LBB0_983
	s_and_b64 vcc, exec, s[56:57]
	s_cbranch_vccz .LBB0_986
	s_barrier

; #define PG8_STAGE(bufoff, gbase, voff) do { _Pragma("unroll") for (int _i = 0; _i < 2; ++_i) \
;         __builtin_amdgcn_global_load_lds((const unsigned*)((const char*)(gbase) + (voff)[_i]), (PG8_LAS unsigned*)(lds + (bufoff) + ldsw + _i * 8192), 16, 0, 0); } while (0)
; #define PG8_LDA(dst, b, h) do { _Pragma("unroll") for (int m = 0; m < 4; ++m) _Pragma("unroll") for (int k = 0; k < 2; ++k) dst[m][k] = *(const PG8_LAS bf16x8*)(lds + PG8_SA(b, h) + aoff + m * 2048 + k * 1024); } while (0)
; #define PG8_LDB(dst, b, h) do { _Pragma("unroll") for (int n = 0; n < 2; ++n) _Pragma("unroll") for (int k = 0; k < 2; ++k) dst[n][k] = *(const PG8_LAS bf16x8*)(lds + PG8_SB(b, h) + boff + n * 2048 + k * 1024); } while (0)
; #define PG8_MMA(ai, bj, At, Bt) do { __builtin_amdgcn_s_setprio(1); _Pragma("unroll") for (int m = 0; m < 4; ++m) _Pragma("unroll") for (int n = 0; n < 2; ++n) _Pragma("unroll") for (int k = 0; k < 2; ++k) \
;         acc[ai][bj][m][n] = __builtin_amdgcn_mfma_f32_16x16x32_bf16(Bt[n][k], At[m][k], acc[ai][bj][m][n], 0, 0, 0); __builtin_amdgcn_s_setprio(0); } while (0)
; #define PG8_WAIT_V(n) asm volatile("s_waitcnt vmcnt(" #n ")" ::: "memory")
; #define PG8_WAIT_L(n) asm volatile("s_waitcnt lgkmcnt(" #n ")" ::: "memory")
; #define PG8_BAR __builtin_amdgcn_s_barrier()
; #define PG8_SCHED __builtin_amdgcn_sched_barrier(0)
;     ...
;             const bool last = (t == nt - 2);
;             const char* a1 = PG8_KADV(cA, (size_t)(t + 1) * kstep);
;             const char* a2 = last ? nA : PG8_KADV(cA, (size_t)(t + 2) * kstep); const char* b2 = last ? nB : PG8_KADV(cB, (size_t)(t + 2) * kstep);
;             const char* a3 = PG8_KADV(a2, kstep); const char* b3 = PG8_KADV(b2, kstep);
;             if (last && has_next) S.a_ready(nxt);
;             if constexpr (SP2) {
;             PG8_LDB(B0, 0, 0); PG8_LDB(B1, 0, 1); PG8_SCHED; PG8_LDA(At, 0, 0); PG8_STAGE(PG8_SA(1, 1), a1 + hstep, voffA);
;             PG8_WAIT_V(8); PG8_WAIT_L(0); PG8_BAR; PG8_MMA(0, 0, At, B0); PG8_MMA(0, 1, At, B1); PG8_BAR; PG8_SCHED;
;             PG8_LDA(At, 0, 1); PG8_STAGE(PG8_SB(0, 0), b2, voffB); PG8_STAGE(PG8_SB(0, 1), b2 + hstep, voffB); PG8_STAGE(PG8_SA(0, 0), a2, voffA);
;             PG8_WAIT_V(8); PG8_WAIT_L(0); PG8_BAR; PG8_MMA(1, 0, At, B0); PG8_MMA(1, 1, At, B1); PG8_BAR; PG8_SCHED;
.LBB0_1066:
	s_add_u32 s62, s60, 0xffffff00
	s_addc_u32 s63, s61, -1
	s_add_i32 s26, 0, 0x10000
	s_cmpk_eq_i32 s3, 0x54
	s_cselect_b32 s67, s5, s63
	s_cselect_b32 s66, s4, s62
	s_cselect_b32 s65, s59, s25
	s_cselect_b32 s64, s58, s2
	s_add_i32 s28, 0, 0x14000
	v_add_u32_e32 v152, s26, v166
	v_add_u32_e32 v164, s28, v166
	ds_read_b128 v[128:131], v152
	ds_read_b128 v[132:135], v152 offset:1024
	ds_read_b128 v[148:151], v152 offset:2048
	ds_read_b128 v[152:155], v152 offset:3072
	ds_read_b128 v[156:159], v164
	ds_read_b128 v[160:163], v164 offset:1024
	ds_read_b128 v[170:173], v164 offset:2048
	ds_read_b128 v[178:181], v164 offset:3072
	s_add_i32 m0, s13, 0xc000
	ds_read_b128 v[184:187], v183
	ds_read_b128 v[188:191], v183 offset:1024
	ds_read_b128 v[192:195], v183 offset:2048
	ds_read_b128 v[196:199], v183 offset:3072
	ds_read_b128 v[200:203], v183 offset:4096
	ds_read_b128 v[204:207], v183 offset:5120
	ds_read_b128 v[208:211], v183 offset:6144
	ds_read_b128 v[212:215], v183 offset:7168
	global_load_lds_dwordx4 v144, s[60:61]
	s_add_i32 m0, s13, 0xe000
	s_nop 0
	global_load_lds_dwordx4 v146, s[60:61]
	s_waitcnt vmcnt(8)
	s_waitcnt lgkmcnt(0)
	s_barrier
	s_setprio 1
	s_waitcnt lgkmcnt(0)
	v_mfma_f32_16x16x32_bf16 v[124:127], v[128:131], v[184:187], v[124:127]
	v_mfma_f32_16x16x32_bf16 v[124:127], v[132:135], v[188:191], v[124:127]
	v_mfma_f32_16x16x32_bf16 v[120:123], v[148:151], v[184:187], v[120:123]
	v_mfma_f32_16x16x32_bf16 v[120:123], v[152:155], v[188:191], v[120:123]
	v_mfma_f32_16x16x32_bf16 v[116:119], v[156:159], v[184:187], v[116:119]
	v_mfma_f32_16x16x32_bf16 v[116:119], v[160:163], v[188:191], v[116:119]
	v_mfma_f32_16x16x32_bf16 v[108:111], v[170:173], v[184:187], v[108:111]
	v_mfma_f32_16x16x32_bf16 v[108:111], v[178:181], v[188:191], v[108:111]
	v_mfma_f32_16x16x32_bf16 v[112:115], v[128:131], v[192:195], v[112:115]
	v_mfma_f32_16x16x32_bf16 v[112:115], v[132:135], v[196:199], v[112:115]
	v_mfma_f32_16x16x32_bf16 v[104:107], v[148:151], v[192:195], v[104:107]
	v_mfma_f32_16x16x32_bf16 v[104:107], v[152:155], v[196:199], v[104:107]
	v_mfma_f32_16x16x32_bf16 v[100:103], v[156:159], v[192:195], v[100:103]
	v_mfma_f32_16x16x32_bf16 v[100:103], v[160:163], v[196:199], v[100:103]
	v_mfma_f32_16x16x32_bf16 v[96:99], v[170:173], v[192:195], v[96:99]
	v_mfma_f32_16x16x32_bf16 v[96:99], v[178:181], v[196:199], v[96:99]
	s_setprio 0
	s_setprio 1
	v_mfma_f32_16x16x32_bf16 v[92:95], v[128:131], v[200:203], v[92:95]
	v_mfma_f32_16x16x32_bf16 v[92:95], v[132:135], v[204:207], v[92:95]
	v_mfma_f32_16x16x32_bf16 v[88:91], v[148:151], v[200:203], v[88:91]
	v_mfma_f32_16x16x32_bf16 v[88:91], v[152:155], v[204:207], v[88:91]
	v_mfma_f32_16x16x32_bf16 v[84:87], v[156:159], v[200:203], v[84:87]
	v_mfma_f32_16x16x32_bf16 v[84:87], v[160:163], v[204:207], v[84:87]
	v_mfma_f32_16x16x32_bf16 v[76:79], v[170:173], v[200:203], v[76:79]
	v_mfma_f32_16x16x32_bf16 v[76:79], v[178:181], v[204:207], v[76:79]
	v_mfma_f32_16x16x32_bf16 v[80:83], v[128:131], v[208:211], v[80:83]
	v_mfma_f32_16x16x32_bf16 v[80:83], v[132:135], v[212:215], v[80:83]
	v_mfma_f32_16x16x32_bf16 v[72:75], v[148:151], v[208:211], v[72:75]
	v_mfma_f32_16x16x32_bf16 v[72:75], v[152:155], v[212:215], v[72:75]
	v_mfma_f32_16x16x32_bf16 v[68:71], v[156:159], v[208:211], v[68:71]
	v_mfma_f32_16x16x32_bf16 v[68:71], v[160:163], v[212:215], v[68:71]
	v_mfma_f32_16x16x32_bf16 v[64:67], v[170:173], v[208:211], v[64:67]
	v_mfma_f32_16x16x32_bf16 v[64:67], v[178:181], v[212:215], v[64:67]
	s_setprio 0
	s_barrier
	s_add_i32 s26, s26, s10
	s_mov_b32 m0, s26
	ds_read_b128 v[184:187], v183 offset:16384
	ds_read_b128 v[188:191], v183 offset:17408
	ds_read_b128 v[192:195], v183 offset:18432
	ds_read_b128 v[196:199], v183 offset:19456
	ds_read_b128 v[200:203], v183 offset:20480
	ds_read_b128 v[204:207], v183 offset:21504
	ds_read_b128 v[208:211], v183 offset:22528
	ds_read_b128 v[212:215], v183 offset:23552
	global_load_lds_dwordx4 v138, s[64:65]
	s_add_i32 m0, s26, 0x2000
	s_add_u32 s42, s64, 0x160000
	s_addc_u32 s43, s65, 0
	s_add_i32 s26, s28, s10
	global_load_lds_dwordx4 v142, s[64:65]
	s_mov_b32 m0, s26
	s_nop 0
	global_load_lds_dwordx4 v138, s[42:43]
	s_add_i32 m0, s26, 0x2000
	s_nop 0
	global_load_lds_dwordx4 v142, s[42:43]
	s_mov_b32 m0, s13
	s_nop 0
	global_load_lds_dwordx4 v136, s[66:67]
	s_mov_b32 m0, s18
	s_nop 0
	global_load_lds_dwordx4 v140, s[66:67]
	s_waitcnt vmcnt(8)
	s_waitcnt lgkmcnt(0)
	s_barrier
	s_setprio 1
	s_waitcnt lgkmcnt(0)
	v_mfma_f32_16x16x32_bf16 v[60:63], v[128:131], v[184:187], v[60:63]
	v_mfma_f32_16x16x32_bf16 v[60:63], v[132:135], v[188:191], v[60:63]
	v_mfma_f32_16x16x32_bf16 v[56:59], v[148:151], v[184:187], v[56:59]
	v_mfma_f32_16x16x32_bf16 v[56:59], v[152:155], v[188:191], v[56:59]
	v_mfma_f32_16x16x32_bf16 v[52:55], v[156:159], v[184:187], v[52:55]
	v_mfma_f32_16x16x32_bf16 v[52:55], v[160:163], v[188:191], v[52:55]
	v_mfma_f32_16x16x32_bf16 v[44:47], v[170:173], v[184:187], v[44:47]
	v_mfma_f32_16x16x32_bf16 v[44:47], v[178:181], v[188:191], v[44:47]
	v_mfma_f32_16x16x32_bf16 v[48:51], v[128:131], v[192:195], v[48:51]
	v_mfma_f32_16x16x32_bf16 v[48:51], v[132:135], v[196:199], v[48:51]
	v_mfma_f32_16x16x32_bf16 v[40:43], v[148:151], v[192:195], v[40:43]
	v_mfma_f32_16x16x32_bf16 v[40:43], v[152:155], v[196:199], v[40:43]
	v_mfma_f32_16x16x32_bf16 v[36:39], v[156:159], v[192:195], v[36:39]
	v_mfma_f32_16x16x32_bf16 v[36:39], v[160:163], v[196:199], v[36:39]
	v_mfma_f32_16x16x32_bf16 v[32:35], v[170:173], v[192:195], v[32:35]
	v_mfma_f32_16x16x32_bf16 v[32:35], v[178:181], v[196:199], v[32:35]
	s_setprio 0
	s_setprio 1
	v_mfma_f32_16x16x32_bf16 v[28:31], v[128:131], v[200:203], v[28:31]
	v_mfma_f32_16x16x32_bf16 v[28:31], v[132:135], v[204:207], v[28:31]
	v_mfma_f32_16x16x32_bf16 v[24:27], v[148:151], v[200:203], v[24:27]
	v_mfma_f32_16x16x32_bf16 v[24:27], v[152:155], v[204:207], v[24:27]
	v_mfma_f32_16x16x32_bf16 v[20:23], v[156:159], v[200:203], v[20:23]
	v_mfma_f32_16x16x32_bf16 v[20:23], v[160:163], v[204:207], v[20:23]
	v_mfma_f32_16x16x32_bf16 v[12:15], v[170:173], v[200:203], v[12:15]
	v_mfma_f32_16x16x32_bf16 v[12:15], v[178:181], v[204:207], v[12:15]
	v_mfma_f32_16x16x32_bf16 v[16:19], v[128:131], v[208:211], v[16:19]
	v_mfma_f32_16x16x32_bf16 v[16:19], v[132:135], v[212:215], v[16:19]
	v_mfma_f32_16x16x32_bf16 v[8:11], v[148:151], v[208:211], v[8:11]
	v_mfma_f32_16x16x32_bf16 v[8:11], v[152:155], v[212:215], v[8:11]
	v_mfma_f32_16x16x32_bf16 v[4:7], v[156:159], v[208:211], v[4:7]
	v_mfma_f32_16x16x32_bf16 v[4:7], v[160:163], v[212:215], v[4:7]
	v_mfma_f32_16x16x32_bf16 v[0:3], v[170:173], v[208:211], v[0:3]
	v_mfma_f32_16x16x32_bf16 v[0:3], v[178:181], v[212:215], v[0:3]
	s_setprio 0
	s_barrier
; #define PG8_STAGE(bufoff, gbase, voff) do { _Pragma("unroll") for (int _i = 0; _i < 2; ++_i) \
;         __builtin_amdgcn_global_load_lds((const unsigned*)((const char*)(gbase) + (voff)[_i]), (PG8_LAS unsigned*)(lds + (bufoff) + ldsw + _i * 8192), 16, 0, 0); } while (0)
; #define PG8_LDA(dst, b, h) do { _Pragma("unroll") for (int m = 0; m < 4; ++m) _Pragma("unroll") for (int k = 0; k < 2; ++k) dst[m][k] = *(const PG8_LAS bf16x8*)(lds + PG8_SA(b, h) + aoff + m * 2048 + k * 1024); } while (0)
; #define PG8_LDB(dst, b, h) do { _Pragma("unroll") for (int n = 0; n < 2; ++n) _Pragma("unroll") for (int k = 0; k < 2; ++k) dst[n][k] = *(const PG8_LAS bf16x8*)(lds + PG8_SB(b, h) + boff + n * 2048 + k * 1024); } while (0)
; #define PG8_MMA(ai, bj, At, Bt) do { __builtin_amdgcn_s_setprio(1); _Pragma("unroll") for (int m = 0; m < 4; ++m) _Pragma("unroll") for (int n = 0; n < 2; ++n) _Pragma("unroll") for (int k = 0; k < 2; ++k) \
;         acc[ai][bj][m][n] = __builtin_amdgcn_mfma_f32_16x16x32_bf16(Bt[n][k], At[m][k], acc[ai][bj][m][n], 0, 0, 0); __builtin_amdgcn_s_setprio(0); } while (0)
; #define PG8_WAIT_V(n) asm volatile("s_waitcnt vmcnt(" #n ")" ::: "memory")
; #define PG8_WAIT_L(n) asm volatile("s_waitcnt lgkmcnt(" #n ")" ::: "memory")
; #define PG8_BAR __builtin_amdgcn_s_barrier()
; #define PG8_SCHED __builtin_amdgcn_sched_barrier(0)
;     ...
;             PG8_LDB(B0, 1, 0); PG8_LDB(B1, 1, 1); PG8_SCHED; PG8_LDA(At, 1, 0); PG8_STAGE(PG8_SA(0, 1), a2 + hstep, voffA);
;             PG8_WAIT_V(8); PG8_WAIT_L(0); PG8_BAR; PG8_MMA(0, 0, At, B0); PG8_MMA(0, 1, At, B1); PG8_BAR; PG8_SCHED;
;             PG8_LDA(At, 1, 1); PG8_STAGE(PG8_SB(1, 0), b3, voffB); PG8_STAGE(PG8_SB(1, 1), b3 + hstep, voffB); PG8_STAGE(PG8_SA(1, 0), a3, voffA);
;             PG8_WAIT_V(8); PG8_WAIT_L(0); PG8_BAR; PG8_MMA(1, 0, At, B0); PG8_MMA(1, 1, At, B1); PG8_BAR; PG8_SCHED;
	s_add_i32 s26, 0, 0x18000
	s_add_i32 s28, 0, 0x1c000
	v_add_u32_e32 v152, s26, v166
	v_add_u32_e32 v168, s28, v166
	ds_read_b128 v[128:131], v152
	ds_read_b128 v[132:135], v152 offset:1024
	ds_read_b128 v[148:151], v152 offset:2048
	ds_read_b128 v[152:155], v152 offset:3072
	ds_read_b128 v[156:159], v168
	ds_read_b128 v[160:163], v168 offset:1024
	ds_read_b128 v[170:173], v168 offset:2048
	ds_read_b128 v[178:181], v168 offset:3072
	s_add_u32 s42, s66, 0x160000
	s_addc_u32 s43, s67, 0
	s_mov_b32 m0, s19
	ds_read_b128 v[184:187], v183 offset:32768
	ds_read_b128 v[188:191], v183 offset:33792
	ds_read_b128 v[192:195], v183 offset:34816
	ds_read_b128 v[196:199], v183 offset:35840
	ds_read_b128 v[200:203], v183 offset:36864
	ds_read_b128 v[204:207], v183 offset:37888
	ds_read_b128 v[208:211], v183 offset:38912
	ds_read_b128 v[212:215], v183 offset:39936
	global_load_lds_dwordx4 v136, s[42:43]
	s_mov_b32 m0, s20
	s_nop 0
	global_load_lds_dwordx4 v140, s[42:43]
	s_waitcnt vmcnt(8)
	s_waitcnt lgkmcnt(0)
	s_barrier
	s_setprio 1
	s_waitcnt lgkmcnt(0)
	v_mfma_f32_16x16x32_bf16 v[124:127], v[128:131], v[184:187], v[124:127]
	v_mfma_f32_16x16x32_bf16 v[124:127], v[132:135], v[188:191], v[124:127]
	v_mfma_f32_16x16x32_bf16 v[120:123], v[148:151], v[184:187], v[120:123]
	v_mfma_f32_16x16x32_bf16 v[120:123], v[152:155], v[188:191], v[120:123]
	v_mfma_f32_16x16x32_bf16 v[116:119], v[156:159], v[184:187], v[116:119]
	v_mfma_f32_16x16x32_bf16 v[116:119], v[160:163], v[188:191], v[116:119]
	v_mfma_f32_16x16x32_bf16 v[108:111], v[170:173], v[184:187], v[108:111]
	v_mfma_f32_16x16x32_bf16 v[108:111], v[178:181], v[188:191], v[108:111]
	v_mfma_f32_16x16x32_bf16 v[112:115], v[128:131], v[192:195], v[112:115]
	v_mfma_f32_16x16x32_bf16 v[112:115], v[132:135], v[196:199], v[112:115]
	v_mfma_f32_16x16x32_bf16 v[104:107], v[148:151], v[192:195], v[104:107]
	v_mfma_f32_16x16x32_bf16 v[104:107], v[152:155], v[196:199], v[104:107]
	v_mfma_f32_16x16x32_bf16 v[100:103], v[156:159], v[192:195], v[100:103]
	v_mfma_f32_16x16x32_bf16 v[100:103], v[160:163], v[196:199], v[100:103]
	v_mfma_f32_16x16x32_bf16 v[96:99], v[170:173], v[192:195], v[96:99]
	v_mfma_f32_16x16x32_bf16 v[96:99], v[178:181], v[196:199], v[96:99]
	s_setprio 0
	s_setprio 1
	v_mfma_f32_16x16x32_bf16 v[92:95], v[128:131], v[200:203], v[92:95]
	v_mfma_f32_16x16x32_bf16 v[92:95], v[132:135], v[204:207], v[92:95]
	v_mfma_f32_16x16x32_bf16 v[88:91], v[148:151], v[200:203], v[88:91]
	v_mfma_f32_16x16x32_bf16 v[88:91], v[152:155], v[204:207], v[88:91]
	v_mfma_f32_16x16x32_bf16 v[84:87], v[156:159], v[200:203], v[84:87]
	v_mfma_f32_16x16x32_bf16 v[84:87], v[160:163], v[204:207], v[84:87]
	v_mfma_f32_16x16x32_bf16 v[76:79], v[170:173], v[200:203], v[76:79]
	v_mfma_f32_16x16x32_bf16 v[76:79], v[178:181], v[204:207], v[76:79]
	v_mfma_f32_16x16x32_bf16 v[80:83], v[128:131], v[208:211], v[80:83]
	v_mfma_f32_16x16x32_bf16 v[80:83], v[132:135], v[212:215], v[80:83]
	v_mfma_f32_16x16x32_bf16 v[72:75], v[148:151], v[208:211], v[72:75]
	v_mfma_f32_16x16x32_bf16 v[72:75], v[152:155], v[212:215], v[72:75]
	v_mfma_f32_16x16x32_bf16 v[68:71], v[156:159], v[208:211], v[68:71]
	v_mfma_f32_16x16x32_bf16 v[68:71], v[160:163], v[212:215], v[68:71]
	v_mfma_f32_16x16x32_bf16 v[64:67], v[170:173], v[208:211], v[64:67]
	v_mfma_f32_16x16x32_bf16 v[64:67], v[178:181], v[212:215], v[64:67]
	s_setprio 0
	s_barrier
	s_add_i32 s26, s26, s10
	s_mov_b32 m0, s26
	ds_read_b128 v[184:187], v183 offset:49152
	ds_read_b128 v[188:191], v183 offset:50176
	ds_read_b128 v[192:195], v183 offset:51200
	ds_read_b128 v[196:199], v183 offset:52224
	ds_read_b128 v[200:203], v183 offset:53248
	ds_read_b128 v[204:207], v183 offset:54272
	ds_read_b128 v[208:211], v183 offset:55296
	ds_read_b128 v[212:215], v183 offset:56320
	s_add_u32 s100, s64, s38
	s_addc_u32 s101, s65, s39
	global_load_lds_dwordx4 v138, s[100:101]
	s_add_i32 m0, s26, 0x2000
	s_add_u32 s42, s64, 0x15ff80
	s_addc_u32 s43, s65, 0
	s_add_i32 s26, s28, s10
	global_load_lds_dwordx4 v142, s[100:101]
	s_mov_b32 m0, s26
	s_nop 0
	global_load_lds_dwordx4 v138, s[42:43]
	s_add_i32 m0, s26, 0x2000
	s_nop 0
	global_load_lds_dwordx4 v142, s[42:43]
	s_mov_b32 m0, s12
	s_nop 0
	s_add_u32 s100, s66, s38
	s_addc_u32 s101, s67, s39
	global_load_lds_dwordx4 v136, s[100:101]
	s_mov_b32 m0, s21
	s_nop 0
	global_load_lds_dwordx4 v140, s[100:101]
	s_waitcnt vmcnt(8)
	s_waitcnt lgkmcnt(0)
	s_barrier
	s_setprio 1
	s_waitcnt lgkmcnt(0)
	v_mfma_f32_16x16x32_bf16 v[60:63], v[128:131], v[184:187], v[60:63]
	v_mfma_f32_16x16x32_bf16 v[60:63], v[132:135], v[188:191], v[60:63]
	v_mfma_f32_16x16x32_bf16 v[56:59], v[148:151], v[184:187], v[56:59]
	v_mfma_f32_16x16x32_bf16 v[56:59], v[152:155], v[188:191], v[56:59]
	v_mfma_f32_16x16x32_bf16 v[52:55], v[156:159], v[184:187], v[52:55]
	v_mfma_f32_16x16x32_bf16 v[52:55], v[160:163], v[188:191], v[52:55]
	v_mfma_f32_16x16x32_bf16 v[44:47], v[170:173], v[184:187], v[44:47]
	v_mfma_f32_16x16x32_bf16 v[44:47], v[178:181], v[188:191], v[44:47]
	v_mfma_f32_16x16x32_bf16 v[48:51], v[128:131], v[192:195], v[48:51]
	v_mfma_f32_16x16x32_bf16 v[48:51], v[132:135], v[196:199], v[48:51]
	v_mfma_f32_16x16x32_bf16 v[40:43], v[148:151], v[192:195], v[40:43]
	v_mfma_f32_16x16x32_bf16 v[40:43], v[152:155], v[196:199], v[40:43]
	v_mfma_f32_16x16x32_bf16 v[36:39], v[156:159], v[192:195], v[36:39]
	v_mfma_f32_16x16x32_bf16 v[36:39], v[160:163], v[196:199], v[36:39]
	v_mfma_f32_16x16x32_bf16 v[32:35], v[170:173], v[192:195], v[32:35]
	v_mfma_f32_16x16x32_bf16 v[32:35], v[178:181], v[196:199], v[32:35]
	s_setprio 0
	s_setprio 1
	v_mfma_f32_16x16x32_bf16 v[28:31], v[128:131], v[200:203], v[28:31]
	v_mfma_f32_16x16x32_bf16 v[28:31], v[132:135], v[204:207], v[28:31]
	v_mfma_f32_16x16x32_bf16 v[24:27], v[148:151], v[200:203], v[24:27]
	v_mfma_f32_16x16x32_bf16 v[24:27], v[152:155], v[204:207], v[24:27]
	v_mfma_f32_16x16x32_bf16 v[20:23], v[156:159], v[200:203], v[20:23]
	v_mfma_f32_16x16x32_bf16 v[20:23], v[160:163], v[204:207], v[20:23]
	v_mfma_f32_16x16x32_bf16 v[12:15], v[170:173], v[200:203], v[12:15]
	v_mfma_f32_16x16x32_bf16 v[12:15], v[178:181], v[204:207], v[12:15]
	v_mfma_f32_16x16x32_bf16 v[16:19], v[128:131], v[208:211], v[16:19]
	v_mfma_f32_16x16x32_bf16 v[16:19], v[132:135], v[212:215], v[16:19]
	v_mfma_f32_16x16x32_bf16 v[8:11], v[148:151], v[208:211], v[8:11]
	v_mfma_f32_16x16x32_bf16 v[8:11], v[152:155], v[212:215], v[8:11]
	v_mfma_f32_16x16x32_bf16 v[4:7], v[156:159], v[208:211], v[4:7]
	v_mfma_f32_16x16x32_bf16 v[4:7], v[160:163], v[212:215], v[4:7]
	v_mfma_f32_16x16x32_bf16 v[0:3], v[170:173], v[208:211], v[0:3]
	v_mfma_f32_16x16x32_bf16 v[0:3], v[178:181], v[212:215], v[0:3]
	s_setprio 0
	s_barrier
	s_add_i32 s3, s3, 2
	s_add_u32 s2, s2, 0xffffff00
	s_addc_u32 s25, s25, -1
	s_cmpk_gt_u32 s3, 0x55
	s_mov_b64 s[60:61], s[62:63]
	s_cbranch_scc0 .LBB0_1066
	s_and_b64 vcc, exec, s[56:57]
	s_cbranch_vccz .LBB0_1069
	s_barrier
